# phase 0 adaLN modulation: silu fill and weight-column dot products issued in batches (all loads in flight) instead of one dependent load per trip; early first K-tile DMA and inline-zero accumulators i
# speedup vs baseline: 1.0095x; 1.0095x over previous
.LBB0_20:
	s_barrier
	s_and_saveexec_b64 s[2:3], s[4:5]
	s_cbranch_execz .LBB0_23
	s_add_u32 s8, s42, 0x1000
	s_addc_u32 s9, s43, 0
	global_load_dword v22, v21, s[42:43]
	global_load_dword v23, v21, s[42:43] offset:1024
	global_load_dword v24, v21, s[42:43] offset:2048
	global_load_dword v25, v21, s[42:43] offset:3072
	global_load_dword v26, v21, s[8:9]
	global_load_dword v27, v21, s[8:9] offset:1024
	global_load_dword v28, v21, s[8:9] offset:2048
	global_load_dword v29, v21, s[8:9] offset:3072
	global_load_dword v30, v21, s[46:47]
	global_load_dword v31, v21, s[46:47] offset:1024
	global_load_dword v32, v21, s[46:47] offset:2048
	global_load_dword v33, v21, s[46:47] offset:3072
	s_waitcnt vmcnt(11)
	v_mul_f32_e32 v6, 0xbfb8aa3b, v22
	v_exp_f32_e32 v6, v6
	s_nop 0
	v_add_f32_e32 v6, 1.0, v6
	v_div_scale_f32 v7, s[10:11], v6, v6, v22
	v_rcp_f32_e32 v8, v7
	v_div_scale_f32 v9, vcc, v22, v6, v22
	v_fma_f32 v17, -v7, v8, 1.0
	v_fmac_f32_e32 v8, v17, v8
	v_mul_f32_e32 v17, v9, v8
	v_fma_f32 v18, -v7, v17, v9
	v_fmac_f32_e32 v17, v18, v8
	v_fma_f32 v7, -v7, v17, v9
	v_div_fmas_f32 v7, v7, v8, v17
	v_div_fixup_f32 v22, v7, v6, v22
	ds_write_b32 v21, v22
	s_waitcnt vmcnt(10)
	v_mul_f32_e32 v6, 0xbfb8aa3b, v23
	v_exp_f32_e32 v6, v6
	s_nop 0
	v_add_f32_e32 v6, 1.0, v6
	v_div_scale_f32 v7, s[10:11], v6, v6, v23
	v_rcp_f32_e32 v8, v7
	v_div_scale_f32 v9, vcc, v23, v6, v23
	v_fma_f32 v17, -v7, v8, 1.0
	v_fmac_f32_e32 v8, v17, v8
	v_mul_f32_e32 v17, v9, v8
	v_fma_f32 v18, -v7, v17, v9
	v_fmac_f32_e32 v17, v18, v8
	v_fma_f32 v7, -v7, v17, v9
	v_div_fmas_f32 v7, v7, v8, v17
	v_div_fixup_f32 v23, v7, v6, v23
	ds_write_b32 v21, v23 offset:1024
	s_waitcnt vmcnt(9)
	v_mul_f32_e32 v6, 0xbfb8aa3b, v24
	v_exp_f32_e32 v6, v6
	s_nop 0
	v_add_f32_e32 v6, 1.0, v6
	v_div_scale_f32 v7, s[10:11], v6, v6, v24
	v_rcp_f32_e32 v8, v7
	v_div_scale_f32 v9, vcc, v24, v6, v24
	v_fma_f32 v17, -v7, v8, 1.0
	v_fmac_f32_e32 v8, v17, v8
	v_mul_f32_e32 v17, v9, v8
	v_fma_f32 v18, -v7, v17, v9
	v_fmac_f32_e32 v17, v18, v8
	v_fma_f32 v7, -v7, v17, v9
	v_div_fmas_f32 v7, v7, v8, v17
	v_div_fixup_f32 v24, v7, v6, v24
	ds_write_b32 v21, v24 offset:2048
	s_waitcnt vmcnt(8)
	v_mul_f32_e32 v6, 0xbfb8aa3b, v25
	v_exp_f32_e32 v6, v6
	s_nop 0
	v_add_f32_e32 v6, 1.0, v6
	v_div_scale_f32 v7, s[10:11], v6, v6, v25
	v_rcp_f32_e32 v8, v7
	v_div_scale_f32 v9, vcc, v25, v6, v25
	v_fma_f32 v17, -v7, v8, 1.0
	v_fmac_f32_e32 v8, v17, v8
	v_mul_f32_e32 v17, v9, v8
	v_fma_f32 v18, -v7, v17, v9
	v_fmac_f32_e32 v17, v18, v8
	v_fma_f32 v7, -v7, v17, v9
	v_div_fmas_f32 v7, v7, v8, v17
	v_div_fixup_f32 v25, v7, v6, v25
	ds_write_b32 v21, v25 offset:3072
	s_waitcnt vmcnt(7)
	v_mul_f32_e32 v6, 0xbfb8aa3b, v26
	v_exp_f32_e32 v6, v6
	s_nop 0
	v_add_f32_e32 v6, 1.0, v6
	v_div_scale_f32 v7, s[10:11], v6, v6, v26
	v_rcp_f32_e32 v8, v7
	v_div_scale_f32 v9, vcc, v26, v6, v26
	v_fma_f32 v17, -v7, v8, 1.0
	v_fmac_f32_e32 v8, v17, v8
	v_mul_f32_e32 v17, v9, v8
	v_fma_f32 v18, -v7, v17, v9
	v_fmac_f32_e32 v17, v18, v8
	v_fma_f32 v7, -v7, v17, v9
	v_div_fmas_f32 v7, v7, v8, v17
	v_div_fixup_f32 v26, v7, v6, v26
	ds_write_b32 v21, v26 offset:4096
	s_waitcnt vmcnt(6)
	v_mul_f32_e32 v6, 0xbfb8aa3b, v27
	v_exp_f32_e32 v6, v6
	s_nop 0
	v_add_f32_e32 v6, 1.0, v6
	v_div_scale_f32 v7, s[10:11], v6, v6, v27
	v_rcp_f32_e32 v8, v7
	v_div_scale_f32 v9, vcc, v27, v6, v27
	v_fma_f32 v17, -v7, v8, 1.0
	v_fmac_f32_e32 v8, v17, v8
	v_mul_f32_e32 v17, v9, v8
	v_fma_f32 v18, -v7, v17, v9
	v_fmac_f32_e32 v17, v18, v8
	v_fma_f32 v7, -v7, v17, v9
	v_div_fmas_f32 v7, v7, v8, v17
	v_div_fixup_f32 v27, v7, v6, v27
	ds_write_b32 v21, v27 offset:5120
	s_waitcnt vmcnt(5)
	v_mul_f32_e32 v6, 0xbfb8aa3b, v28
	v_exp_f32_e32 v6, v6
	s_nop 0
	v_add_f32_e32 v6, 1.0, v6
	v_div_scale_f32 v7, s[10:11], v6, v6, v28
	v_rcp_f32_e32 v8, v7
	v_div_scale_f32 v9, vcc, v28, v6, v28
	v_fma_f32 v17, -v7, v8, 1.0
	v_fmac_f32_e32 v8, v17, v8
	v_mul_f32_e32 v17, v9, v8
	v_fma_f32 v18, -v7, v17, v9
	v_fmac_f32_e32 v17, v18, v8
	v_fma_f32 v7, -v7, v17, v9
	v_div_fmas_f32 v7, v7, v8, v17
	v_div_fixup_f32 v28, v7, v6, v28
	ds_write_b32 v21, v28 offset:6144
	s_waitcnt vmcnt(4)
	v_mul_f32_e32 v6, 0xbfb8aa3b, v29
	v_exp_f32_e32 v6, v6
	s_nop 0
	v_add_f32_e32 v6, 1.0, v6
	v_div_scale_f32 v7, s[10:11], v6, v6, v29
	v_rcp_f32_e32 v8, v7
	v_div_scale_f32 v9, vcc, v29, v6, v29
	v_fma_f32 v17, -v7, v8, 1.0
	v_fmac_f32_e32 v8, v17, v8
	v_mul_f32_e32 v17, v9, v8
	v_fma_f32 v18, -v7, v17, v9
	v_fmac_f32_e32 v17, v18, v8
	v_fma_f32 v7, -v7, v17, v9
	v_div_fmas_f32 v7, v7, v8, v17
	v_div_fixup_f32 v29, v7, v6, v29
	ds_write_b32 v21, v29 offset:7168
	s_waitcnt vmcnt(3)
	v_mul_f32_e32 v6, 0xbfb8aa3b, v30
	v_exp_f32_e32 v6, v6
	s_nop 0
	v_add_f32_e32 v6, 1.0, v6
	v_div_scale_f32 v7, s[10:11], v6, v6, v30
	v_rcp_f32_e32 v8, v7
	v_div_scale_f32 v9, vcc, v30, v6, v30
	v_fma_f32 v17, -v7, v8, 1.0
	v_fmac_f32_e32 v8, v17, v8
	v_mul_f32_e32 v17, v9, v8
	v_fma_f32 v18, -v7, v17, v9
	v_fmac_f32_e32 v17, v18, v8
	v_fma_f32 v7, -v7, v17, v9
	v_div_fmas_f32 v7, v7, v8, v17
	v_div_fixup_f32 v30, v7, v6, v30
	ds_write_b32 v21, v30 offset:8192
	s_waitcnt vmcnt(2)
	v_mul_f32_e32 v6, 0xbfb8aa3b, v31
	v_exp_f32_e32 v6, v6
	s_nop 0
	v_add_f32_e32 v6, 1.0, v6
	v_div_scale_f32 v7, s[10:11], v6, v6, v31
	v_rcp_f32_e32 v8, v7
	v_div_scale_f32 v9, vcc, v31, v6, v31
	v_fma_f32 v17, -v7, v8, 1.0
	v_fmac_f32_e32 v8, v17, v8
	v_mul_f32_e32 v17, v9, v8
	v_fma_f32 v18, -v7, v17, v9
	v_fmac_f32_e32 v17, v18, v8
	v_fma_f32 v7, -v7, v17, v9
	v_div_fmas_f32 v7, v7, v8, v17
	v_div_fixup_f32 v31, v7, v6, v31
	ds_write_b32 v21, v31 offset:9216
	s_waitcnt vmcnt(1)
	v_mul_f32_e32 v6, 0xbfb8aa3b, v32
	v_exp_f32_e32 v6, v6
	s_nop 0
	v_add_f32_e32 v6, 1.0, v6
	v_div_scale_f32 v7, s[10:11], v6, v6, v32
	v_rcp_f32_e32 v8, v7
	v_div_scale_f32 v9, vcc, v32, v6, v32
	v_fma_f32 v17, -v7, v8, 1.0
	v_fmac_f32_e32 v8, v17, v8
	v_mul_f32_e32 v17, v9, v8
	v_fma_f32 v18, -v7, v17, v9
	v_fmac_f32_e32 v17, v18, v8
	v_fma_f32 v7, -v7, v17, v9
	v_div_fmas_f32 v7, v7, v8, v17
	v_div_fixup_f32 v32, v7, v6, v32
	ds_write_b32 v21, v32 offset:10240
	s_waitcnt vmcnt(0)
	v_mul_f32_e32 v6, 0xbfb8aa3b, v33
	v_exp_f32_e32 v6, v6
	s_nop 0
	v_add_f32_e32 v6, 1.0, v6
	v_div_scale_f32 v7, s[10:11], v6, v6, v33
	v_rcp_f32_e32 v8, v7
	v_div_scale_f32 v9, vcc, v33, v6, v33
	v_fma_f32 v17, -v7, v8, 1.0
	v_fmac_f32_e32 v8, v17, v8
	v_mul_f32_e32 v17, v9, v8
	v_fma_f32 v18, -v7, v17, v9
	v_fmac_f32_e32 v17, v18, v8
	v_fma_f32 v7, -v7, v17, v9
	v_div_fmas_f32 v7, v7, v8, v17
	v_div_fixup_f32 v33, v7, v6, v33
	ds_write_b32 v21, v33 offset:11264
.LBB0_23:
	s_or_b64 exec, exec, s[2:3]
	s_mul_hi_i32 s2, s36, 0x2aaaaaab
	s_lshr_b32 s3, s2, 31
	s_ashr_i32 s10, s2, 4
	s_add_i32 s10, s10, s3
	s_mul_i32 s2, s10, 0x60
	s_sub_i32 s2, s36, s2
	s_lshl_b32 s2, s2, 5
	s_ashr_i32 s3, s2, 31
	s_mul_i32 s37, s10, 0xc00000
	s_lshl_b64 s[8:9], s[2:3], 2
	s_mul_hi_i32 s11, s10, 0xc00000
	s_add_u32 s8, s37, s8
	s_addc_u32 s9, s11, s9
	s_add_u32 s8, s8, s48
	s_addc_u32 s9, s9, s49
	s_mov_b32 s37, 0x180000
	v_mul_lo_u32 v4, v0, s37
	v_lshl_add_u32 v4, v1, 2, v4
	v_mov_b32_e32 v8, 0
	v_mov_b32_e32 v9, 0
	v_mov_b32_e32 v17, 0
	s_waitcnt lgkmcnt(0)
	s_barrier
	global_load_dword v34, v4, s[8:9] nt
	s_add_u32 s8, s8, 0x3000
	s_addc_u32 s9, s9, 0
	global_load_dword v35, v4, s[8:9] nt
	s_add_u32 s8, s8, 0x3000
	s_addc_u32 s9, s9, 0
	global_load_dword v36, v4, s[8:9] nt
	s_add_u32 s8, s8, 0x3000
	s_addc_u32 s9, s9, 0
	global_load_dword v37, v4, s[8:9] nt
	s_add_u32 s8, s8, 0x3000
	s_addc_u32 s9, s9, 0
	global_load_dword v38, v4, s[8:9] nt
	s_add_u32 s8, s8, 0x3000
	s_addc_u32 s9, s9, 0
	global_load_dword v39, v4, s[8:9] nt
	s_add_u32 s8, s8, 0x3000
	s_addc_u32 s9, s9, 0
	global_load_dword v40, v4, s[8:9] nt
	s_add_u32 s8, s8, 0x3000
	s_addc_u32 s9, s9, 0
	global_load_dword v41, v4, s[8:9] nt
	s_add_u32 s8, s8, 0x3000
	s_addc_u32 s9, s9, 0
	global_load_dword v42, v4, s[8:9] nt
	s_add_u32 s8, s8, 0x3000
	s_addc_u32 s9, s9, 0
	global_load_dword v43, v4, s[8:9] nt
	s_add_u32 s8, s8, 0x3000
	s_addc_u32 s9, s9, 0
	global_load_dword v44, v4, s[8:9] nt
	s_add_u32 s8, s8, 0x3000
	s_addc_u32 s9, s9, 0
	global_load_dword v45, v4, s[8:9] nt
	s_add_u32 s8, s8, 0x3000
	s_addc_u32 s9, s9, 0
	global_load_dword v46, v4, s[8:9] nt
	s_add_u32 s8, s8, 0x3000
	s_addc_u32 s9, s9, 0
	global_load_dword v47, v4, s[8:9] nt
	s_add_u32 s8, s8, 0x3000
	s_addc_u32 s9, s9, 0
	global_load_dword v48, v4, s[8:9] nt
	s_add_u32 s8, s8, 0x3000
	s_addc_u32 s9, s9, 0
	global_load_dword v49, v4, s[8:9] nt
	s_add_u32 s8, s8, 0x3000
	s_addc_u32 s9, s9, 0
	global_load_dword v50, v4, s[8:9] nt
	s_add_u32 s8, s8, 0x3000
	s_addc_u32 s9, s9, 0
	global_load_dword v51, v4, s[8:9] nt
	s_add_u32 s8, s8, 0x3000
	s_addc_u32 s9, s9, 0
	global_load_dword v52, v4, s[8:9] nt
	s_add_u32 s8, s8, 0x3000
	s_addc_u32 s9, s9, 0
	global_load_dword v53, v4, s[8:9] nt
	s_add_u32 s8, s8, 0x3000
	s_addc_u32 s9, s9, 0
	global_load_dword v54, v4, s[8:9] nt
	s_add_u32 s8, s8, 0x3000
	s_addc_u32 s9, s9, 0
	global_load_dword v55, v4, s[8:9] nt
	s_add_u32 s8, s8, 0x3000
	s_addc_u32 s9, s9, 0
	global_load_dword v56, v4, s[8:9] nt
	s_add_u32 s8, s8, 0x3000
	s_addc_u32 s9, s9, 0
	global_load_dword v57, v4, s[8:9] nt
	s_add_u32 s8, s8, 0x3000
	s_addc_u32 s9, s9, 0
	global_load_dword v58, v4, s[8:9] nt
	s_add_u32 s8, s8, 0x3000
	s_addc_u32 s9, s9, 0
	global_load_dword v59, v4, s[8:9] nt
	s_add_u32 s8, s8, 0x3000
	s_addc_u32 s9, s9, 0
	global_load_dword v60, v4, s[8:9] nt
	s_add_u32 s8, s8, 0x3000
	s_addc_u32 s9, s9, 0
	global_load_dword v61, v4, s[8:9] nt
	s_add_u32 s8, s8, 0x3000
	s_addc_u32 s9, s9, 0
	global_load_dword v62, v4, s[8:9] nt
	s_add_u32 s8, s8, 0x3000
	s_addc_u32 s9, s9, 0
	global_load_dword v63, v4, s[8:9] nt
	s_add_u32 s8, s8, 0x3000
	s_addc_u32 s9, s9, 0
	global_load_dword v64, v4, s[8:9] nt
	s_add_u32 s8, s8, 0x3000
	s_addc_u32 s9, s9, 0
	global_load_dword v65, v4, s[8:9] nt
	s_add_u32 s8, s8, 0x3000
	s_addc_u32 s9, s9, 0
	global_load_dword v66, v4, s[8:9] nt
	s_add_u32 s8, s8, 0x3000
	s_addc_u32 s9, s9, 0
	global_load_dword v67, v4, s[8:9] nt
	s_add_u32 s8, s8, 0x3000
	s_addc_u32 s9, s9, 0
	global_load_dword v68, v4, s[8:9] nt
	s_add_u32 s8, s8, 0x3000
	s_addc_u32 s9, s9, 0
	global_load_dword v69, v4, s[8:9] nt
	s_add_u32 s8, s8, 0x3000
	s_addc_u32 s9, s9, 0
	global_load_dword v70, v4, s[8:9] nt
	s_add_u32 s8, s8, 0x3000
	s_addc_u32 s9, s9, 0
	global_load_dword v71, v4, s[8:9] nt
	s_add_u32 s8, s8, 0x3000
	s_addc_u32 s9, s9, 0
	global_load_dword v72, v4, s[8:9] nt
	s_add_u32 s8, s8, 0x3000
	s_addc_u32 s9, s9, 0
	global_load_dword v73, v4, s[8:9] nt
	s_add_u32 s8, s8, 0x3000
	s_addc_u32 s9, s9, 0
	global_load_dword v74, v4, s[8:9] nt
	s_add_u32 s8, s8, 0x3000
	s_addc_u32 s9, s9, 0
	global_load_dword v75, v4, s[8:9] nt
	s_add_u32 s8, s8, 0x3000
	s_addc_u32 s9, s9, 0
	global_load_dword v76, v4, s[8:9] nt
	s_add_u32 s8, s8, 0x3000
	s_addc_u32 s9, s9, 0
	global_load_dword v77, v4, s[8:9] nt
	s_add_u32 s8, s8, 0x3000
	s_addc_u32 s9, s9, 0
	global_load_dword v78, v4, s[8:9] nt
	s_add_u32 s8, s8, 0x3000
	s_addc_u32 s9, s9, 0
	global_load_dword v79, v4, s[8:9] nt
	s_add_u32 s8, s8, 0x3000
	s_addc_u32 s9, s9, 0
	global_load_dword v80, v4, s[8:9] nt
	s_add_u32 s8, s8, 0x3000
	s_addc_u32 s9, s9, 0
	global_load_dword v81, v4, s[8:9] nt
	s_add_u32 s8, s8, 0x3000
	s_addc_u32 s9, s9, 0
	global_load_dword v82, v4, s[8:9] nt
	s_add_u32 s8, s8, 0x3000
	s_addc_u32 s9, s9, 0
	global_load_dword v83, v4, s[8:9] nt
	s_add_u32 s8, s8, 0x3000
	s_addc_u32 s9, s9, 0
	global_load_dword v84, v4, s[8:9] nt
	s_add_u32 s8, s8, 0x3000
	s_addc_u32 s9, s9, 0
	global_load_dword v85, v4, s[8:9] nt
	s_add_u32 s8, s8, 0x3000
	s_addc_u32 s9, s9, 0
	global_load_dword v86, v4, s[8:9] nt
	s_add_u32 s8, s8, 0x3000
	s_addc_u32 s9, s9, 0
	global_load_dword v87, v4, s[8:9] nt
	s_add_u32 s8, s8, 0x3000
	s_addc_u32 s9, s9, 0
	global_load_dword v88, v4, s[8:9] nt
	s_add_u32 s8, s8, 0x3000
	s_addc_u32 s9, s9, 0
	global_load_dword v89, v4, s[8:9] nt
	s_add_u32 s8, s8, 0x3000
	s_addc_u32 s9, s9, 0
	global_load_dword v90, v4, s[8:9] nt
	s_add_u32 s8, s8, 0x3000
	s_addc_u32 s9, s9, 0
	global_load_dword v91, v4, s[8:9] nt
	s_add_u32 s8, s8, 0x3000
	s_addc_u32 s9, s9, 0
	global_load_dword v92, v4, s[8:9] nt
	s_add_u32 s8, s8, 0x3000
	s_addc_u32 s9, s9, 0
	global_load_dword v93, v4, s[8:9] nt
	s_add_u32 s8, s8, 0x3000
	s_addc_u32 s9, s9, 0
	global_load_dword v94, v4, s[8:9] nt
	s_add_u32 s8, s8, 0x3000
	s_addc_u32 s9, s9, 0
	global_load_dword v95, v4, s[8:9] nt
	s_add_u32 s8, s8, 0x3000
	s_addc_u32 s9, s9, 0
	global_load_dword v98, v4, s[8:9] nt
	s_add_u32 s8, s8, 0x3000
	s_addc_u32 s9, s9, 0
	global_load_dword v99, v4, s[8:9] nt
	s_add_u32 s8, s8, 0x3000
	s_addc_u32 s9, s9, 0
	s_waitcnt vmcnt(32)
	ds_read_b64 v[22:23], v11 offset:0
	ds_read_b64 v[24:25], v11 offset:4096
	ds_read_b64 v[26:27], v11 offset:8192
	ds_read_b64 v[28:29], v11 offset:8
	ds_read_b64 v[30:31], v11 offset:4104
	ds_read_b64 v[32:33], v11 offset:8200
	s_waitcnt lgkmcnt(3)
	v_fmac_f32_e32 v8, v34, v22
	v_fmac_f32_e32 v9, v34, v24
	v_fmac_f32_e32 v17, v34, v26
	v_fmac_f32_e32 v8, v35, v23
	v_fmac_f32_e32 v9, v35, v25
	v_fmac_f32_e32 v17, v35, v27
	ds_read_b64 v[22:23], v11 offset:16
	ds_read_b64 v[24:25], v11 offset:4112
	ds_read_b64 v[26:27], v11 offset:8208
	s_waitcnt lgkmcnt(3)
	v_fmac_f32_e32 v8, v36, v28
	v_fmac_f32_e32 v9, v36, v30
	v_fmac_f32_e32 v17, v36, v32
	v_fmac_f32_e32 v8, v37, v29
	v_fmac_f32_e32 v9, v37, v31
	v_fmac_f32_e32 v17, v37, v33
	ds_read_b64 v[28:29], v11 offset:24
	ds_read_b64 v[30:31], v11 offset:4120
	ds_read_b64 v[32:33], v11 offset:8216
	s_waitcnt lgkmcnt(3)
	v_fmac_f32_e32 v8, v38, v22
	v_fmac_f32_e32 v9, v38, v24
	v_fmac_f32_e32 v17, v38, v26
	v_fmac_f32_e32 v8, v39, v23
	v_fmac_f32_e32 v9, v39, v25
	v_fmac_f32_e32 v17, v39, v27
	ds_read_b64 v[22:23], v11 offset:32
	ds_read_b64 v[24:25], v11 offset:4128
	ds_read_b64 v[26:27], v11 offset:8224
	s_waitcnt lgkmcnt(3)
	v_fmac_f32_e32 v8, v40, v28
	v_fmac_f32_e32 v9, v40, v30
	v_fmac_f32_e32 v17, v40, v32
	v_fmac_f32_e32 v8, v41, v29
	v_fmac_f32_e32 v9, v41, v31
	v_fmac_f32_e32 v17, v41, v33
	ds_read_b64 v[28:29], v11 offset:40
	ds_read_b64 v[30:31], v11 offset:4136
	ds_read_b64 v[32:33], v11 offset:8232
	s_waitcnt lgkmcnt(3)
	v_fmac_f32_e32 v8, v42, v22
	v_fmac_f32_e32 v9, v42, v24
	v_fmac_f32_e32 v17, v42, v26
	v_fmac_f32_e32 v8, v43, v23
	v_fmac_f32_e32 v9, v43, v25
	v_fmac_f32_e32 v17, v43, v27
	ds_read_b64 v[22:23], v11 offset:48
	ds_read_b64 v[24:25], v11 offset:4144
	ds_read_b64 v[26:27], v11 offset:8240
	s_waitcnt lgkmcnt(3)
	v_fmac_f32_e32 v8, v44, v28
	v_fmac_f32_e32 v9, v44, v30
	v_fmac_f32_e32 v17, v44, v32
	v_fmac_f32_e32 v8, v45, v29
	v_fmac_f32_e32 v9, v45, v31
	v_fmac_f32_e32 v17, v45, v33
	ds_read_b64 v[28:29], v11 offset:56
	ds_read_b64 v[30:31], v11 offset:4152
	ds_read_b64 v[32:33], v11 offset:8248
	s_waitcnt lgkmcnt(3)
	v_fmac_f32_e32 v8, v46, v22
	v_fmac_f32_e32 v9, v46, v24
	v_fmac_f32_e32 v17, v46, v26
	v_fmac_f32_e32 v8, v47, v23
	v_fmac_f32_e32 v9, v47, v25
	v_fmac_f32_e32 v17, v47, v27
	ds_read_b64 v[22:23], v11 offset:64
	ds_read_b64 v[24:25], v11 offset:4160
	ds_read_b64 v[26:27], v11 offset:8256
	s_waitcnt lgkmcnt(3)
	v_fmac_f32_e32 v8, v48, v28
	v_fmac_f32_e32 v9, v48, v30
	v_fmac_f32_e32 v17, v48, v32
	v_fmac_f32_e32 v8, v49, v29
	v_fmac_f32_e32 v9, v49, v31
	v_fmac_f32_e32 v17, v49, v33
	ds_read_b64 v[28:29], v11 offset:72
	ds_read_b64 v[30:31], v11 offset:4168
	ds_read_b64 v[32:33], v11 offset:8264
	s_waitcnt lgkmcnt(3)
	v_fmac_f32_e32 v8, v50, v22
	v_fmac_f32_e32 v9, v50, v24
	v_fmac_f32_e32 v17, v50, v26
	v_fmac_f32_e32 v8, v51, v23
	v_fmac_f32_e32 v9, v51, v25
	v_fmac_f32_e32 v17, v51, v27
	ds_read_b64 v[22:23], v11 offset:80
	ds_read_b64 v[24:25], v11 offset:4176
	ds_read_b64 v[26:27], v11 offset:8272
	s_waitcnt lgkmcnt(3)
	v_fmac_f32_e32 v8, v52, v28
	v_fmac_f32_e32 v9, v52, v30
	v_fmac_f32_e32 v17, v52, v32
	v_fmac_f32_e32 v8, v53, v29
	v_fmac_f32_e32 v9, v53, v31
	v_fmac_f32_e32 v17, v53, v33
	ds_read_b64 v[28:29], v11 offset:88
	ds_read_b64 v[30:31], v11 offset:4184
	ds_read_b64 v[32:33], v11 offset:8280
	s_waitcnt lgkmcnt(3)
	v_fmac_f32_e32 v8, v54, v22
	v_fmac_f32_e32 v9, v54, v24
	v_fmac_f32_e32 v17, v54, v26
	v_fmac_f32_e32 v8, v55, v23
	v_fmac_f32_e32 v9, v55, v25
	v_fmac_f32_e32 v17, v55, v27
	ds_read_b64 v[22:23], v11 offset:96
	ds_read_b64 v[24:25], v11 offset:4192
	ds_read_b64 v[26:27], v11 offset:8288
	s_waitcnt lgkmcnt(3)
	v_fmac_f32_e32 v8, v56, v28
	v_fmac_f32_e32 v9, v56, v30
	v_fmac_f32_e32 v17, v56, v32
	v_fmac_f32_e32 v8, v57, v29
	v_fmac_f32_e32 v9, v57, v31
	v_fmac_f32_e32 v17, v57, v33
	ds_read_b64 v[28:29], v11 offset:104
	ds_read_b64 v[30:31], v11 offset:4200
	ds_read_b64 v[32:33], v11 offset:8296
	s_waitcnt lgkmcnt(3)
	v_fmac_f32_e32 v8, v58, v22
	v_fmac_f32_e32 v9, v58, v24
	v_fmac_f32_e32 v17, v58, v26
	v_fmac_f32_e32 v8, v59, v23
	v_fmac_f32_e32 v9, v59, v25
	v_fmac_f32_e32 v17, v59, v27
	ds_read_b64 v[22:23], v11 offset:112
	ds_read_b64 v[24:25], v11 offset:4208
	ds_read_b64 v[26:27], v11 offset:8304
	s_waitcnt lgkmcnt(3)
	v_fmac_f32_e32 v8, v60, v28
	v_fmac_f32_e32 v9, v60, v30
	v_fmac_f32_e32 v17, v60, v32
	v_fmac_f32_e32 v8, v61, v29
	v_fmac_f32_e32 v9, v61, v31
	v_fmac_f32_e32 v17, v61, v33
	ds_read_b64 v[28:29], v11 offset:120
	ds_read_b64 v[30:31], v11 offset:4216
	ds_read_b64 v[32:33], v11 offset:8312
	s_waitcnt lgkmcnt(3)
	v_fmac_f32_e32 v8, v62, v22
	v_fmac_f32_e32 v9, v62, v24
	v_fmac_f32_e32 v17, v62, v26
	v_fmac_f32_e32 v8, v63, v23
	v_fmac_f32_e32 v9, v63, v25
	v_fmac_f32_e32 v17, v63, v27
	ds_read_b64 v[22:23], v11 offset:128
	ds_read_b64 v[24:25], v11 offset:4224
	ds_read_b64 v[26:27], v11 offset:8320
	s_waitcnt lgkmcnt(3)
	v_fmac_f32_e32 v8, v64, v28
	v_fmac_f32_e32 v9, v64, v30
	v_fmac_f32_e32 v17, v64, v32
	v_fmac_f32_e32 v8, v65, v29
	v_fmac_f32_e32 v9, v65, v31
	v_fmac_f32_e32 v17, v65, v33
	global_load_dword v34, v4, s[8:9] nt
	s_add_u32 s8, s8, 0x3000
	s_addc_u32 s9, s9, 0
	global_load_dword v35, v4, s[8:9] nt
	s_add_u32 s8, s8, 0x3000
	s_addc_u32 s9, s9, 0
	global_load_dword v36, v4, s[8:9] nt
	s_add_u32 s8, s8, 0x3000
	s_addc_u32 s9, s9, 0
	global_load_dword v37, v4, s[8:9] nt
	s_add_u32 s8, s8, 0x3000
	s_addc_u32 s9, s9, 0
	global_load_dword v38, v4, s[8:9] nt
	s_add_u32 s8, s8, 0x3000
	s_addc_u32 s9, s9, 0
	global_load_dword v39, v4, s[8:9] nt
	s_add_u32 s8, s8, 0x3000
	s_addc_u32 s9, s9, 0
	global_load_dword v40, v4, s[8:9] nt
	s_add_u32 s8, s8, 0x3000
	s_addc_u32 s9, s9, 0
	global_load_dword v41, v4, s[8:9] nt
	s_add_u32 s8, s8, 0x3000
	s_addc_u32 s9, s9, 0
	global_load_dword v42, v4, s[8:9] nt
	s_add_u32 s8, s8, 0x3000
	s_addc_u32 s9, s9, 0
	global_load_dword v43, v4, s[8:9] nt
	s_add_u32 s8, s8, 0x3000
	s_addc_u32 s9, s9, 0
	global_load_dword v44, v4, s[8:9] nt
	s_add_u32 s8, s8, 0x3000
	s_addc_u32 s9, s9, 0
	global_load_dword v45, v4, s[8:9] nt
	s_add_u32 s8, s8, 0x3000
	s_addc_u32 s9, s9, 0
	global_load_dword v46, v4, s[8:9] nt
	s_add_u32 s8, s8, 0x3000
	s_addc_u32 s9, s9, 0
	global_load_dword v47, v4, s[8:9] nt
	s_add_u32 s8, s8, 0x3000
	s_addc_u32 s9, s9, 0
	global_load_dword v48, v4, s[8:9] nt
	s_add_u32 s8, s8, 0x3000
	s_addc_u32 s9, s9, 0
	global_load_dword v49, v4, s[8:9] nt
	s_add_u32 s8, s8, 0x3000
	s_addc_u32 s9, s9, 0
	global_load_dword v50, v4, s[8:9] nt
	s_add_u32 s8, s8, 0x3000
	s_addc_u32 s9, s9, 0
	global_load_dword v51, v4, s[8:9] nt
	s_add_u32 s8, s8, 0x3000
	s_addc_u32 s9, s9, 0
	global_load_dword v52, v4, s[8:9] nt
	s_add_u32 s8, s8, 0x3000
	s_addc_u32 s9, s9, 0
	global_load_dword v53, v4, s[8:9] nt
	s_add_u32 s8, s8, 0x3000
	s_addc_u32 s9, s9, 0
	global_load_dword v54, v4, s[8:9] nt
	s_add_u32 s8, s8, 0x3000
	s_addc_u32 s9, s9, 0
	global_load_dword v55, v4, s[8:9] nt
	s_add_u32 s8, s8, 0x3000
	s_addc_u32 s9, s9, 0
	global_load_dword v56, v4, s[8:9] nt
	s_add_u32 s8, s8, 0x3000
	s_addc_u32 s9, s9, 0
	global_load_dword v57, v4, s[8:9] nt
	s_add_u32 s8, s8, 0x3000
	s_addc_u32 s9, s9, 0
	global_load_dword v58, v4, s[8:9] nt
	s_add_u32 s8, s8, 0x3000
	s_addc_u32 s9, s9, 0
	global_load_dword v59, v4, s[8:9] nt
	s_add_u32 s8, s8, 0x3000
	s_addc_u32 s9, s9, 0
	global_load_dword v60, v4, s[8:9] nt
	s_add_u32 s8, s8, 0x3000
	s_addc_u32 s9, s9, 0
	global_load_dword v61, v4, s[8:9] nt
	s_add_u32 s8, s8, 0x3000
	s_addc_u32 s9, s9, 0
	global_load_dword v62, v4, s[8:9] nt
	s_add_u32 s8, s8, 0x3000
	s_addc_u32 s9, s9, 0
	global_load_dword v63, v4, s[8:9] nt
	s_add_u32 s8, s8, 0x3000
	s_addc_u32 s9, s9, 0
	global_load_dword v64, v4, s[8:9] nt
	s_add_u32 s8, s8, 0x3000
	s_addc_u32 s9, s9, 0
	global_load_dword v65, v4, s[8:9] nt
	s_add_u32 s8, s8, 0x3000
	s_addc_u32 s9, s9, 0
	s_waitcnt vmcnt(32)
	ds_read_b64 v[28:29], v11 offset:136
	ds_read_b64 v[30:31], v11 offset:4232
	ds_read_b64 v[32:33], v11 offset:8328
	s_waitcnt lgkmcnt(3)
	v_fmac_f32_e32 v8, v66, v22
	v_fmac_f32_e32 v9, v66, v24
	v_fmac_f32_e32 v17, v66, v26
	v_fmac_f32_e32 v8, v67, v23
	v_fmac_f32_e32 v9, v67, v25
	v_fmac_f32_e32 v17, v67, v27
	ds_read_b64 v[22:23], v11 offset:144
	ds_read_b64 v[24:25], v11 offset:4240
	ds_read_b64 v[26:27], v11 offset:8336
	s_waitcnt lgkmcnt(3)
	v_fmac_f32_e32 v8, v68, v28
	v_fmac_f32_e32 v9, v68, v30
	v_fmac_f32_e32 v17, v68, v32
	v_fmac_f32_e32 v8, v69, v29
	v_fmac_f32_e32 v9, v69, v31
	v_fmac_f32_e32 v17, v69, v33
	ds_read_b64 v[28:29], v11 offset:152
	ds_read_b64 v[30:31], v11 offset:4248
	ds_read_b64 v[32:33], v11 offset:8344
	s_waitcnt lgkmcnt(3)
	v_fmac_f32_e32 v8, v70, v22
	v_fmac_f32_e32 v9, v70, v24
	v_fmac_f32_e32 v17, v70, v26
	v_fmac_f32_e32 v8, v71, v23
	v_fmac_f32_e32 v9, v71, v25
	v_fmac_f32_e32 v17, v71, v27
	ds_read_b64 v[22:23], v11 offset:160
	ds_read_b64 v[24:25], v11 offset:4256
	ds_read_b64 v[26:27], v11 offset:8352
	s_waitcnt lgkmcnt(3)
	v_fmac_f32_e32 v8, v72, v28
	v_fmac_f32_e32 v9, v72, v30
	v_fmac_f32_e32 v17, v72, v32
	v_fmac_f32_e32 v8, v73, v29
	v_fmac_f32_e32 v9, v73, v31
	v_fmac_f32_e32 v17, v73, v33
	ds_read_b64 v[28:29], v11 offset:168
	ds_read_b64 v[30:31], v11 offset:4264
	ds_read_b64 v[32:33], v11 offset:8360
	s_waitcnt lgkmcnt(3)
	v_fmac_f32_e32 v8, v74, v22
	v_fmac_f32_e32 v9, v74, v24
	v_fmac_f32_e32 v17, v74, v26
	v_fmac_f32_e32 v8, v75, v23
	v_fmac_f32_e32 v9, v75, v25
	v_fmac_f32_e32 v17, v75, v27
	ds_read_b64 v[22:23], v11 offset:176
	ds_read_b64 v[24:25], v11 offset:4272
	ds_read_b64 v[26:27], v11 offset:8368
	s_waitcnt lgkmcnt(3)
	v_fmac_f32_e32 v8, v76, v28
	v_fmac_f32_e32 v9, v76, v30
	v_fmac_f32_e32 v17, v76, v32
	v_fmac_f32_e32 v8, v77, v29
	v_fmac_f32_e32 v9, v77, v31
	v_fmac_f32_e32 v17, v77, v33
	ds_read_b64 v[28:29], v11 offset:184
	ds_read_b64 v[30:31], v11 offset:4280
	ds_read_b64 v[32:33], v11 offset:8376
	s_waitcnt lgkmcnt(3)
	v_fmac_f32_e32 v8, v78, v22
	v_fmac_f32_e32 v9, v78, v24
	v_fmac_f32_e32 v17, v78, v26
	v_fmac_f32_e32 v8, v79, v23
	v_fmac_f32_e32 v9, v79, v25
	v_fmac_f32_e32 v17, v79, v27
	ds_read_b64 v[22:23], v11 offset:192
	ds_read_b64 v[24:25], v11 offset:4288
	ds_read_b64 v[26:27], v11 offset:8384
	s_waitcnt lgkmcnt(3)
	v_fmac_f32_e32 v8, v80, v28
	v_fmac_f32_e32 v9, v80, v30
	v_fmac_f32_e32 v17, v80, v32
	v_fmac_f32_e32 v8, v81, v29
	v_fmac_f32_e32 v9, v81, v31
	v_fmac_f32_e32 v17, v81, v33
	ds_read_b64 v[28:29], v11 offset:200
	ds_read_b64 v[30:31], v11 offset:4296
	ds_read_b64 v[32:33], v11 offset:8392
	s_waitcnt lgkmcnt(3)
	v_fmac_f32_e32 v8, v82, v22
	v_fmac_f32_e32 v9, v82, v24
	v_fmac_f32_e32 v17, v82, v26
	v_fmac_f32_e32 v8, v83, v23
	v_fmac_f32_e32 v9, v83, v25
	v_fmac_f32_e32 v17, v83, v27
	ds_read_b64 v[22:23], v11 offset:208
	ds_read_b64 v[24:25], v11 offset:4304
	ds_read_b64 v[26:27], v11 offset:8400
	s_waitcnt lgkmcnt(3)
	v_fmac_f32_e32 v8, v84, v28
	v_fmac_f32_e32 v9, v84, v30
	v_fmac_f32_e32 v17, v84, v32
	v_fmac_f32_e32 v8, v85, v29
	v_fmac_f32_e32 v9, v85, v31
	v_fmac_f32_e32 v17, v85, v33
	ds_read_b64 v[28:29], v11 offset:216
	ds_read_b64 v[30:31], v11 offset:4312
	ds_read_b64 v[32:33], v11 offset:8408
	s_waitcnt lgkmcnt(3)
	v_fmac_f32_e32 v8, v86, v22
	v_fmac_f32_e32 v9, v86, v24
	v_fmac_f32_e32 v17, v86, v26
	v_fmac_f32_e32 v8, v87, v23
	v_fmac_f32_e32 v9, v87, v25
	v_fmac_f32_e32 v17, v87, v27
	ds_read_b64 v[22:23], v11 offset:224
	ds_read_b64 v[24:25], v11 offset:4320
	ds_read_b64 v[26:27], v11 offset:8416
	s_waitcnt lgkmcnt(3)
	v_fmac_f32_e32 v8, v88, v28
	v_fmac_f32_e32 v9, v88, v30
	v_fmac_f32_e32 v17, v88, v32
	v_fmac_f32_e32 v8, v89, v29
	v_fmac_f32_e32 v9, v89, v31
	v_fmac_f32_e32 v17, v89, v33
	ds_read_b64 v[28:29], v11 offset:232
	ds_read_b64 v[30:31], v11 offset:4328
	ds_read_b64 v[32:33], v11 offset:8424
	s_waitcnt lgkmcnt(3)
	v_fmac_f32_e32 v8, v90, v22
	v_fmac_f32_e32 v9, v90, v24
	v_fmac_f32_e32 v17, v90, v26
	v_fmac_f32_e32 v8, v91, v23
	v_fmac_f32_e32 v9, v91, v25
	v_fmac_f32_e32 v17, v91, v27
	ds_read_b64 v[22:23], v11 offset:240
	ds_read_b64 v[24:25], v11 offset:4336
	ds_read_b64 v[26:27], v11 offset:8432
	s_waitcnt lgkmcnt(3)
	v_fmac_f32_e32 v8, v92, v28
	v_fmac_f32_e32 v9, v92, v30
	v_fmac_f32_e32 v17, v92, v32
	v_fmac_f32_e32 v8, v93, v29
	v_fmac_f32_e32 v9, v93, v31
	v_fmac_f32_e32 v17, v93, v33
	ds_read_b64 v[28:29], v11 offset:248
	ds_read_b64 v[30:31], v11 offset:4344
	ds_read_b64 v[32:33], v11 offset:8440
	s_waitcnt lgkmcnt(3)
	v_fmac_f32_e32 v8, v94, v22
	v_fmac_f32_e32 v9, v94, v24
	v_fmac_f32_e32 v17, v94, v26
	v_fmac_f32_e32 v8, v95, v23
	v_fmac_f32_e32 v9, v95, v25
	v_fmac_f32_e32 v17, v95, v27
	ds_read_b64 v[22:23], v11 offset:256
	ds_read_b64 v[24:25], v11 offset:4352
	ds_read_b64 v[26:27], v11 offset:8448
	s_waitcnt lgkmcnt(3)
	v_fmac_f32_e32 v8, v98, v28
	v_fmac_f32_e32 v9, v98, v30
	v_fmac_f32_e32 v17, v98, v32
	v_fmac_f32_e32 v8, v99, v29
	v_fmac_f32_e32 v9, v99, v31
	v_fmac_f32_e32 v17, v99, v33
	global_load_dword v66, v4, s[8:9] nt
	s_add_u32 s8, s8, 0x3000
	s_addc_u32 s9, s9, 0
	global_load_dword v67, v4, s[8:9] nt
	s_add_u32 s8, s8, 0x3000
	s_addc_u32 s9, s9, 0
	global_load_dword v68, v4, s[8:9] nt
	s_add_u32 s8, s8, 0x3000
	s_addc_u32 s9, s9, 0
	global_load_dword v69, v4, s[8:9] nt
	s_add_u32 s8, s8, 0x3000
	s_addc_u32 s9, s9, 0
	global_load_dword v70, v4, s[8:9] nt
	s_add_u32 s8, s8, 0x3000
	s_addc_u32 s9, s9, 0
	global_load_dword v71, v4, s[8:9] nt
	s_add_u32 s8, s8, 0x3000
	s_addc_u32 s9, s9, 0
	global_load_dword v72, v4, s[8:9] nt
	s_add_u32 s8, s8, 0x3000
	s_addc_u32 s9, s9, 0
	global_load_dword v73, v4, s[8:9] nt
	s_add_u32 s8, s8, 0x3000
	s_addc_u32 s9, s9, 0
	global_load_dword v74, v4, s[8:9] nt
	s_add_u32 s8, s8, 0x3000
	s_addc_u32 s9, s9, 0
	global_load_dword v75, v4, s[8:9] nt
	s_add_u32 s8, s8, 0x3000
	s_addc_u32 s9, s9, 0
	global_load_dword v76, v4, s[8:9] nt
	s_add_u32 s8, s8, 0x3000
	s_addc_u32 s9, s9, 0
	global_load_dword v77, v4, s[8:9] nt
	s_add_u32 s8, s8, 0x3000
	s_addc_u32 s9, s9, 0
	global_load_dword v78, v4, s[8:9] nt
	s_add_u32 s8, s8, 0x3000
	s_addc_u32 s9, s9, 0
	global_load_dword v79, v4, s[8:9] nt
	s_add_u32 s8, s8, 0x3000
	s_addc_u32 s9, s9, 0
	global_load_dword v80, v4, s[8:9] nt
	s_add_u32 s8, s8, 0x3000
	s_addc_u32 s9, s9, 0
	global_load_dword v81, v4, s[8:9] nt
	s_add_u32 s8, s8, 0x3000
	s_addc_u32 s9, s9, 0
	global_load_dword v82, v4, s[8:9] nt
	s_add_u32 s8, s8, 0x3000
	s_addc_u32 s9, s9, 0
	global_load_dword v83, v4, s[8:9] nt
	s_add_u32 s8, s8, 0x3000
	s_addc_u32 s9, s9, 0
	global_load_dword v84, v4, s[8:9] nt
	s_add_u32 s8, s8, 0x3000
	s_addc_u32 s9, s9, 0
	global_load_dword v85, v4, s[8:9] nt
	s_add_u32 s8, s8, 0x3000
	s_addc_u32 s9, s9, 0
	global_load_dword v86, v4, s[8:9] nt
	s_add_u32 s8, s8, 0x3000
	s_addc_u32 s9, s9, 0
	global_load_dword v87, v4, s[8:9] nt
	s_add_u32 s8, s8, 0x3000
	s_addc_u32 s9, s9, 0
	global_load_dword v88, v4, s[8:9] nt
	s_add_u32 s8, s8, 0x3000
	s_addc_u32 s9, s9, 0
	global_load_dword v89, v4, s[8:9] nt
	s_add_u32 s8, s8, 0x3000
	s_addc_u32 s9, s9, 0
	global_load_dword v90, v4, s[8:9] nt
	s_add_u32 s8, s8, 0x3000
	s_addc_u32 s9, s9, 0
	global_load_dword v91, v4, s[8:9] nt
	s_add_u32 s8, s8, 0x3000
	s_addc_u32 s9, s9, 0
	global_load_dword v92, v4, s[8:9] nt
	s_add_u32 s8, s8, 0x3000
	s_addc_u32 s9, s9, 0
	global_load_dword v93, v4, s[8:9] nt
	s_add_u32 s8, s8, 0x3000
	s_addc_u32 s9, s9, 0
	global_load_dword v94, v4, s[8:9] nt
	s_add_u32 s8, s8, 0x3000
	s_addc_u32 s9, s9, 0
	global_load_dword v95, v4, s[8:9] nt
	s_add_u32 s8, s8, 0x3000
	s_addc_u32 s9, s9, 0
	global_load_dword v98, v4, s[8:9] nt
	s_add_u32 s8, s8, 0x3000
	s_addc_u32 s9, s9, 0
	global_load_dword v99, v4, s[8:9] nt
	s_add_u32 s8, s8, 0x3000
	s_addc_u32 s9, s9, 0
	s_waitcnt vmcnt(32)
	ds_read_b64 v[28:29], v11 offset:264
	ds_read_b64 v[30:31], v11 offset:4360
	ds_read_b64 v[32:33], v11 offset:8456
	s_waitcnt lgkmcnt(3)
	v_fmac_f32_e32 v8, v34, v22
	v_fmac_f32_e32 v9, v34, v24
	v_fmac_f32_e32 v17, v34, v26
	v_fmac_f32_e32 v8, v35, v23
	v_fmac_f32_e32 v9, v35, v25
	v_fmac_f32_e32 v17, v35, v27
	ds_read_b64 v[22:23], v11 offset:272
	ds_read_b64 v[24:25], v11 offset:4368
	ds_read_b64 v[26:27], v11 offset:8464
	s_waitcnt lgkmcnt(3)
	v_fmac_f32_e32 v8, v36, v28
	v_fmac_f32_e32 v9, v36, v30
	v_fmac_f32_e32 v17, v36, v32
	v_fmac_f32_e32 v8, v37, v29
	v_fmac_f32_e32 v9, v37, v31
	v_fmac_f32_e32 v17, v37, v33
	ds_read_b64 v[28:29], v11 offset:280
	ds_read_b64 v[30:31], v11 offset:4376
	ds_read_b64 v[32:33], v11 offset:8472
	s_waitcnt lgkmcnt(3)
	v_fmac_f32_e32 v8, v38, v22
	v_fmac_f32_e32 v9, v38, v24
	v_fmac_f32_e32 v17, v38, v26
	v_fmac_f32_e32 v8, v39, v23
	v_fmac_f32_e32 v9, v39, v25
	v_fmac_f32_e32 v17, v39, v27
	ds_read_b64 v[22:23], v11 offset:288
	ds_read_b64 v[24:25], v11 offset:4384
	ds_read_b64 v[26:27], v11 offset:8480
	s_waitcnt lgkmcnt(3)
	v_fmac_f32_e32 v8, v40, v28
	v_fmac_f32_e32 v9, v40, v30
	v_fmac_f32_e32 v17, v40, v32
	v_fmac_f32_e32 v8, v41, v29
	v_fmac_f32_e32 v9, v41, v31
	v_fmac_f32_e32 v17, v41, v33
	ds_read_b64 v[28:29], v11 offset:296
	ds_read_b64 v[30:31], v11 offset:4392
	ds_read_b64 v[32:33], v11 offset:8488
	s_waitcnt lgkmcnt(3)
	v_fmac_f32_e32 v8, v42, v22
	v_fmac_f32_e32 v9, v42, v24
	v_fmac_f32_e32 v17, v42, v26
	v_fmac_f32_e32 v8, v43, v23
	v_fmac_f32_e32 v9, v43, v25
	v_fmac_f32_e32 v17, v43, v27
	ds_read_b64 v[22:23], v11 offset:304
	ds_read_b64 v[24:25], v11 offset:4400
	ds_read_b64 v[26:27], v11 offset:8496
	s_waitcnt lgkmcnt(3)
	v_fmac_f32_e32 v8, v44, v28
	v_fmac_f32_e32 v9, v44, v30
	v_fmac_f32_e32 v17, v44, v32
	v_fmac_f32_e32 v8, v45, v29
	v_fmac_f32_e32 v9, v45, v31
	v_fmac_f32_e32 v17, v45, v33
	ds_read_b64 v[28:29], v11 offset:312
	ds_read_b64 v[30:31], v11 offset:4408
	ds_read_b64 v[32:33], v11 offset:8504
	s_waitcnt lgkmcnt(3)
	v_fmac_f32_e32 v8, v46, v22
	v_fmac_f32_e32 v9, v46, v24
	v_fmac_f32_e32 v17, v46, v26
	v_fmac_f32_e32 v8, v47, v23
	v_fmac_f32_e32 v9, v47, v25
	v_fmac_f32_e32 v17, v47, v27
	ds_read_b64 v[22:23], v11 offset:320
	ds_read_b64 v[24:25], v11 offset:4416
	ds_read_b64 v[26:27], v11 offset:8512
	s_waitcnt lgkmcnt(3)
	v_fmac_f32_e32 v8, v48, v28
	v_fmac_f32_e32 v9, v48, v30
	v_fmac_f32_e32 v17, v48, v32
	v_fmac_f32_e32 v8, v49, v29
	v_fmac_f32_e32 v9, v49, v31
	v_fmac_f32_e32 v17, v49, v33
	ds_read_b64 v[28:29], v11 offset:328
	ds_read_b64 v[30:31], v11 offset:4424
	ds_read_b64 v[32:33], v11 offset:8520
	s_waitcnt lgkmcnt(3)
	v_fmac_f32_e32 v8, v50, v22
	v_fmac_f32_e32 v9, v50, v24
	v_fmac_f32_e32 v17, v50, v26
	v_fmac_f32_e32 v8, v51, v23
	v_fmac_f32_e32 v9, v51, v25
	v_fmac_f32_e32 v17, v51, v27
	ds_read_b64 v[22:23], v11 offset:336
	ds_read_b64 v[24:25], v11 offset:4432
	ds_read_b64 v[26:27], v11 offset:8528
	s_waitcnt lgkmcnt(3)
	v_fmac_f32_e32 v8, v52, v28
	v_fmac_f32_e32 v9, v52, v30
	v_fmac_f32_e32 v17, v52, v32
	v_fmac_f32_e32 v8, v53, v29
	v_fmac_f32_e32 v9, v53, v31
	v_fmac_f32_e32 v17, v53, v33
	ds_read_b64 v[28:29], v11 offset:344
	ds_read_b64 v[30:31], v11 offset:4440
	ds_read_b64 v[32:33], v11 offset:8536
	s_waitcnt lgkmcnt(3)
	v_fmac_f32_e32 v8, v54, v22
	v_fmac_f32_e32 v9, v54, v24
	v_fmac_f32_e32 v17, v54, v26
	v_fmac_f32_e32 v8, v55, v23
	v_fmac_f32_e32 v9, v55, v25
	v_fmac_f32_e32 v17, v55, v27
	ds_read_b64 v[22:23], v11 offset:352
	ds_read_b64 v[24:25], v11 offset:4448
	ds_read_b64 v[26:27], v11 offset:8544
	s_waitcnt lgkmcnt(3)
	v_fmac_f32_e32 v8, v56, v28
	v_fmac_f32_e32 v9, v56, v30
	v_fmac_f32_e32 v17, v56, v32
	v_fmac_f32_e32 v8, v57, v29
	v_fmac_f32_e32 v9, v57, v31
	v_fmac_f32_e32 v17, v57, v33
	ds_read_b64 v[28:29], v11 offset:360
	ds_read_b64 v[30:31], v11 offset:4456
	ds_read_b64 v[32:33], v11 offset:8552
	s_waitcnt lgkmcnt(3)
	v_fmac_f32_e32 v8, v58, v22
	v_fmac_f32_e32 v9, v58, v24
	v_fmac_f32_e32 v17, v58, v26
	v_fmac_f32_e32 v8, v59, v23
	v_fmac_f32_e32 v9, v59, v25
	v_fmac_f32_e32 v17, v59, v27
	ds_read_b64 v[22:23], v11 offset:368
	ds_read_b64 v[24:25], v11 offset:4464
	ds_read_b64 v[26:27], v11 offset:8560
	s_waitcnt lgkmcnt(3)
	v_fmac_f32_e32 v8, v60, v28
	v_fmac_f32_e32 v9, v60, v30
	v_fmac_f32_e32 v17, v60, v32
	v_fmac_f32_e32 v8, v61, v29
	v_fmac_f32_e32 v9, v61, v31
	v_fmac_f32_e32 v17, v61, v33
	ds_read_b64 v[28:29], v11 offset:376
	ds_read_b64 v[30:31], v11 offset:4472
	ds_read_b64 v[32:33], v11 offset:8568
	s_waitcnt lgkmcnt(3)
	v_fmac_f32_e32 v8, v62, v22
	v_fmac_f32_e32 v9, v62, v24
	v_fmac_f32_e32 v17, v62, v26
	v_fmac_f32_e32 v8, v63, v23
	v_fmac_f32_e32 v9, v63, v25
	v_fmac_f32_e32 v17, v63, v27
	ds_read_b64 v[22:23], v11 offset:384
	ds_read_b64 v[24:25], v11 offset:4480
	ds_read_b64 v[26:27], v11 offset:8576
	s_waitcnt lgkmcnt(3)
	v_fmac_f32_e32 v8, v64, v28
	v_fmac_f32_e32 v9, v64, v30
	v_fmac_f32_e32 v17, v64, v32
	v_fmac_f32_e32 v8, v65, v29
	v_fmac_f32_e32 v9, v65, v31
	v_fmac_f32_e32 v17, v65, v33
	s_waitcnt vmcnt(0)
	ds_read_b64 v[28:29], v11 offset:392
	ds_read_b64 v[30:31], v11 offset:4488
	ds_read_b64 v[32:33], v11 offset:8584
	s_waitcnt lgkmcnt(3)
	v_fmac_f32_e32 v8, v66, v22
	v_fmac_f32_e32 v9, v66, v24
	v_fmac_f32_e32 v17, v66, v26
	v_fmac_f32_e32 v8, v67, v23
	v_fmac_f32_e32 v9, v67, v25
	v_fmac_f32_e32 v17, v67, v27
	ds_read_b64 v[22:23], v11 offset:400
	ds_read_b64 v[24:25], v11 offset:4496
	ds_read_b64 v[26:27], v11 offset:8592
	s_waitcnt lgkmcnt(3)
	v_fmac_f32_e32 v8, v68, v28
	v_fmac_f32_e32 v9, v68, v30
	v_fmac_f32_e32 v17, v68, v32
	v_fmac_f32_e32 v8, v69, v29
	v_fmac_f32_e32 v9, v69, v31
	v_fmac_f32_e32 v17, v69, v33
	ds_read_b64 v[28:29], v11 offset:408
	ds_read_b64 v[30:31], v11 offset:4504
	ds_read_b64 v[32:33], v11 offset:8600
	s_waitcnt lgkmcnt(3)
	v_fmac_f32_e32 v8, v70, v22
	v_fmac_f32_e32 v9, v70, v24
	v_fmac_f32_e32 v17, v70, v26
	v_fmac_f32_e32 v8, v71, v23
	v_fmac_f32_e32 v9, v71, v25
	v_fmac_f32_e32 v17, v71, v27
	ds_read_b64 v[22:23], v11 offset:416
	ds_read_b64 v[24:25], v11 offset:4512
	ds_read_b64 v[26:27], v11 offset:8608
	s_waitcnt lgkmcnt(3)
	v_fmac_f32_e32 v8, v72, v28
	v_fmac_f32_e32 v9, v72, v30
	v_fmac_f32_e32 v17, v72, v32
	v_fmac_f32_e32 v8, v73, v29
	v_fmac_f32_e32 v9, v73, v31
	v_fmac_f32_e32 v17, v73, v33
	ds_read_b64 v[28:29], v11 offset:424
	ds_read_b64 v[30:31], v11 offset:4520
	ds_read_b64 v[32:33], v11 offset:8616
	s_waitcnt lgkmcnt(3)
	v_fmac_f32_e32 v8, v74, v22
	v_fmac_f32_e32 v9, v74, v24
	v_fmac_f32_e32 v17, v74, v26
	v_fmac_f32_e32 v8, v75, v23
	v_fmac_f32_e32 v9, v75, v25
	v_fmac_f32_e32 v17, v75, v27
	ds_read_b64 v[22:23], v11 offset:432
	ds_read_b64 v[24:25], v11 offset:4528
	ds_read_b64 v[26:27], v11 offset:8624
	s_waitcnt lgkmcnt(3)
	v_fmac_f32_e32 v8, v76, v28
	v_fmac_f32_e32 v9, v76, v30
	v_fmac_f32_e32 v17, v76, v32
	v_fmac_f32_e32 v8, v77, v29
	v_fmac_f32_e32 v9, v77, v31
	v_fmac_f32_e32 v17, v77, v33
	ds_read_b64 v[28:29], v11 offset:440
	ds_read_b64 v[30:31], v11 offset:4536
	ds_read_b64 v[32:33], v11 offset:8632
	s_waitcnt lgkmcnt(3)
	v_fmac_f32_e32 v8, v78, v22
	v_fmac_f32_e32 v9, v78, v24
	v_fmac_f32_e32 v17, v78, v26
	v_fmac_f32_e32 v8, v79, v23
	v_fmac_f32_e32 v9, v79, v25
	v_fmac_f32_e32 v17, v79, v27
	ds_read_b64 v[22:23], v11 offset:448
	ds_read_b64 v[24:25], v11 offset:4544
	ds_read_b64 v[26:27], v11 offset:8640
	s_waitcnt lgkmcnt(3)
	v_fmac_f32_e32 v8, v80, v28
	v_fmac_f32_e32 v9, v80, v30
	v_fmac_f32_e32 v17, v80, v32
	v_fmac_f32_e32 v8, v81, v29
	v_fmac_f32_e32 v9, v81, v31
	v_fmac_f32_e32 v17, v81, v33
	ds_read_b64 v[28:29], v11 offset:456
	ds_read_b64 v[30:31], v11 offset:4552
	ds_read_b64 v[32:33], v11 offset:8648
	s_waitcnt lgkmcnt(3)
	v_fmac_f32_e32 v8, v82, v22
	v_fmac_f32_e32 v9, v82, v24
	v_fmac_f32_e32 v17, v82, v26
	v_fmac_f32_e32 v8, v83, v23
	v_fmac_f32_e32 v9, v83, v25
	v_fmac_f32_e32 v17, v83, v27
	ds_read_b64 v[22:23], v11 offset:464
	ds_read_b64 v[24:25], v11 offset:4560
	ds_read_b64 v[26:27], v11 offset:8656
	s_waitcnt lgkmcnt(3)
	v_fmac_f32_e32 v8, v84, v28
	v_fmac_f32_e32 v9, v84, v30
	v_fmac_f32_e32 v17, v84, v32
	v_fmac_f32_e32 v8, v85, v29
	v_fmac_f32_e32 v9, v85, v31
	v_fmac_f32_e32 v17, v85, v33
	ds_read_b64 v[28:29], v11 offset:472
	ds_read_b64 v[30:31], v11 offset:4568
	ds_read_b64 v[32:33], v11 offset:8664
	s_waitcnt lgkmcnt(3)
	v_fmac_f32_e32 v8, v86, v22
	v_fmac_f32_e32 v9, v86, v24
	v_fmac_f32_e32 v17, v86, v26
	v_fmac_f32_e32 v8, v87, v23
	v_fmac_f32_e32 v9, v87, v25
	v_fmac_f32_e32 v17, v87, v27
	ds_read_b64 v[22:23], v11 offset:480
	ds_read_b64 v[24:25], v11 offset:4576
	ds_read_b64 v[26:27], v11 offset:8672
	s_waitcnt lgkmcnt(3)
	v_fmac_f32_e32 v8, v88, v28
	v_fmac_f32_e32 v9, v88, v30
	v_fmac_f32_e32 v17, v88, v32
	v_fmac_f32_e32 v8, v89, v29
	v_fmac_f32_e32 v9, v89, v31
	v_fmac_f32_e32 v17, v89, v33
	ds_read_b64 v[28:29], v11 offset:488
	ds_read_b64 v[30:31], v11 offset:4584
	ds_read_b64 v[32:33], v11 offset:8680
	s_waitcnt lgkmcnt(3)
	v_fmac_f32_e32 v8, v90, v22
	v_fmac_f32_e32 v9, v90, v24
	v_fmac_f32_e32 v17, v90, v26
	v_fmac_f32_e32 v8, v91, v23
	v_fmac_f32_e32 v9, v91, v25
	v_fmac_f32_e32 v17, v91, v27
	ds_read_b64 v[22:23], v11 offset:496
	ds_read_b64 v[24:25], v11 offset:4592
	ds_read_b64 v[26:27], v11 offset:8688
	s_waitcnt lgkmcnt(3)
	v_fmac_f32_e32 v8, v92, v28
	v_fmac_f32_e32 v9, v92, v30
	v_fmac_f32_e32 v17, v92, v32
	v_fmac_f32_e32 v8, v93, v29
	v_fmac_f32_e32 v9, v93, v31
	v_fmac_f32_e32 v17, v93, v33
	ds_read_b64 v[28:29], v11 offset:504
	ds_read_b64 v[30:31], v11 offset:4600
	ds_read_b64 v[32:33], v11 offset:8696
	s_waitcnt lgkmcnt(3)
	v_fmac_f32_e32 v8, v94, v22
	v_fmac_f32_e32 v9, v94, v24
	v_fmac_f32_e32 v17, v94, v26
	v_fmac_f32_e32 v8, v95, v23
	v_fmac_f32_e32 v9, v95, v25
	v_fmac_f32_e32 v17, v95, v27
	s_waitcnt lgkmcnt(0)
	v_fmac_f32_e32 v8, v98, v28
	v_fmac_f32_e32 v9, v98, v30
	v_fmac_f32_e32 v17, v98, v32
	v_fmac_f32_e32 v8, v99, v29
	v_fmac_f32_e32 v9, v99, v31
	v_fmac_f32_e32 v17, v99, v33
	s_barrier
	ds_write2_b32 v12, v8, v9 offset1:32
	ds_write_b32 v10, v17 offset:12544
	s_waitcnt lgkmcnt(0)
	s_barrier
	s_and_saveexec_b64 s[8:9], s[6:7]
	s_cbranch_execz .LBB0_19
	s_mul_i32 s3, s10, 0xc00
	s_add_i32 s3, s3, s2
	v_or_b32_e32 v6, s3, v1
	v_ashrrev_i32_e32 v7, 31, v6
	v_lshl_add_u64 v[6:7], v[6:7], 2, s[50:51]
	global_load_dword v4, v[6:7], off
	ds_read2_b32 v[6:7], v13 offset1:96
	ds_read2_b32 v[8:9], v14 offset0:64 offset1:160
	ds_read2_b32 v[18:19], v15 offset0:128 offset1:224
	ds_read2_b32 v[22:23], v16 offset0:64 offset1:160
	v_mad_u64_u32 v[24:25], s[10:11], s10, 3, v[0:1]
	s_waitcnt lgkmcnt(3)
	v_add_f32_e32 v6, 0, v6
	v_add_f32_e32 v6, v6, v7
	s_waitcnt lgkmcnt(2)
	v_add_f32_e32 v6, v6, v8
	v_add_f32_e32 v6, v6, v9
	v_mul_lo_u32 v17, v24, s12
	s_waitcnt lgkmcnt(1)
	v_add_f32_e32 v6, v6, v18
	v_add_u32_e32 v17, s2, v17
	v_add_f32_e32 v6, v6, v19
	v_or_b32_e32 v24, v17, v1
	s_waitcnt lgkmcnt(0)
	v_add_f32_e32 v6, v6, v22
	v_readlane_b32 s2, v207, 2
	v_ashrrev_i32_e32 v25, 31, v24
	v_add_f32_e32 v6, v6, v23
	v_readlane_b32 s3, v207, 3
	s_waitcnt vmcnt(0)
	v_add_f32_e32 v4, v6, v4
	v_lshl_add_u64 v[6:7], v[24:25], 2, s[2:3]
	global_store_dword v[6:7], v4, off
	s_branch .LBB0_19

.LBB0_243:
	s_lshl_b64 s[0:1], s[18:19], 18
	s_add_u32 s76, s4, s0
	s_addc_u32 s77, s5, s1
	s_mov_b32 s43, s19
	s_lshl_b64 s[16:17], s[42:43], 18
	s_add_u32 s36, s60, s16
	s_addc_u32 s37, s49, s17
	s_mov_b32 s78, s36
	s_mov_b32 s79, s37
	v_lshrrev_b32_e32 v96, 3, v138
	v_bfe_u32 v97, v138, 4, 3
	v_and_b32_e32 v98, 7, v138
	v_xor_b32_e32 v97, v97, v98
	v_lshlrev_b32_e32 v97, 4, v97
	v_lshl_add_u32 v240, v96, 11, v97
	v_add_u32_e32 v241, 0x10000, v240
	v_add_u32_e32 v242, 0x20000, v240
	v_add_u32_e32 v243, 0x30000, v240
	v_lshrrev_b32_e32 v99, 6, v138
	s_nop 0
	v_readfirstlane_b32 s80, v99
	s_lshl_b32 s81, s80, 10
	s_barrier
	s_add_i32 m0, s81, 0
	s_nop 0
	global_load_lds_dwordx4 v240, s[76:77]
	s_add_i32 m0, s81, 4096
	s_nop 0
	global_load_lds_dwordx4 v241, s[76:77]
	s_add_i32 m0, s81, 8192
	s_nop 0
	global_load_lds_dwordx4 v242, s[76:77]
	s_add_i32 m0, s81, 12288
	s_nop 0
	global_load_lds_dwordx4 v243, s[76:77]
	s_add_i32 m0, s81, 16384
	s_nop 0
	global_load_lds_dwordx4 v240, s[78:79]
	s_add_i32 m0, s81, 20480
	s_nop 0
	global_load_lds_dwordx4 v241, s[78:79]
	s_add_i32 m0, s81, 24576
	s_nop 0
	global_load_lds_dwordx4 v242, s[78:79]
	s_add_i32 m0, s81, 28672
	s_nop 0
	global_load_lds_dwordx4 v243, s[78:79]
	s_add_u32 s76, s76, 0x80
	s_addc_u32 s77, s77, 0
	s_add_u32 s78, s78, 0x80
	s_addc_u32 s79, s79, 0
	v_and_b32_e32 v100, 15, v138
	v_bfe_u32 v101, v138, 4, 2
	v_lshrrev_b32_e32 v102, 1, v100
	v_xor_b32_e32 v102, v102, v101
	v_lshlrev_b32_e32 v102, 4, v102
	v_lshrrev_b32_e32 v103, 1, v99
	v_and_b32_e32 v99, 1, v99
	v_lshl_add_u32 v96, v103, 6, v100
	v_lshl_add_u32 v244, v96, 7, v102
	v_xor_b32_e32 v245, 64, v244
	v_lshl_add_u32 v96, v99, 6, v100
	v_lshl_add_u32 v246, v96, 7, v102
	v_add_u32_e32 v246, 0x4000, v246
	v_xor_b32_e32 v247, 64, v246
	v_lshlrev_b32_e32 v96, 6, v103
	v_lshl_add_u32 v96, v101, 2, v96
	s_movk_i32 s0, 0x210
	v_mul_lo_u32 v96, v96, s0
	v_lshl_add_u32 v97, v99, 6, v100
	v_lshl_add_u32 v248, v97, 2, v96
	s_movk_i32 s82, 7
	s_waitcnt vmcnt(0)
	s_barrier
	ds_read_b128 v[64:67], v244 offset:0
	ds_read_b128 v[80:83], v246 offset:0
	ds_read_b128 v[84:87], v246 offset:2048
	ds_read_b128 v[88:91], v246 offset:4096
	ds_read_b128 v[92:95], v246 offset:6144
	ds_read_b128 v[68:71], v244 offset:2048
	ds_read_b128 v[72:75], v244 offset:4096
	ds_read_b128 v[76:79], v244 offset:6144
	s_waitcnt lgkmcnt(6)
	v_mfma_f32_16x16x32_bf16 v[0:3], v[64:67], v[80:83], 0
	ds_read_b128 v[208:211], v245 offset:0
	s_add_i32 m0, s81, 32768
	s_waitcnt lgkmcnt(6)
	v_mfma_f32_16x16x32_bf16 v[4:7], v[64:67], v[84:87], 0
	ds_read_b128 v[224:227], v247 offset:0
	global_load_lds_dwordx4 v240, s[76:77]
	s_waitcnt lgkmcnt(6)
	v_mfma_f32_16x16x32_bf16 v[8:11], v[64:67], v[88:91], 0
	ds_read_b128 v[228:231], v247 offset:2048
	s_add_i32 m0, s81, 36864
	s_waitcnt lgkmcnt(6)
	v_mfma_f32_16x16x32_bf16 v[12:15], v[64:67], v[92:95], 0
	ds_read_b128 v[232:235], v247 offset:4096
	global_load_lds_dwordx4 v241, s[76:77]
	s_waitcnt lgkmcnt(6)
	v_mfma_f32_16x16x32_bf16 v[16:19], v[68:71], v[80:83], 0
	ds_read_b128 v[236:239], v247 offset:6144
	s_add_i32 m0, s81, 40960
	v_mfma_f32_16x16x32_bf16 v[20:23], v[68:71], v[84:87], 0
	ds_read_b128 v[212:215], v245 offset:2048
	global_load_lds_dwordx4 v242, s[76:77]
	v_mfma_f32_16x16x32_bf16 v[24:27], v[68:71], v[88:91], 0
	ds_read_b128 v[216:219], v245 offset:4096
	s_add_i32 m0, s81, 45056
	v_mfma_f32_16x16x32_bf16 v[28:31], v[68:71], v[92:95], 0
	ds_read_b128 v[220:223], v245 offset:6144
	global_load_lds_dwordx4 v243, s[76:77]
	s_waitcnt lgkmcnt(9)
	v_mfma_f32_16x16x32_bf16 v[32:35], v[72:75], v[80:83], 0
	s_add_i32 m0, s81, 49152
	v_mfma_f32_16x16x32_bf16 v[36:39], v[72:75], v[84:87], 0
	global_load_lds_dwordx4 v240, s[78:79]
	v_mfma_f32_16x16x32_bf16 v[40:43], v[72:75], v[88:91], 0
	s_add_i32 m0, s81, 53248
	v_mfma_f32_16x16x32_bf16 v[44:47], v[72:75], v[92:95], 0
	global_load_lds_dwordx4 v241, s[78:79]
	s_waitcnt lgkmcnt(8)
	v_mfma_f32_16x16x32_bf16 v[48:51], v[76:79], v[80:83], 0
	s_add_i32 m0, s81, 57344
	v_mfma_f32_16x16x32_bf16 v[52:55], v[76:79], v[84:87], 0
	global_load_lds_dwordx4 v242, s[78:79]
	v_mfma_f32_16x16x32_bf16 v[56:59], v[76:79], v[88:91], 0
	s_add_i32 m0, s81, 61440
	v_mfma_f32_16x16x32_bf16 v[60:63], v[76:79], v[92:95], 0
	global_load_lds_dwordx4 v243, s[78:79]
	s_waitcnt lgkmcnt(6)
	v_mfma_f32_16x16x32_bf16 v[0:3], v[208:211], v[224:227], v[0:3]
	s_add_u32 s76, s76, 0x80
	s_addc_u32 s77, s77, 0
	s_waitcnt lgkmcnt(5)
	v_mfma_f32_16x16x32_bf16 v[4:7], v[208:211], v[228:231], v[4:7]
	s_waitcnt lgkmcnt(4)
	v_mfma_f32_16x16x32_bf16 v[8:11], v[208:211], v[232:235], v[8:11]
	s_add_u32 s78, s78, 0x80
	s_addc_u32 s79, s79, 0
	s_waitcnt lgkmcnt(3)
	v_mfma_f32_16x16x32_bf16 v[12:15], v[208:211], v[236:239], v[12:15]
	s_waitcnt lgkmcnt(2)
	v_mfma_f32_16x16x32_bf16 v[16:19], v[212:215], v[224:227], v[16:19]
	v_mfma_f32_16x16x32_bf16 v[20:23], v[212:215], v[228:231], v[20:23]
	v_mfma_f32_16x16x32_bf16 v[24:27], v[212:215], v[232:235], v[24:27]
	v_mfma_f32_16x16x32_bf16 v[28:31], v[212:215], v[236:239], v[28:31]
	s_waitcnt lgkmcnt(1)
	v_mfma_f32_16x16x32_bf16 v[32:35], v[216:219], v[224:227], v[32:35]
	v_mfma_f32_16x16x32_bf16 v[36:39], v[216:219], v[228:231], v[36:39]
	v_mfma_f32_16x16x32_bf16 v[40:43], v[216:219], v[232:235], v[40:43]
	v_mfma_f32_16x16x32_bf16 v[44:47], v[216:219], v[236:239], v[44:47]
	s_waitcnt lgkmcnt(0)
	v_mfma_f32_16x16x32_bf16 v[48:51], v[220:223], v[224:227], v[48:51]
	v_mfma_f32_16x16x32_bf16 v[52:55], v[220:223], v[228:231], v[52:55]
	v_mfma_f32_16x16x32_bf16 v[56:59], v[220:223], v[232:235], v[56:59]
	v_mfma_f32_16x16x32_bf16 v[60:63], v[220:223], v[236:239], v[60:63]
	s_waitcnt vmcnt(0)
	s_barrier
	ds_read_b128 v[64:67], v244 offset:32768
	ds_read_b128 v[80:83], v246 offset:32768
	ds_read_b128 v[84:87], v246 offset:34816
	ds_read_b128 v[88:91], v246 offset:36864
	ds_read_b128 v[92:95], v246 offset:38912
	ds_read_b128 v[68:71], v244 offset:34816
	ds_read_b128 v[72:75], v244 offset:36864
	ds_read_b128 v[76:79], v244 offset:38912
	s_waitcnt lgkmcnt(6)
	v_mfma_f32_16x16x32_bf16 v[0:3], v[64:67], v[80:83], v[0:3]
	ds_read_b128 v[208:211], v245 offset:32768
	s_add_i32 m0, s81, 0
	s_waitcnt lgkmcnt(6)
	v_mfma_f32_16x16x32_bf16 v[4:7], v[64:67], v[84:87], v[4:7]
	ds_read_b128 v[224:227], v247 offset:32768
	global_load_lds_dwordx4 v240, s[76:77]
	s_waitcnt lgkmcnt(6)
	v_mfma_f32_16x16x32_bf16 v[8:11], v[64:67], v[88:91], v[8:11]
	ds_read_b128 v[228:231], v247 offset:34816
	s_add_i32 m0, s81, 4096
	s_waitcnt lgkmcnt(6)
	v_mfma_f32_16x16x32_bf16 v[12:15], v[64:67], v[92:95], v[12:15]
	ds_read_b128 v[232:235], v247 offset:36864
	global_load_lds_dwordx4 v241, s[76:77]
	s_waitcnt lgkmcnt(6)
	v_mfma_f32_16x16x32_bf16 v[16:19], v[68:71], v[80:83], v[16:19]
	ds_read_b128 v[236:239], v247 offset:38912
	s_add_i32 m0, s81, 8192
	v_mfma_f32_16x16x32_bf16 v[20:23], v[68:71], v[84:87], v[20:23]
	ds_read_b128 v[212:215], v245 offset:34816
	global_load_lds_dwordx4 v242, s[76:77]
	v_mfma_f32_16x16x32_bf16 v[24:27], v[68:71], v[88:91], v[24:27]
	ds_read_b128 v[216:219], v245 offset:36864
	s_add_i32 m0, s81, 12288
	v_mfma_f32_16x16x32_bf16 v[28:31], v[68:71], v[92:95], v[28:31]
	ds_read_b128 v[220:223], v245 offset:38912
	global_load_lds_dwordx4 v243, s[76:77]
	s_waitcnt lgkmcnt(9)
	v_mfma_f32_16x16x32_bf16 v[32:35], v[72:75], v[80:83], v[32:35]
	s_add_i32 m0, s81, 16384
	v_mfma_f32_16x16x32_bf16 v[36:39], v[72:75], v[84:87], v[36:39]
	global_load_lds_dwordx4 v240, s[78:79]
	v_mfma_f32_16x16x32_bf16 v[40:43], v[72:75], v[88:91], v[40:43]
	s_add_i32 m0, s81, 20480
	v_mfma_f32_16x16x32_bf16 v[44:47], v[72:75], v[92:95], v[44:47]
	global_load_lds_dwordx4 v241, s[78:79]
	s_waitcnt lgkmcnt(8)
	v_mfma_f32_16x16x32_bf16 v[48:51], v[76:79], v[80:83], v[48:51]
	s_add_i32 m0, s81, 24576
	v_mfma_f32_16x16x32_bf16 v[52:55], v[76:79], v[84:87], v[52:55]
	global_load_lds_dwordx4 v242, s[78:79]
	v_mfma_f32_16x16x32_bf16 v[56:59], v[76:79], v[88:91], v[56:59]
	s_add_i32 m0, s81, 28672
	v_mfma_f32_16x16x32_bf16 v[60:63], v[76:79], v[92:95], v[60:63]
	global_load_lds_dwordx4 v243, s[78:79]
	s_waitcnt lgkmcnt(6)
	v_mfma_f32_16x16x32_bf16 v[0:3], v[208:211], v[224:227], v[0:3]
	s_add_u32 s76, s76, 0x80
	s_addc_u32 s77, s77, 0
	s_waitcnt lgkmcnt(5)
	v_mfma_f32_16x16x32_bf16 v[4:7], v[208:211], v[228:231], v[4:7]
	s_waitcnt lgkmcnt(4)
	v_mfma_f32_16x16x32_bf16 v[8:11], v[208:211], v[232:235], v[8:11]
	s_add_u32 s78, s78, 0x80
	s_addc_u32 s79, s79, 0
	s_waitcnt lgkmcnt(3)
	v_mfma_f32_16x16x32_bf16 v[12:15], v[208:211], v[236:239], v[12:15]
	s_waitcnt lgkmcnt(2)
	v_mfma_f32_16x16x32_bf16 v[16:19], v[212:215], v[224:227], v[16:19]
	v_mfma_f32_16x16x32_bf16 v[20:23], v[212:215], v[228:231], v[20:23]
	v_mfma_f32_16x16x32_bf16 v[24:27], v[212:215], v[232:235], v[24:27]
	v_mfma_f32_16x16x32_bf16 v[28:31], v[212:215], v[236:239], v[28:31]
	s_waitcnt lgkmcnt(1)
	v_mfma_f32_16x16x32_bf16 v[32:35], v[216:219], v[224:227], v[32:35]
	v_mfma_f32_16x16x32_bf16 v[36:39], v[216:219], v[228:231], v[36:39]
	v_mfma_f32_16x16x32_bf16 v[40:43], v[216:219], v[232:235], v[40:43]
	v_mfma_f32_16x16x32_bf16 v[44:47], v[216:219], v[236:239], v[44:47]
	s_waitcnt lgkmcnt(0)
	v_mfma_f32_16x16x32_bf16 v[48:51], v[220:223], v[224:227], v[48:51]
	v_mfma_f32_16x16x32_bf16 v[52:55], v[220:223], v[228:231], v[52:55]
	v_mfma_f32_16x16x32_bf16 v[56:59], v[220:223], v[232:235], v[56:59]
	v_mfma_f32_16x16x32_bf16 v[60:63], v[220:223], v[236:239], v[60:63]
	s_movk_i32 s82, 6

.LBB0_625:
	s_lshr_b32 s0, s41, 6
	s_and_b32 s1, s41, 63
	s_lshr_b32 s82, s1, 3
	s_and_b32 s1, s1, 7
	s_lshl_b32 s0, s0, 3
	s_or_b32 s83, s0, s1
	s_lshl_b32 s0, s83, 18
	s_add_u32 s0, s0, 0x1100000
	s_add_u32 s76, s94, s0
	s_addc_u32 s77, s95, 0
	s_lshl_b32 s0, s82, 18
	s_add_u32 s78, s38, s0
	s_addc_u32 s79, s39, 0
	v_lshrrev_b32_e32 v98, 3, v138
	v_bfe_u32 v99, v138, 4, 3
	v_and_b32_e32 v100, 7, v138
	v_xor_b32_e32 v99, v99, v100
	v_lshlrev_b32_e32 v99, 4, v99
	v_lshl_add_u32 v240, v98, 11, v99
	v_add_u32_e32 v241, 0x10000, v240
	v_add_u32_e32 v242, 0x20000, v240
	v_add_u32_e32 v243, 0x30000, v240
	v_lshrrev_b32_e32 v101, 6, v138
	s_nop 0
	v_readfirstlane_b32 s80, v101
	s_lshl_b32 s81, s80, 10
	s_barrier
	s_add_i32 m0, s81, 0
	s_nop 0
	global_load_lds_dwordx4 v240, s[76:77]
	s_add_i32 m0, s81, 4096
	s_nop 0
	global_load_lds_dwordx4 v241, s[76:77]
	s_add_i32 m0, s81, 8192
	s_nop 0
	global_load_lds_dwordx4 v242, s[76:77]
	s_add_i32 m0, s81, 12288
	s_nop 0
	global_load_lds_dwordx4 v243, s[76:77]
	s_add_i32 m0, s81, 16384
	s_nop 0
	global_load_lds_dwordx4 v240, s[78:79]
	s_add_i32 m0, s81, 20480
	s_nop 0
	global_load_lds_dwordx4 v241, s[78:79]
	s_add_i32 m0, s81, 24576
	s_nop 0
	global_load_lds_dwordx4 v242, s[78:79]
	s_add_i32 m0, s81, 28672
	s_nop 0
	global_load_lds_dwordx4 v243, s[78:79]
	s_add_u32 s76, s76, 0x80
	s_addc_u32 s77, s77, 0
	s_add_u32 s78, s78, 0x80
	s_addc_u32 s79, s79, 0
	v_and_b32_e32 v104, 15, v138
	v_bfe_u32 v105, v138, 4, 2
	v_lshrrev_b32_e32 v106, 1, v104
	v_xor_b32_e32 v106, v106, v105
	v_lshlrev_b32_e32 v106, 4, v106
	v_lshrrev_b32_e32 v107, 1, v101
	v_and_b32_e32 v101, 1, v101
	v_lshl_add_u32 v98, v107, 6, v104
	v_lshl_add_u32 v244, v98, 7, v106
	v_xor_b32_e32 v245, 64, v244
	v_lshl_add_u32 v98, v101, 6, v104
	v_lshl_add_u32 v246, v98, 7, v106
	v_add_u32_e32 v246, 0x4000, v246
	v_xor_b32_e32 v247, 64, v246
	v_lshlrev_b32_e32 v98, 6, v107
	v_lshl_add_u32 v98, v105, 2, v98
	s_movk_i32 s0, 0x210
	v_mul_lo_u32 v98, v98, s0
	v_lshl_add_u32 v99, v101, 6, v104
	v_lshl_add_u32 v248, v99, 2, v98
	v_lshrrev_b32_e32 v110, 4, v138
	v_and_b32_e32 v111, 15, v138
	v_lshlrev_b32_e32 v114, 5, v111
	v_lshl_add_u32 v102, v110, 12, v114
	v_lshlrev_b32_e32 v108, 4, v111
	v_lshl_add_u32 v108, v110, 11, v108
	v_mul_lo_u32 v124, v110, s0
	v_add_u32_e32 v124, v124, v114
	s_lshl_b32 s0, s83, 7
	s_lshl_b32 s1, s82, 7
	s_lshl_b32 s2, s0, 10
	s_add_u32 s2, s2, s1
	s_cmp_eq_u64 s[52:53], 0
	s_cbranch_scc0 .Lot_l1addr
	v_readlane_b32 s86, v207, 4
	v_readlane_b32 s87, v207, 5
	s_lshl_b32 s3, s2, 2
	s_add_u32 s86, s86, s3
	s_addc_u32 s87, s87, 0
	s_lshl_b32 s3, s2, 1
	s_add_u32 s3, s3, 0xa700000
	s_add_u32 s88, s94, s3
	s_addc_u32 s89, s95, 0
	s_branch .Lot_addr_done

.Lot_addr_done:
	s_lshr_b32 s2, s83, 6
	s_mul_i32 s2, s2, 0x3000
	s_lshl_b32 s3, s1, 2
	s_add_u32 s2, s2, s3
	s_add_u32 s2, s2, 0x2000
	s_add_u32 s90, s12, s2
	s_addc_u32 s91, s13, 0
	s_cmp_eq_u64 s[52:53], 0
	s_cbranch_scc0 .Lot_main_l1
	s_waitcnt vmcnt(0)
	s_barrier
	ds_read_b128 v[176:179], v244 offset:0
	ds_read_b128 v[80:83], v246 offset:0
	ds_read_b128 v[84:87], v246 offset:2048
	ds_read_b128 v[88:91], v246 offset:4096
	ds_read_b128 v[92:95], v246 offset:6144
	ds_read_b128 v[180:183], v244 offset:2048
	ds_read_b128 v[184:187], v244 offset:4096
	ds_read_b128 v[188:191], v244 offset:6144
	s_waitcnt lgkmcnt(6)
	v_mfma_f32_16x16x32_bf16 v[0:3], v[176:179], v[80:83], 0
	ds_read_b128 v[208:211], v245 offset:0
	s_add_i32 m0, s81, 32768
	s_waitcnt lgkmcnt(6)
	v_mfma_f32_16x16x32_bf16 v[4:7], v[176:179], v[84:87], 0
	ds_read_b128 v[224:227], v247 offset:0
	global_load_lds_dwordx4 v240, s[76:77]
	s_waitcnt lgkmcnt(6)
	v_mfma_f32_16x16x32_bf16 v[8:11], v[176:179], v[88:91], 0
	ds_read_b128 v[228:231], v247 offset:2048
	s_add_i32 m0, s81, 36864
	s_waitcnt lgkmcnt(6)
	v_mfma_f32_16x16x32_bf16 v[12:15], v[176:179], v[92:95], 0
	ds_read_b128 v[232:235], v247 offset:4096
	global_load_lds_dwordx4 v241, s[76:77]
	s_waitcnt lgkmcnt(6)
	v_mfma_f32_16x16x32_bf16 v[16:19], v[180:183], v[80:83], 0
	ds_read_b128 v[236:239], v247 offset:6144
	s_add_i32 m0, s81, 40960
	v_mfma_f32_16x16x32_bf16 v[20:23], v[180:183], v[84:87], 0
	ds_read_b128 v[212:215], v245 offset:2048
	global_load_lds_dwordx4 v242, s[76:77]
	v_mfma_f32_16x16x32_bf16 v[24:27], v[180:183], v[88:91], 0
	ds_read_b128 v[216:219], v245 offset:4096
	s_add_i32 m0, s81, 45056
	v_mfma_f32_16x16x32_bf16 v[28:31], v[180:183], v[92:95], 0
	ds_read_b128 v[220:223], v245 offset:6144
	global_load_lds_dwordx4 v243, s[76:77]
	s_waitcnt lgkmcnt(9)
	v_mfma_f32_16x16x32_bf16 v[32:35], v[184:187], v[80:83], 0
	s_add_i32 m0, s81, 49152
	v_mfma_f32_16x16x32_bf16 v[36:39], v[184:187], v[84:87], 0
	global_load_lds_dwordx4 v240, s[78:79]
	v_mfma_f32_16x16x32_bf16 v[40:43], v[184:187], v[88:91], 0
	s_add_i32 m0, s81, 53248
	v_mfma_f32_16x16x32_bf16 v[44:47], v[184:187], v[92:95], 0
	global_load_lds_dwordx4 v241, s[78:79]
	s_waitcnt lgkmcnt(8)
	v_mfma_f32_16x16x32_bf16 v[48:51], v[188:191], v[80:83], 0
	s_add_i32 m0, s81, 57344
	v_mfma_f32_16x16x32_bf16 v[52:55], v[188:191], v[84:87], 0
	global_load_lds_dwordx4 v242, s[78:79]
	v_mfma_f32_16x16x32_bf16 v[56:59], v[188:191], v[88:91], 0
	s_add_i32 m0, s81, 61440
	v_mfma_f32_16x16x32_bf16 v[60:63], v[188:191], v[92:95], 0
	global_load_lds_dwordx4 v243, s[78:79]
	s_waitcnt lgkmcnt(6)
	v_mfma_f32_16x16x32_bf16 v[0:3], v[208:211], v[224:227], v[0:3]
	s_add_u32 s76, s76, 0x80
	s_addc_u32 s77, s77, 0
	s_waitcnt lgkmcnt(5)
	v_mfma_f32_16x16x32_bf16 v[4:7], v[208:211], v[228:231], v[4:7]
	s_waitcnt lgkmcnt(4)
	v_mfma_f32_16x16x32_bf16 v[8:11], v[208:211], v[232:235], v[8:11]
	s_add_u32 s78, s78, 0x80
	s_addc_u32 s79, s79, 0
	s_waitcnt lgkmcnt(3)
	v_mfma_f32_16x16x32_bf16 v[12:15], v[208:211], v[236:239], v[12:15]
	s_waitcnt lgkmcnt(2)
	v_mfma_f32_16x16x32_bf16 v[16:19], v[212:215], v[224:227], v[16:19]
	v_mfma_f32_16x16x32_bf16 v[20:23], v[212:215], v[228:231], v[20:23]
	v_mfma_f32_16x16x32_bf16 v[24:27], v[212:215], v[232:235], v[24:27]
	v_mfma_f32_16x16x32_bf16 v[28:31], v[212:215], v[236:239], v[28:31]
	s_waitcnt lgkmcnt(1)
	v_mfma_f32_16x16x32_bf16 v[32:35], v[216:219], v[224:227], v[32:35]
	v_mfma_f32_16x16x32_bf16 v[36:39], v[216:219], v[228:231], v[36:39]
	v_mfma_f32_16x16x32_bf16 v[40:43], v[216:219], v[232:235], v[40:43]
	v_mfma_f32_16x16x32_bf16 v[44:47], v[216:219], v[236:239], v[44:47]
	s_waitcnt lgkmcnt(0)
	v_mfma_f32_16x16x32_bf16 v[48:51], v[220:223], v[224:227], v[48:51]
	v_mfma_f32_16x16x32_bf16 v[52:55], v[220:223], v[228:231], v[52:55]
	v_mfma_f32_16x16x32_bf16 v[56:59], v[220:223], v[232:235], v[56:59]
	v_mfma_f32_16x16x32_bf16 v[60:63], v[220:223], v[236:239], v[60:63]
	s_waitcnt vmcnt(0)
	s_barrier
	ds_read_b128 v[176:179], v244 offset:32768
	ds_read_b128 v[80:83], v246 offset:32768
	ds_read_b128 v[84:87], v246 offset:34816
	ds_read_b128 v[88:91], v246 offset:36864
	ds_read_b128 v[92:95], v246 offset:38912
	ds_read_b128 v[180:183], v244 offset:34816
	ds_read_b128 v[184:187], v244 offset:36864
	ds_read_b128 v[188:191], v244 offset:38912
	s_waitcnt lgkmcnt(6)
	v_mfma_f32_16x16x32_bf16 v[0:3], v[176:179], v[80:83], v[0:3]
	ds_read_b128 v[208:211], v245 offset:32768
	s_add_i32 m0, s81, 0
	s_waitcnt lgkmcnt(6)
	v_mfma_f32_16x16x32_bf16 v[4:7], v[176:179], v[84:87], v[4:7]
	ds_read_b128 v[224:227], v247 offset:32768
	global_load_lds_dwordx4 v240, s[76:77]
	s_waitcnt lgkmcnt(6)
	v_mfma_f32_16x16x32_bf16 v[8:11], v[176:179], v[88:91], v[8:11]
	ds_read_b128 v[228:231], v247 offset:34816
	s_add_i32 m0, s81, 4096
	s_waitcnt lgkmcnt(6)
	v_mfma_f32_16x16x32_bf16 v[12:15], v[176:179], v[92:95], v[12:15]
	ds_read_b128 v[232:235], v247 offset:36864
	global_load_lds_dwordx4 v241, s[76:77]
	s_waitcnt lgkmcnt(6)
	v_mfma_f32_16x16x32_bf16 v[16:19], v[180:183], v[80:83], v[16:19]
	ds_read_b128 v[236:239], v247 offset:38912
	s_add_i32 m0, s81, 8192
	v_mfma_f32_16x16x32_bf16 v[20:23], v[180:183], v[84:87], v[20:23]
	ds_read_b128 v[212:215], v245 offset:34816
	global_load_lds_dwordx4 v242, s[76:77]
	v_mfma_f32_16x16x32_bf16 v[24:27], v[180:183], v[88:91], v[24:27]
	ds_read_b128 v[216:219], v245 offset:36864
	s_add_i32 m0, s81, 12288
	v_mfma_f32_16x16x32_bf16 v[28:31], v[180:183], v[92:95], v[28:31]
	ds_read_b128 v[220:223], v245 offset:38912
	global_load_lds_dwordx4 v243, s[76:77]
	s_waitcnt lgkmcnt(9)
	v_mfma_f32_16x16x32_bf16 v[32:35], v[184:187], v[80:83], v[32:35]
	s_add_i32 m0, s81, 16384
	v_mfma_f32_16x16x32_bf16 v[36:39], v[184:187], v[84:87], v[36:39]
	global_load_lds_dwordx4 v240, s[78:79]
	v_mfma_f32_16x16x32_bf16 v[40:43], v[184:187], v[88:91], v[40:43]
	s_add_i32 m0, s81, 20480
	v_mfma_f32_16x16x32_bf16 v[44:47], v[184:187], v[92:95], v[44:47]
	global_load_lds_dwordx4 v241, s[78:79]
	s_waitcnt lgkmcnt(8)
	v_mfma_f32_16x16x32_bf16 v[48:51], v[188:191], v[80:83], v[48:51]
	s_add_i32 m0, s81, 24576
	v_mfma_f32_16x16x32_bf16 v[52:55], v[188:191], v[84:87], v[52:55]
	global_load_lds_dwordx4 v242, s[78:79]
	v_mfma_f32_16x16x32_bf16 v[56:59], v[188:191], v[88:91], v[56:59]
	s_add_i32 m0, s81, 28672
	v_mfma_f32_16x16x32_bf16 v[60:63], v[188:191], v[92:95], v[60:63]
	global_load_lds_dwordx4 v243, s[78:79]
	s_waitcnt lgkmcnt(6)
	v_mfma_f32_16x16x32_bf16 v[0:3], v[208:211], v[224:227], v[0:3]
	s_add_u32 s76, s76, 0x80
	s_addc_u32 s77, s77, 0
	s_waitcnt lgkmcnt(5)
	v_mfma_f32_16x16x32_bf16 v[4:7], v[208:211], v[228:231], v[4:7]
	s_waitcnt lgkmcnt(4)
	v_mfma_f32_16x16x32_bf16 v[8:11], v[208:211], v[232:235], v[8:11]
	s_add_u32 s78, s78, 0x80
	s_addc_u32 s79, s79, 0
	s_waitcnt lgkmcnt(3)
	v_mfma_f32_16x16x32_bf16 v[12:15], v[208:211], v[236:239], v[12:15]
	s_waitcnt lgkmcnt(2)
	v_mfma_f32_16x16x32_bf16 v[16:19], v[212:215], v[224:227], v[16:19]
	v_add_u32_e32 v96, 0x0, v102
	v_mfma_f32_16x16x32_bf16 v[20:23], v[212:215], v[228:231], v[20:23]
	global_load_dwordx4 v[64:67], v96, s[86:87] nt
	v_mfma_f32_16x16x32_bf16 v[24:27], v[212:215], v[232:235], v[24:27]
	v_mfma_f32_16x16x32_bf16 v[28:31], v[212:215], v[236:239], v[28:31]
	s_waitcnt lgkmcnt(1)
	v_mfma_f32_16x16x32_bf16 v[32:35], v[216:219], v[224:227], v[32:35]
	v_mfma_f32_16x16x32_bf16 v[36:39], v[216:219], v[228:231], v[36:39]
	v_mfma_f32_16x16x32_bf16 v[40:43], v[216:219], v[232:235], v[40:43]
	v_mfma_f32_16x16x32_bf16 v[44:47], v[216:219], v[236:239], v[44:47]
	s_waitcnt lgkmcnt(0)
	v_mfma_f32_16x16x32_bf16 v[48:51], v[220:223], v[224:227], v[48:51]
	v_mfma_f32_16x16x32_bf16 v[52:55], v[220:223], v[228:231], v[52:55]
	v_mfma_f32_16x16x32_bf16 v[56:59], v[220:223], v[232:235], v[56:59]
	v_mfma_f32_16x16x32_bf16 v[60:63], v[220:223], v[236:239], v[60:63]
	s_waitcnt vmcnt(1)
	s_barrier
	ds_read_b128 v[176:179], v244 offset:0
	ds_read_b128 v[80:83], v246 offset:0
	ds_read_b128 v[84:87], v246 offset:2048
	ds_read_b128 v[88:91], v246 offset:4096
	ds_read_b128 v[92:95], v246 offset:6144
	ds_read_b128 v[180:183], v244 offset:2048
	ds_read_b128 v[184:187], v244 offset:4096
	ds_read_b128 v[188:191], v244 offset:6144
	s_waitcnt lgkmcnt(6)
	v_mfma_f32_16x16x32_bf16 v[0:3], v[176:179], v[80:83], v[0:3]
	ds_read_b128 v[208:211], v245 offset:0
	s_add_i32 m0, s81, 32768
	s_waitcnt lgkmcnt(6)
	v_mfma_f32_16x16x32_bf16 v[4:7], v[176:179], v[84:87], v[4:7]
	ds_read_b128 v[224:227], v247 offset:0
	global_load_lds_dwordx4 v240, s[76:77]
	s_waitcnt lgkmcnt(6)
	v_mfma_f32_16x16x32_bf16 v[8:11], v[176:179], v[88:91], v[8:11]
	ds_read_b128 v[228:231], v247 offset:2048
	s_add_i32 m0, s81, 36864
	s_waitcnt lgkmcnt(6)
	v_mfma_f32_16x16x32_bf16 v[12:15], v[176:179], v[92:95], v[12:15]
	ds_read_b128 v[232:235], v247 offset:4096
	global_load_lds_dwordx4 v241, s[76:77]
	s_waitcnt lgkmcnt(6)
	v_mfma_f32_16x16x32_bf16 v[16:19], v[180:183], v[80:83], v[16:19]
	ds_read_b128 v[236:239], v247 offset:6144
	s_add_i32 m0, s81, 40960
	v_mfma_f32_16x16x32_bf16 v[20:23], v[180:183], v[84:87], v[20:23]
	ds_read_b128 v[212:215], v245 offset:2048
	global_load_lds_dwordx4 v242, s[76:77]
	v_mfma_f32_16x16x32_bf16 v[24:27], v[180:183], v[88:91], v[24:27]
	ds_read_b128 v[216:219], v245 offset:4096
	s_add_i32 m0, s81, 45056
	v_mfma_f32_16x16x32_bf16 v[28:31], v[180:183], v[92:95], v[28:31]
	ds_read_b128 v[220:223], v245 offset:6144
	global_load_lds_dwordx4 v243, s[76:77]
	s_waitcnt lgkmcnt(9)
	v_mfma_f32_16x16x32_bf16 v[32:35], v[184:187], v[80:83], v[32:35]
	s_add_i32 m0, s81, 49152
	v_mfma_f32_16x16x32_bf16 v[36:39], v[184:187], v[84:87], v[36:39]
	global_load_lds_dwordx4 v240, s[78:79]
	v_mfma_f32_16x16x32_bf16 v[40:43], v[184:187], v[88:91], v[40:43]
	s_add_i32 m0, s81, 53248
	v_mfma_f32_16x16x32_bf16 v[44:47], v[184:187], v[92:95], v[44:47]
	global_load_lds_dwordx4 v241, s[78:79]
	s_waitcnt lgkmcnt(8)
	v_mfma_f32_16x16x32_bf16 v[48:51], v[188:191], v[80:83], v[48:51]
	s_add_i32 m0, s81, 57344
	v_mfma_f32_16x16x32_bf16 v[52:55], v[188:191], v[84:87], v[52:55]
	global_load_lds_dwordx4 v242, s[78:79]
	v_mfma_f32_16x16x32_bf16 v[56:59], v[188:191], v[88:91], v[56:59]
	s_add_i32 m0, s81, 61440
	v_mfma_f32_16x16x32_bf16 v[60:63], v[188:191], v[92:95], v[60:63]
	global_load_lds_dwordx4 v243, s[78:79]
	s_waitcnt lgkmcnt(6)
	v_mfma_f32_16x16x32_bf16 v[0:3], v[208:211], v[224:227], v[0:3]
	s_add_u32 s76, s76, 0x80
	s_addc_u32 s77, s77, 0
	s_waitcnt lgkmcnt(5)
	v_mfma_f32_16x16x32_bf16 v[4:7], v[208:211], v[228:231], v[4:7]
	s_waitcnt lgkmcnt(4)
	v_mfma_f32_16x16x32_bf16 v[8:11], v[208:211], v[232:235], v[8:11]
	s_add_u32 s78, s78, 0x80
	s_addc_u32 s79, s79, 0
	s_waitcnt lgkmcnt(3)
	v_mfma_f32_16x16x32_bf16 v[12:15], v[208:211], v[236:239], v[12:15]
	s_waitcnt lgkmcnt(2)
	v_mfma_f32_16x16x32_bf16 v[16:19], v[212:215], v[224:227], v[16:19]
	v_add_u32_e32 v96, 0x0, v102
	v_mfma_f32_16x16x32_bf16 v[20:23], v[212:215], v[228:231], v[20:23]
	global_load_dwordx4 v[68:71], v96, s[86:87] offset:16 nt
	v_mfma_f32_16x16x32_bf16 v[24:27], v[212:215], v[232:235], v[24:27]
	v_mfma_f32_16x16x32_bf16 v[28:31], v[212:215], v[236:239], v[28:31]
	s_waitcnt lgkmcnt(1)
	v_mfma_f32_16x16x32_bf16 v[32:35], v[216:219], v[224:227], v[32:35]
	v_mfma_f32_16x16x32_bf16 v[36:39], v[216:219], v[228:231], v[36:39]
	v_mfma_f32_16x16x32_bf16 v[40:43], v[216:219], v[232:235], v[40:43]
	v_mfma_f32_16x16x32_bf16 v[44:47], v[216:219], v[236:239], v[44:47]
	s_waitcnt lgkmcnt(0)
	v_mfma_f32_16x16x32_bf16 v[48:51], v[220:223], v[224:227], v[48:51]
	v_mfma_f32_16x16x32_bf16 v[52:55], v[220:223], v[228:231], v[52:55]
	v_mfma_f32_16x16x32_bf16 v[56:59], v[220:223], v[232:235], v[56:59]
	v_mfma_f32_16x16x32_bf16 v[60:63], v[220:223], v[236:239], v[60:63]
	s_waitcnt vmcnt(1)
	s_barrier
	ds_read_b128 v[176:179], v244 offset:32768
	ds_read_b128 v[80:83], v246 offset:32768
	ds_read_b128 v[84:87], v246 offset:34816
	ds_read_b128 v[88:91], v246 offset:36864
	ds_read_b128 v[92:95], v246 offset:38912
	ds_read_b128 v[180:183], v244 offset:34816
	ds_read_b128 v[184:187], v244 offset:36864
	ds_read_b128 v[188:191], v244 offset:38912
	s_waitcnt lgkmcnt(6)
	v_mfma_f32_16x16x32_bf16 v[0:3], v[176:179], v[80:83], v[0:3]
	ds_read_b128 v[208:211], v245 offset:32768
	s_add_i32 m0, s81, 0
	s_waitcnt lgkmcnt(6)
	v_mfma_f32_16x16x32_bf16 v[4:7], v[176:179], v[84:87], v[4:7]
	ds_read_b128 v[224:227], v247 offset:32768
	global_load_lds_dwordx4 v240, s[76:77]
	s_waitcnt lgkmcnt(6)
	v_mfma_f32_16x16x32_bf16 v[8:11], v[176:179], v[88:91], v[8:11]
	ds_read_b128 v[228:231], v247 offset:34816
	s_add_i32 m0, s81, 4096
	s_waitcnt lgkmcnt(6)
	v_mfma_f32_16x16x32_bf16 v[12:15], v[176:179], v[92:95], v[12:15]
	ds_read_b128 v[232:235], v247 offset:36864
	global_load_lds_dwordx4 v241, s[76:77]
	s_waitcnt lgkmcnt(6)
	v_mfma_f32_16x16x32_bf16 v[16:19], v[180:183], v[80:83], v[16:19]
	ds_read_b128 v[236:239], v247 offset:38912
	s_add_i32 m0, s81, 8192
	v_mfma_f32_16x16x32_bf16 v[20:23], v[180:183], v[84:87], v[20:23]
	ds_read_b128 v[212:215], v245 offset:34816
	global_load_lds_dwordx4 v242, s[76:77]
	v_mfma_f32_16x16x32_bf16 v[24:27], v[180:183], v[88:91], v[24:27]
	ds_read_b128 v[216:219], v245 offset:36864
	s_add_i32 m0, s81, 12288
	v_mfma_f32_16x16x32_bf16 v[28:31], v[180:183], v[92:95], v[28:31]
	ds_read_b128 v[220:223], v245 offset:38912
	global_load_lds_dwordx4 v243, s[76:77]
	s_waitcnt lgkmcnt(9)
	v_mfma_f32_16x16x32_bf16 v[32:35], v[184:187], v[80:83], v[32:35]
	s_add_i32 m0, s81, 16384
	v_mfma_f32_16x16x32_bf16 v[36:39], v[184:187], v[84:87], v[36:39]
	global_load_lds_dwordx4 v240, s[78:79]
	v_mfma_f32_16x16x32_bf16 v[40:43], v[184:187], v[88:91], v[40:43]
	s_add_i32 m0, s81, 20480
	v_mfma_f32_16x16x32_bf16 v[44:47], v[184:187], v[92:95], v[44:47]
	global_load_lds_dwordx4 v241, s[78:79]
	s_waitcnt lgkmcnt(8)
	v_mfma_f32_16x16x32_bf16 v[48:51], v[188:191], v[80:83], v[48:51]
	s_add_i32 m0, s81, 24576
	v_mfma_f32_16x16x32_bf16 v[52:55], v[188:191], v[84:87], v[52:55]
	global_load_lds_dwordx4 v242, s[78:79]
	v_mfma_f32_16x16x32_bf16 v[56:59], v[188:191], v[88:91], v[56:59]
	s_add_i32 m0, s81, 28672
	v_mfma_f32_16x16x32_bf16 v[60:63], v[188:191], v[92:95], v[60:63]
	global_load_lds_dwordx4 v243, s[78:79]
	s_waitcnt lgkmcnt(6)
	v_mfma_f32_16x16x32_bf16 v[0:3], v[208:211], v[224:227], v[0:3]
	s_add_u32 s76, s76, 0x80
	s_addc_u32 s77, s77, 0
	s_waitcnt lgkmcnt(5)
	v_mfma_f32_16x16x32_bf16 v[4:7], v[208:211], v[228:231], v[4:7]
	s_waitcnt lgkmcnt(4)
	v_mfma_f32_16x16x32_bf16 v[8:11], v[208:211], v[232:235], v[8:11]
	s_add_u32 s78, s78, 0x80
	s_addc_u32 s79, s79, 0
	s_waitcnt lgkmcnt(3)
	v_mfma_f32_16x16x32_bf16 v[12:15], v[208:211], v[236:239], v[12:15]
	s_waitcnt lgkmcnt(2)
	v_mfma_f32_16x16x32_bf16 v[16:19], v[212:215], v[224:227], v[16:19]
	v_add_u32_e32 v96, 0x10000, v102
	v_mfma_f32_16x16x32_bf16 v[20:23], v[212:215], v[228:231], v[20:23]
	global_load_dwordx4 v[74:77], v96, s[86:87] nt
	v_mfma_f32_16x16x32_bf16 v[24:27], v[212:215], v[232:235], v[24:27]
	v_mfma_f32_16x16x32_bf16 v[28:31], v[212:215], v[236:239], v[28:31]
	s_waitcnt lgkmcnt(1)
	v_mfma_f32_16x16x32_bf16 v[32:35], v[216:219], v[224:227], v[32:35]
	v_mfma_f32_16x16x32_bf16 v[36:39], v[216:219], v[228:231], v[36:39]
	v_mfma_f32_16x16x32_bf16 v[40:43], v[216:219], v[232:235], v[40:43]
	v_mfma_f32_16x16x32_bf16 v[44:47], v[216:219], v[236:239], v[44:47]
	s_waitcnt lgkmcnt(0)
	v_mfma_f32_16x16x32_bf16 v[48:51], v[220:223], v[224:227], v[48:51]
	v_mfma_f32_16x16x32_bf16 v[52:55], v[220:223], v[228:231], v[52:55]
	v_mfma_f32_16x16x32_bf16 v[56:59], v[220:223], v[232:235], v[56:59]
	v_mfma_f32_16x16x32_bf16 v[60:63], v[220:223], v[236:239], v[60:63]
	s_waitcnt vmcnt(1)
	s_barrier
	ds_read_b128 v[176:179], v244 offset:0
	ds_read_b128 v[80:83], v246 offset:0
	ds_read_b128 v[84:87], v246 offset:2048
	ds_read_b128 v[88:91], v246 offset:4096
	ds_read_b128 v[92:95], v246 offset:6144
	ds_read_b128 v[180:183], v244 offset:2048
	ds_read_b128 v[184:187], v244 offset:4096
	ds_read_b128 v[188:191], v244 offset:6144
	s_waitcnt lgkmcnt(6)
	v_mfma_f32_16x16x32_bf16 v[0:3], v[176:179], v[80:83], v[0:3]
	ds_read_b128 v[208:211], v245 offset:0
	s_add_i32 m0, s81, 32768
	s_waitcnt lgkmcnt(6)
	v_mfma_f32_16x16x32_bf16 v[4:7], v[176:179], v[84:87], v[4:7]
	ds_read_b128 v[224:227], v247 offset:0
	global_load_lds_dwordx4 v240, s[76:77]
	s_waitcnt lgkmcnt(6)
	v_mfma_f32_16x16x32_bf16 v[8:11], v[176:179], v[88:91], v[8:11]
	ds_read_b128 v[228:231], v247 offset:2048
	s_add_i32 m0, s81, 36864
	s_waitcnt lgkmcnt(6)
	v_mfma_f32_16x16x32_bf16 v[12:15], v[176:179], v[92:95], v[12:15]
	ds_read_b128 v[232:235], v247 offset:4096
	global_load_lds_dwordx4 v241, s[76:77]
	s_waitcnt lgkmcnt(6)
	v_mfma_f32_16x16x32_bf16 v[16:19], v[180:183], v[80:83], v[16:19]
	ds_read_b128 v[236:239], v247 offset:6144
	s_add_i32 m0, s81, 40960
	v_mfma_f32_16x16x32_bf16 v[20:23], v[180:183], v[84:87], v[20:23]
	ds_read_b128 v[212:215], v245 offset:2048
	global_load_lds_dwordx4 v242, s[76:77]
	v_mfma_f32_16x16x32_bf16 v[24:27], v[180:183], v[88:91], v[24:27]
	ds_read_b128 v[216:219], v245 offset:4096
	s_add_i32 m0, s81, 45056
	v_mfma_f32_16x16x32_bf16 v[28:31], v[180:183], v[92:95], v[28:31]
	ds_read_b128 v[220:223], v245 offset:6144
	global_load_lds_dwordx4 v243, s[76:77]
	s_waitcnt lgkmcnt(9)
	v_mfma_f32_16x16x32_bf16 v[32:35], v[184:187], v[80:83], v[32:35]
	s_add_i32 m0, s81, 49152
	v_mfma_f32_16x16x32_bf16 v[36:39], v[184:187], v[84:87], v[36:39]
	global_load_lds_dwordx4 v240, s[78:79]
	v_mfma_f32_16x16x32_bf16 v[40:43], v[184:187], v[88:91], v[40:43]
	s_add_i32 m0, s81, 53248
	v_mfma_f32_16x16x32_bf16 v[44:47], v[184:187], v[92:95], v[44:47]
	global_load_lds_dwordx4 v241, s[78:79]
	s_waitcnt lgkmcnt(8)
	v_mfma_f32_16x16x32_bf16 v[48:51], v[188:191], v[80:83], v[48:51]
	s_add_i32 m0, s81, 57344
	v_mfma_f32_16x16x32_bf16 v[52:55], v[188:191], v[84:87], v[52:55]
	global_load_lds_dwordx4 v242, s[78:79]
	v_mfma_f32_16x16x32_bf16 v[56:59], v[188:191], v[88:91], v[56:59]
	s_add_i32 m0, s81, 61440
	v_mfma_f32_16x16x32_bf16 v[60:63], v[188:191], v[92:95], v[60:63]
	global_load_lds_dwordx4 v243, s[78:79]
	s_waitcnt lgkmcnt(6)
	v_mfma_f32_16x16x32_bf16 v[0:3], v[208:211], v[224:227], v[0:3]
	s_add_u32 s76, s76, 0x80
	s_addc_u32 s77, s77, 0
	s_waitcnt lgkmcnt(5)
	v_mfma_f32_16x16x32_bf16 v[4:7], v[208:211], v[228:231], v[4:7]
	s_waitcnt lgkmcnt(4)
	v_mfma_f32_16x16x32_bf16 v[8:11], v[208:211], v[232:235], v[8:11]
	s_add_u32 s78, s78, 0x80
	s_addc_u32 s79, s79, 0
	s_waitcnt lgkmcnt(3)
	v_mfma_f32_16x16x32_bf16 v[12:15], v[208:211], v[236:239], v[12:15]
	s_waitcnt lgkmcnt(2)
	v_mfma_f32_16x16x32_bf16 v[16:19], v[212:215], v[224:227], v[16:19]
	v_add_u32_e32 v96, 0x10000, v102
	v_mfma_f32_16x16x32_bf16 v[20:23], v[212:215], v[228:231], v[20:23]
	global_load_dwordx4 v[98:101], v96, s[86:87] offset:16 nt
	v_mfma_f32_16x16x32_bf16 v[24:27], v[212:215], v[232:235], v[24:27]
	v_mfma_f32_16x16x32_bf16 v[28:31], v[212:215], v[236:239], v[28:31]
	s_waitcnt lgkmcnt(1)
	v_mfma_f32_16x16x32_bf16 v[32:35], v[216:219], v[224:227], v[32:35]
	v_mfma_f32_16x16x32_bf16 v[36:39], v[216:219], v[228:231], v[36:39]
	v_mfma_f32_16x16x32_bf16 v[40:43], v[216:219], v[232:235], v[40:43]
	v_mfma_f32_16x16x32_bf16 v[44:47], v[216:219], v[236:239], v[44:47]
	s_waitcnt lgkmcnt(0)
	v_mfma_f32_16x16x32_bf16 v[48:51], v[220:223], v[224:227], v[48:51]
	v_mfma_f32_16x16x32_bf16 v[52:55], v[220:223], v[228:231], v[52:55]
	v_mfma_f32_16x16x32_bf16 v[56:59], v[220:223], v[232:235], v[56:59]
	v_mfma_f32_16x16x32_bf16 v[60:63], v[220:223], v[236:239], v[60:63]
	s_waitcnt vmcnt(1)
	s_barrier
	ds_read_b128 v[176:179], v244 offset:32768
	ds_read_b128 v[80:83], v246 offset:32768
	ds_read_b128 v[84:87], v246 offset:34816
	ds_read_b128 v[88:91], v246 offset:36864
	ds_read_b128 v[92:95], v246 offset:38912
	ds_read_b128 v[180:183], v244 offset:34816
	ds_read_b128 v[184:187], v244 offset:36864
	ds_read_b128 v[188:191], v244 offset:38912
	s_waitcnt lgkmcnt(6)
	v_mfma_f32_16x16x32_bf16 v[0:3], v[176:179], v[80:83], v[0:3]
	ds_read_b128 v[208:211], v245 offset:32768
	s_add_i32 m0, s81, 0
	s_waitcnt lgkmcnt(6)
	v_mfma_f32_16x16x32_bf16 v[4:7], v[176:179], v[84:87], v[4:7]
	ds_read_b128 v[224:227], v247 offset:32768
	global_load_lds_dwordx4 v240, s[76:77]
	s_waitcnt lgkmcnt(6)
	v_mfma_f32_16x16x32_bf16 v[8:11], v[176:179], v[88:91], v[8:11]
	ds_read_b128 v[228:231], v247 offset:34816
	s_add_i32 m0, s81, 4096
	s_waitcnt lgkmcnt(6)
	v_mfma_f32_16x16x32_bf16 v[12:15], v[176:179], v[92:95], v[12:15]
	ds_read_b128 v[232:235], v247 offset:36864
	global_load_lds_dwordx4 v241, s[76:77]
	s_waitcnt lgkmcnt(6)
	v_mfma_f32_16x16x32_bf16 v[16:19], v[180:183], v[80:83], v[16:19]
	ds_read_b128 v[236:239], v247 offset:38912
	s_add_i32 m0, s81, 8192
	v_mfma_f32_16x16x32_bf16 v[20:23], v[180:183], v[84:87], v[20:23]
	ds_read_b128 v[212:215], v245 offset:34816
	global_load_lds_dwordx4 v242, s[76:77]
	v_mfma_f32_16x16x32_bf16 v[24:27], v[180:183], v[88:91], v[24:27]
	ds_read_b128 v[216:219], v245 offset:36864
	s_add_i32 m0, s81, 12288
	v_mfma_f32_16x16x32_bf16 v[28:31], v[180:183], v[92:95], v[28:31]
	ds_read_b128 v[220:223], v245 offset:38912
	global_load_lds_dwordx4 v243, s[76:77]
	s_waitcnt lgkmcnt(9)
	v_mfma_f32_16x16x32_bf16 v[32:35], v[184:187], v[80:83], v[32:35]
	s_add_i32 m0, s81, 16384
	v_mfma_f32_16x16x32_bf16 v[36:39], v[184:187], v[84:87], v[36:39]
	global_load_lds_dwordx4 v240, s[78:79]
	v_mfma_f32_16x16x32_bf16 v[40:43], v[184:187], v[88:91], v[40:43]
	s_add_i32 m0, s81, 20480
	v_mfma_f32_16x16x32_bf16 v[44:47], v[184:187], v[92:95], v[44:47]
	global_load_lds_dwordx4 v241, s[78:79]
	s_waitcnt lgkmcnt(8)
	v_mfma_f32_16x16x32_bf16 v[48:51], v[188:191], v[80:83], v[48:51]
	s_add_i32 m0, s81, 24576
	v_mfma_f32_16x16x32_bf16 v[52:55], v[188:191], v[84:87], v[52:55]
	global_load_lds_dwordx4 v242, s[78:79]
	v_mfma_f32_16x16x32_bf16 v[56:59], v[188:191], v[88:91], v[56:59]
	s_add_i32 m0, s81, 28672
	v_mfma_f32_16x16x32_bf16 v[60:63], v[188:191], v[92:95], v[60:63]
	global_load_lds_dwordx4 v243, s[78:79]
	s_waitcnt lgkmcnt(6)
	v_mfma_f32_16x16x32_bf16 v[0:3], v[208:211], v[224:227], v[0:3]
	s_add_u32 s76, s76, 0x80
	s_addc_u32 s77, s77, 0
	s_waitcnt lgkmcnt(5)
	v_mfma_f32_16x16x32_bf16 v[4:7], v[208:211], v[228:231], v[4:7]
	s_waitcnt lgkmcnt(4)
	v_mfma_f32_16x16x32_bf16 v[8:11], v[208:211], v[232:235], v[8:11]
	s_add_u32 s78, s78, 0x80
	s_addc_u32 s79, s79, 0
	s_waitcnt lgkmcnt(3)
	v_mfma_f32_16x16x32_bf16 v[12:15], v[208:211], v[236:239], v[12:15]
	s_waitcnt lgkmcnt(2)
	v_mfma_f32_16x16x32_bf16 v[16:19], v[212:215], v[224:227], v[16:19]
	v_add_u32_e32 v96, 0x20000, v102
	v_mfma_f32_16x16x32_bf16 v[20:23], v[212:215], v[228:231], v[20:23]
	global_load_dwordx4 v[104:107], v96, s[86:87] nt
	v_mfma_f32_16x16x32_bf16 v[24:27], v[212:215], v[232:235], v[24:27]
	v_mfma_f32_16x16x32_bf16 v[28:31], v[212:215], v[236:239], v[28:31]
	s_waitcnt lgkmcnt(1)
	v_mfma_f32_16x16x32_bf16 v[32:35], v[216:219], v[224:227], v[32:35]
	v_mfma_f32_16x16x32_bf16 v[36:39], v[216:219], v[228:231], v[36:39]
	v_mfma_f32_16x16x32_bf16 v[40:43], v[216:219], v[232:235], v[40:43]
	v_mfma_f32_16x16x32_bf16 v[44:47], v[216:219], v[236:239], v[44:47]
	s_waitcnt lgkmcnt(0)
	v_mfma_f32_16x16x32_bf16 v[48:51], v[220:223], v[224:227], v[48:51]
	v_mfma_f32_16x16x32_bf16 v[52:55], v[220:223], v[228:231], v[52:55]
	v_mfma_f32_16x16x32_bf16 v[56:59], v[220:223], v[232:235], v[56:59]
	v_mfma_f32_16x16x32_bf16 v[60:63], v[220:223], v[236:239], v[60:63]
	s_waitcnt vmcnt(1)
	s_barrier
	ds_read_b128 v[176:179], v244 offset:0
	ds_read_b128 v[80:83], v246 offset:0
	ds_read_b128 v[84:87], v246 offset:2048
	ds_read_b128 v[88:91], v246 offset:4096
	ds_read_b128 v[92:95], v246 offset:6144
	ds_read_b128 v[180:183], v244 offset:2048
	ds_read_b128 v[184:187], v244 offset:4096
	ds_read_b128 v[188:191], v244 offset:6144
	s_waitcnt lgkmcnt(6)
	v_mfma_f32_16x16x32_bf16 v[0:3], v[176:179], v[80:83], v[0:3]
	ds_read_b128 v[208:211], v245 offset:0
	s_add_i32 m0, s81, 32768
	s_waitcnt lgkmcnt(6)
	v_mfma_f32_16x16x32_bf16 v[4:7], v[176:179], v[84:87], v[4:7]
	ds_read_b128 v[224:227], v247 offset:0
	global_load_lds_dwordx4 v240, s[76:77]
	s_waitcnt lgkmcnt(6)
	v_mfma_f32_16x16x32_bf16 v[8:11], v[176:179], v[88:91], v[8:11]
	ds_read_b128 v[228:231], v247 offset:2048
	s_add_i32 m0, s81, 36864
	s_waitcnt lgkmcnt(6)
	v_mfma_f32_16x16x32_bf16 v[12:15], v[176:179], v[92:95], v[12:15]
	ds_read_b128 v[232:235], v247 offset:4096
	global_load_lds_dwordx4 v241, s[76:77]
	s_waitcnt lgkmcnt(6)
	v_mfma_f32_16x16x32_bf16 v[16:19], v[180:183], v[80:83], v[16:19]
	ds_read_b128 v[236:239], v247 offset:6144
	s_add_i32 m0, s81, 40960
	v_mfma_f32_16x16x32_bf16 v[20:23], v[180:183], v[84:87], v[20:23]
	ds_read_b128 v[212:215], v245 offset:2048
	global_load_lds_dwordx4 v242, s[76:77]
	v_mfma_f32_16x16x32_bf16 v[24:27], v[180:183], v[88:91], v[24:27]
	ds_read_b128 v[216:219], v245 offset:4096
	s_add_i32 m0, s81, 45056
	v_mfma_f32_16x16x32_bf16 v[28:31], v[180:183], v[92:95], v[28:31]
	ds_read_b128 v[220:223], v245 offset:6144
	global_load_lds_dwordx4 v243, s[76:77]
	s_waitcnt lgkmcnt(9)
	v_mfma_f32_16x16x32_bf16 v[32:35], v[184:187], v[80:83], v[32:35]
	s_add_i32 m0, s81, 49152
	v_mfma_f32_16x16x32_bf16 v[36:39], v[184:187], v[84:87], v[36:39]
	global_load_lds_dwordx4 v240, s[78:79]
	v_mfma_f32_16x16x32_bf16 v[40:43], v[184:187], v[88:91], v[40:43]
	s_add_i32 m0, s81, 53248
	v_mfma_f32_16x16x32_bf16 v[44:47], v[184:187], v[92:95], v[44:47]
	global_load_lds_dwordx4 v241, s[78:79]
	s_waitcnt lgkmcnt(8)
	v_mfma_f32_16x16x32_bf16 v[48:51], v[188:191], v[80:83], v[48:51]
	s_add_i32 m0, s81, 57344
	v_mfma_f32_16x16x32_bf16 v[52:55], v[188:191], v[84:87], v[52:55]
	global_load_lds_dwordx4 v242, s[78:79]
	v_mfma_f32_16x16x32_bf16 v[56:59], v[188:191], v[88:91], v[56:59]
	s_add_i32 m0, s81, 61440
	v_mfma_f32_16x16x32_bf16 v[60:63], v[188:191], v[92:95], v[60:63]
	global_load_lds_dwordx4 v243, s[78:79]
	s_waitcnt lgkmcnt(6)
	v_mfma_f32_16x16x32_bf16 v[0:3], v[208:211], v[224:227], v[0:3]
	s_add_u32 s76, s76, 0x80
	s_addc_u32 s77, s77, 0
	s_waitcnt lgkmcnt(5)
	v_mfma_f32_16x16x32_bf16 v[4:7], v[208:211], v[228:231], v[4:7]
	s_waitcnt lgkmcnt(4)
	v_mfma_f32_16x16x32_bf16 v[8:11], v[208:211], v[232:235], v[8:11]
	s_add_u32 s78, s78, 0x80
	s_addc_u32 s79, s79, 0
	s_waitcnt lgkmcnt(3)
	v_mfma_f32_16x16x32_bf16 v[12:15], v[208:211], v[236:239], v[12:15]
	s_waitcnt lgkmcnt(2)
	v_mfma_f32_16x16x32_bf16 v[16:19], v[212:215], v[224:227], v[16:19]
	v_add_u32_e32 v96, 0x20000, v102
	v_mfma_f32_16x16x32_bf16 v[20:23], v[212:215], v[228:231], v[20:23]
	global_load_dwordx4 v[110:113], v96, s[86:87] offset:16 nt
	v_mfma_f32_16x16x32_bf16 v[24:27], v[212:215], v[232:235], v[24:27]
	v_mfma_f32_16x16x32_bf16 v[28:31], v[212:215], v[236:239], v[28:31]
	s_waitcnt lgkmcnt(1)
	v_mfma_f32_16x16x32_bf16 v[32:35], v[216:219], v[224:227], v[32:35]
	v_mfma_f32_16x16x32_bf16 v[36:39], v[216:219], v[228:231], v[36:39]
	v_mfma_f32_16x16x32_bf16 v[40:43], v[216:219], v[232:235], v[40:43]
	v_mfma_f32_16x16x32_bf16 v[44:47], v[216:219], v[236:239], v[44:47]
	s_waitcnt lgkmcnt(0)
	v_mfma_f32_16x16x32_bf16 v[48:51], v[220:223], v[224:227], v[48:51]
	v_mfma_f32_16x16x32_bf16 v[52:55], v[220:223], v[228:231], v[52:55]
	v_mfma_f32_16x16x32_bf16 v[56:59], v[220:223], v[232:235], v[56:59]
	v_mfma_f32_16x16x32_bf16 v[60:63], v[220:223], v[236:239], v[60:63]
	s_waitcnt vmcnt(1)
	s_barrier
	ds_read_b128 v[176:179], v244 offset:32768
	ds_read_b128 v[80:83], v246 offset:32768
	ds_read_b128 v[84:87], v246 offset:34816
	ds_read_b128 v[88:91], v246 offset:36864
	ds_read_b128 v[92:95], v246 offset:38912
	ds_read_b128 v[180:183], v244 offset:34816
	ds_read_b128 v[184:187], v244 offset:36864
	ds_read_b128 v[188:191], v244 offset:38912
	s_waitcnt lgkmcnt(6)
	v_mfma_f32_16x16x32_bf16 v[0:3], v[176:179], v[80:83], v[0:3]
	ds_read_b128 v[208:211], v245 offset:32768
	s_add_i32 m0, s81, 0
	s_waitcnt lgkmcnt(6)
	v_mfma_f32_16x16x32_bf16 v[4:7], v[176:179], v[84:87], v[4:7]
	ds_read_b128 v[224:227], v247 offset:32768
	global_load_lds_dwordx4 v240, s[76:77]
	s_waitcnt lgkmcnt(6)
	v_mfma_f32_16x16x32_bf16 v[8:11], v[176:179], v[88:91], v[8:11]
	ds_read_b128 v[228:231], v247 offset:34816
	s_add_i32 m0, s81, 4096
	s_waitcnt lgkmcnt(6)
	v_mfma_f32_16x16x32_bf16 v[12:15], v[176:179], v[92:95], v[12:15]
	ds_read_b128 v[232:235], v247 offset:36864
	global_load_lds_dwordx4 v241, s[76:77]
	s_waitcnt lgkmcnt(6)
	v_mfma_f32_16x16x32_bf16 v[16:19], v[180:183], v[80:83], v[16:19]
	ds_read_b128 v[236:239], v247 offset:38912
	s_add_i32 m0, s81, 8192
	v_mfma_f32_16x16x32_bf16 v[20:23], v[180:183], v[84:87], v[20:23]
	ds_read_b128 v[212:215], v245 offset:34816
	global_load_lds_dwordx4 v242, s[76:77]
	v_mfma_f32_16x16x32_bf16 v[24:27], v[180:183], v[88:91], v[24:27]
	ds_read_b128 v[216:219], v245 offset:36864
	s_add_i32 m0, s81, 12288
	v_mfma_f32_16x16x32_bf16 v[28:31], v[180:183], v[92:95], v[28:31]
	ds_read_b128 v[220:223], v245 offset:38912
	global_load_lds_dwordx4 v243, s[76:77]
	s_waitcnt lgkmcnt(9)
	v_mfma_f32_16x16x32_bf16 v[32:35], v[184:187], v[80:83], v[32:35]
	s_add_i32 m0, s81, 16384
	v_mfma_f32_16x16x32_bf16 v[36:39], v[184:187], v[84:87], v[36:39]
	global_load_lds_dwordx4 v240, s[78:79]
	v_mfma_f32_16x16x32_bf16 v[40:43], v[184:187], v[88:91], v[40:43]
	s_add_i32 m0, s81, 20480
	v_mfma_f32_16x16x32_bf16 v[44:47], v[184:187], v[92:95], v[44:47]
	global_load_lds_dwordx4 v241, s[78:79]
	s_waitcnt lgkmcnt(8)
	v_mfma_f32_16x16x32_bf16 v[48:51], v[188:191], v[80:83], v[48:51]
	s_add_i32 m0, s81, 24576
	v_mfma_f32_16x16x32_bf16 v[52:55], v[188:191], v[84:87], v[52:55]
	global_load_lds_dwordx4 v242, s[78:79]
	v_mfma_f32_16x16x32_bf16 v[56:59], v[188:191], v[88:91], v[56:59]
	s_add_i32 m0, s81, 28672
	v_mfma_f32_16x16x32_bf16 v[60:63], v[188:191], v[92:95], v[60:63]
	global_load_lds_dwordx4 v243, s[78:79]
	s_waitcnt lgkmcnt(6)
	v_mfma_f32_16x16x32_bf16 v[0:3], v[208:211], v[224:227], v[0:3]
	s_add_u32 s76, s76, 0x80
	s_addc_u32 s77, s77, 0
	s_waitcnt lgkmcnt(5)
	v_mfma_f32_16x16x32_bf16 v[4:7], v[208:211], v[228:231], v[4:7]
	s_waitcnt lgkmcnt(4)
	v_mfma_f32_16x16x32_bf16 v[8:11], v[208:211], v[232:235], v[8:11]
	s_add_u32 s78, s78, 0x80
	s_addc_u32 s79, s79, 0
	s_waitcnt lgkmcnt(3)
	v_mfma_f32_16x16x32_bf16 v[12:15], v[208:211], v[236:239], v[12:15]
	s_waitcnt lgkmcnt(2)
	v_mfma_f32_16x16x32_bf16 v[16:19], v[212:215], v[224:227], v[16:19]
	v_add_u32_e32 v96, 0x30000, v102
	v_mfma_f32_16x16x32_bf16 v[20:23], v[212:215], v[228:231], v[20:23]
	global_load_dwordx4 v[116:119], v96, s[86:87] nt
	v_mfma_f32_16x16x32_bf16 v[24:27], v[212:215], v[232:235], v[24:27]
	v_mfma_f32_16x16x32_bf16 v[28:31], v[212:215], v[236:239], v[28:31]
	s_waitcnt lgkmcnt(1)
	v_mfma_f32_16x16x32_bf16 v[32:35], v[216:219], v[224:227], v[32:35]
	v_mfma_f32_16x16x32_bf16 v[36:39], v[216:219], v[228:231], v[36:39]
	v_mfma_f32_16x16x32_bf16 v[40:43], v[216:219], v[232:235], v[40:43]
	v_mfma_f32_16x16x32_bf16 v[44:47], v[216:219], v[236:239], v[44:47]
	s_waitcnt lgkmcnt(0)
	v_mfma_f32_16x16x32_bf16 v[48:51], v[220:223], v[224:227], v[48:51]
	v_mfma_f32_16x16x32_bf16 v[52:55], v[220:223], v[228:231], v[52:55]
	v_mfma_f32_16x16x32_bf16 v[56:59], v[220:223], v[232:235], v[56:59]
	v_mfma_f32_16x16x32_bf16 v[60:63], v[220:223], v[236:239], v[60:63]
	s_waitcnt vmcnt(1)
	s_barrier
	ds_read_b128 v[176:179], v244 offset:0
	ds_read_b128 v[80:83], v246 offset:0
	ds_read_b128 v[84:87], v246 offset:2048
	ds_read_b128 v[88:91], v246 offset:4096
	ds_read_b128 v[92:95], v246 offset:6144
	ds_read_b128 v[180:183], v244 offset:2048
	ds_read_b128 v[184:187], v244 offset:4096
	ds_read_b128 v[188:191], v244 offset:6144
	s_waitcnt lgkmcnt(6)
	v_mfma_f32_16x16x32_bf16 v[0:3], v[176:179], v[80:83], v[0:3]
	ds_read_b128 v[208:211], v245 offset:0
	s_add_i32 m0, s81, 32768
	s_waitcnt lgkmcnt(6)
	v_mfma_f32_16x16x32_bf16 v[4:7], v[176:179], v[84:87], v[4:7]
	ds_read_b128 v[224:227], v247 offset:0
	global_load_lds_dwordx4 v240, s[76:77]
	s_waitcnt lgkmcnt(6)
	v_mfma_f32_16x16x32_bf16 v[8:11], v[176:179], v[88:91], v[8:11]
	ds_read_b128 v[228:231], v247 offset:2048
	s_add_i32 m0, s81, 36864
	s_waitcnt lgkmcnt(6)
	v_mfma_f32_16x16x32_bf16 v[12:15], v[176:179], v[92:95], v[12:15]
	ds_read_b128 v[232:235], v247 offset:4096
	global_load_lds_dwordx4 v241, s[76:77]
	s_waitcnt lgkmcnt(6)
	v_mfma_f32_16x16x32_bf16 v[16:19], v[180:183], v[80:83], v[16:19]
	ds_read_b128 v[236:239], v247 offset:6144
	s_add_i32 m0, s81, 40960
	v_mfma_f32_16x16x32_bf16 v[20:23], v[180:183], v[84:87], v[20:23]
	ds_read_b128 v[212:215], v245 offset:2048
	global_load_lds_dwordx4 v242, s[76:77]
	v_mfma_f32_16x16x32_bf16 v[24:27], v[180:183], v[88:91], v[24:27]
	ds_read_b128 v[216:219], v245 offset:4096
	s_add_i32 m0, s81, 45056
	v_mfma_f32_16x16x32_bf16 v[28:31], v[180:183], v[92:95], v[28:31]
	ds_read_b128 v[220:223], v245 offset:6144
	global_load_lds_dwordx4 v243, s[76:77]
	s_waitcnt lgkmcnt(9)
	v_mfma_f32_16x16x32_bf16 v[32:35], v[184:187], v[80:83], v[32:35]
	s_add_i32 m0, s81, 49152
	v_mfma_f32_16x16x32_bf16 v[36:39], v[184:187], v[84:87], v[36:39]
	global_load_lds_dwordx4 v240, s[78:79]
	v_mfma_f32_16x16x32_bf16 v[40:43], v[184:187], v[88:91], v[40:43]
	s_add_i32 m0, s81, 53248
	v_mfma_f32_16x16x32_bf16 v[44:47], v[184:187], v[92:95], v[44:47]
	global_load_lds_dwordx4 v241, s[78:79]
	s_waitcnt lgkmcnt(8)
	v_mfma_f32_16x16x32_bf16 v[48:51], v[188:191], v[80:83], v[48:51]
	s_add_i32 m0, s81, 57344
	v_mfma_f32_16x16x32_bf16 v[52:55], v[188:191], v[84:87], v[52:55]
	global_load_lds_dwordx4 v242, s[78:79]
	v_mfma_f32_16x16x32_bf16 v[56:59], v[188:191], v[88:91], v[56:59]
	s_add_i32 m0, s81, 61440
	v_mfma_f32_16x16x32_bf16 v[60:63], v[188:191], v[92:95], v[60:63]
	global_load_lds_dwordx4 v243, s[78:79]
	s_waitcnt lgkmcnt(6)
	v_mfma_f32_16x16x32_bf16 v[0:3], v[208:211], v[224:227], v[0:3]
	s_add_u32 s76, s76, 0x80
	s_addc_u32 s77, s77, 0
	s_waitcnt lgkmcnt(5)
	v_mfma_f32_16x16x32_bf16 v[4:7], v[208:211], v[228:231], v[4:7]
	s_waitcnt lgkmcnt(4)
	v_mfma_f32_16x16x32_bf16 v[8:11], v[208:211], v[232:235], v[8:11]
	s_add_u32 s78, s78, 0x80
	s_addc_u32 s79, s79, 0
	s_waitcnt lgkmcnt(3)
	v_mfma_f32_16x16x32_bf16 v[12:15], v[208:211], v[236:239], v[12:15]
	s_waitcnt lgkmcnt(2)
	v_mfma_f32_16x16x32_bf16 v[16:19], v[212:215], v[224:227], v[16:19]
	v_add_u32_e32 v96, 0x30000, v102
	v_mfma_f32_16x16x32_bf16 v[20:23], v[212:215], v[228:231], v[20:23]
	global_load_dwordx4 v[120:123], v96, s[86:87] offset:16 nt
	v_mfma_f32_16x16x32_bf16 v[24:27], v[212:215], v[232:235], v[24:27]
	v_mfma_f32_16x16x32_bf16 v[28:31], v[212:215], v[236:239], v[28:31]
	s_waitcnt lgkmcnt(1)
	v_mfma_f32_16x16x32_bf16 v[32:35], v[216:219], v[224:227], v[32:35]
	v_mfma_f32_16x16x32_bf16 v[36:39], v[216:219], v[228:231], v[36:39]
	v_mfma_f32_16x16x32_bf16 v[40:43], v[216:219], v[232:235], v[40:43]
	v_mfma_f32_16x16x32_bf16 v[44:47], v[216:219], v[236:239], v[44:47]
	s_waitcnt lgkmcnt(0)
	v_mfma_f32_16x16x32_bf16 v[48:51], v[220:223], v[224:227], v[48:51]
	v_mfma_f32_16x16x32_bf16 v[52:55], v[220:223], v[228:231], v[52:55]
	v_mfma_f32_16x16x32_bf16 v[56:59], v[220:223], v[232:235], v[56:59]
	v_mfma_f32_16x16x32_bf16 v[60:63], v[220:223], v[236:239], v[60:63]
	s_waitcnt vmcnt(1)
	s_barrier
	ds_read_b128 v[176:179], v244 offset:32768
	ds_read_b128 v[80:83], v246 offset:32768
	ds_read_b128 v[84:87], v246 offset:34816
	ds_read_b128 v[88:91], v246 offset:36864
	ds_read_b128 v[92:95], v246 offset:38912
	ds_read_b128 v[180:183], v244 offset:34816
	ds_read_b128 v[184:187], v244 offset:36864
	ds_read_b128 v[188:191], v244 offset:38912
	s_waitcnt lgkmcnt(6)
	v_mfma_f32_16x16x32_bf16 v[0:3], v[176:179], v[80:83], v[0:3]
	ds_read_b128 v[208:211], v245 offset:32768
	s_add_i32 m0, s81, 0
	s_waitcnt lgkmcnt(6)
	v_mfma_f32_16x16x32_bf16 v[4:7], v[176:179], v[84:87], v[4:7]
	ds_read_b128 v[224:227], v247 offset:32768
	global_load_lds_dwordx4 v240, s[76:77]
	s_waitcnt lgkmcnt(6)
	v_mfma_f32_16x16x32_bf16 v[8:11], v[176:179], v[88:91], v[8:11]
	ds_read_b128 v[228:231], v247 offset:34816
	s_add_i32 m0, s81, 4096
	s_waitcnt lgkmcnt(6)
	v_mfma_f32_16x16x32_bf16 v[12:15], v[176:179], v[92:95], v[12:15]
	ds_read_b128 v[232:235], v247 offset:36864
	global_load_lds_dwordx4 v241, s[76:77]
	s_waitcnt lgkmcnt(6)
	v_mfma_f32_16x16x32_bf16 v[16:19], v[180:183], v[80:83], v[16:19]
	ds_read_b128 v[236:239], v247 offset:38912
	s_add_i32 m0, s81, 8192
	v_mfma_f32_16x16x32_bf16 v[20:23], v[180:183], v[84:87], v[20:23]
	ds_read_b128 v[212:215], v245 offset:34816
	global_load_lds_dwordx4 v242, s[76:77]
	v_mfma_f32_16x16x32_bf16 v[24:27], v[180:183], v[88:91], v[24:27]
	ds_read_b128 v[216:219], v245 offset:36864
	s_add_i32 m0, s81, 12288
	v_mfma_f32_16x16x32_bf16 v[28:31], v[180:183], v[92:95], v[28:31]
	ds_read_b128 v[220:223], v245 offset:38912
	global_load_lds_dwordx4 v243, s[76:77]
	s_waitcnt lgkmcnt(9)
	v_mfma_f32_16x16x32_bf16 v[32:35], v[184:187], v[80:83], v[32:35]
	s_add_i32 m0, s81, 16384
	v_mfma_f32_16x16x32_bf16 v[36:39], v[184:187], v[84:87], v[36:39]
	global_load_lds_dwordx4 v240, s[78:79]
	v_mfma_f32_16x16x32_bf16 v[40:43], v[184:187], v[88:91], v[40:43]
	s_add_i32 m0, s81, 20480
	v_mfma_f32_16x16x32_bf16 v[44:47], v[184:187], v[92:95], v[44:47]
	global_load_lds_dwordx4 v241, s[78:79]
	s_waitcnt lgkmcnt(8)
	v_mfma_f32_16x16x32_bf16 v[48:51], v[188:191], v[80:83], v[48:51]
	s_add_i32 m0, s81, 24576
	v_mfma_f32_16x16x32_bf16 v[52:55], v[188:191], v[84:87], v[52:55]
	global_load_lds_dwordx4 v242, s[78:79]
	v_mfma_f32_16x16x32_bf16 v[56:59], v[188:191], v[88:91], v[56:59]
	s_add_i32 m0, s81, 28672
	v_mfma_f32_16x16x32_bf16 v[60:63], v[188:191], v[92:95], v[60:63]
	global_load_lds_dwordx4 v243, s[78:79]
	s_waitcnt lgkmcnt(6)
	v_mfma_f32_16x16x32_bf16 v[0:3], v[208:211], v[224:227], v[0:3]
	s_add_u32 s76, s76, 0x80
	s_addc_u32 s77, s77, 0
	s_waitcnt lgkmcnt(5)
	v_mfma_f32_16x16x32_bf16 v[4:7], v[208:211], v[228:231], v[4:7]
	s_waitcnt lgkmcnt(4)
	v_mfma_f32_16x16x32_bf16 v[8:11], v[208:211], v[232:235], v[8:11]
	s_add_u32 s78, s78, 0x80
	s_addc_u32 s79, s79, 0
	s_waitcnt lgkmcnt(3)
	v_mfma_f32_16x16x32_bf16 v[12:15], v[208:211], v[236:239], v[12:15]
	s_waitcnt lgkmcnt(2)
	v_mfma_f32_16x16x32_bf16 v[16:19], v[212:215], v[224:227], v[16:19]
	v_add_u32_e32 v96, 0x40000, v102
	v_mfma_f32_16x16x32_bf16 v[20:23], v[212:215], v[228:231], v[20:23]
	global_load_dwordx4 v[126:129], v96, s[86:87] nt
	v_mfma_f32_16x16x32_bf16 v[24:27], v[212:215], v[232:235], v[24:27]
	v_mfma_f32_16x16x32_bf16 v[28:31], v[212:215], v[236:239], v[28:31]
	s_waitcnt lgkmcnt(1)
	v_mfma_f32_16x16x32_bf16 v[32:35], v[216:219], v[224:227], v[32:35]
	v_mfma_f32_16x16x32_bf16 v[36:39], v[216:219], v[228:231], v[36:39]
	v_mfma_f32_16x16x32_bf16 v[40:43], v[216:219], v[232:235], v[40:43]
	v_mfma_f32_16x16x32_bf16 v[44:47], v[216:219], v[236:239], v[44:47]
	s_waitcnt lgkmcnt(0)
	v_mfma_f32_16x16x32_bf16 v[48:51], v[220:223], v[224:227], v[48:51]
	v_mfma_f32_16x16x32_bf16 v[52:55], v[220:223], v[228:231], v[52:55]
	v_mfma_f32_16x16x32_bf16 v[56:59], v[220:223], v[232:235], v[56:59]
	v_mfma_f32_16x16x32_bf16 v[60:63], v[220:223], v[236:239], v[60:63]
	s_waitcnt vmcnt(1)
	s_barrier
	ds_read_b128 v[176:179], v244 offset:0
	ds_read_b128 v[80:83], v246 offset:0
	ds_read_b128 v[84:87], v246 offset:2048
	ds_read_b128 v[88:91], v246 offset:4096
	ds_read_b128 v[92:95], v246 offset:6144
	ds_read_b128 v[180:183], v244 offset:2048
	ds_read_b128 v[184:187], v244 offset:4096
	ds_read_b128 v[188:191], v244 offset:6144
	s_waitcnt lgkmcnt(6)
	v_mfma_f32_16x16x32_bf16 v[0:3], v[176:179], v[80:83], v[0:3]
	ds_read_b128 v[208:211], v245 offset:0
	s_add_i32 m0, s81, 32768
	s_waitcnt lgkmcnt(6)
	v_mfma_f32_16x16x32_bf16 v[4:7], v[176:179], v[84:87], v[4:7]
	ds_read_b128 v[224:227], v247 offset:0
	global_load_lds_dwordx4 v240, s[76:77]
	s_waitcnt lgkmcnt(6)
	v_mfma_f32_16x16x32_bf16 v[8:11], v[176:179], v[88:91], v[8:11]
	ds_read_b128 v[228:231], v247 offset:2048
	s_add_i32 m0, s81, 36864
	s_waitcnt lgkmcnt(6)
	v_mfma_f32_16x16x32_bf16 v[12:15], v[176:179], v[92:95], v[12:15]
	ds_read_b128 v[232:235], v247 offset:4096
	global_load_lds_dwordx4 v241, s[76:77]
	s_waitcnt lgkmcnt(6)
	v_mfma_f32_16x16x32_bf16 v[16:19], v[180:183], v[80:83], v[16:19]
	ds_read_b128 v[236:239], v247 offset:6144
	s_add_i32 m0, s81, 40960
	v_mfma_f32_16x16x32_bf16 v[20:23], v[180:183], v[84:87], v[20:23]
	ds_read_b128 v[212:215], v245 offset:2048
	global_load_lds_dwordx4 v242, s[76:77]
	v_mfma_f32_16x16x32_bf16 v[24:27], v[180:183], v[88:91], v[24:27]
	ds_read_b128 v[216:219], v245 offset:4096
	s_add_i32 m0, s81, 45056
	v_mfma_f32_16x16x32_bf16 v[28:31], v[180:183], v[92:95], v[28:31]
	ds_read_b128 v[220:223], v245 offset:6144
	global_load_lds_dwordx4 v243, s[76:77]
	s_waitcnt lgkmcnt(9)
	v_mfma_f32_16x16x32_bf16 v[32:35], v[184:187], v[80:83], v[32:35]
	s_add_i32 m0, s81, 49152
	v_mfma_f32_16x16x32_bf16 v[36:39], v[184:187], v[84:87], v[36:39]
	global_load_lds_dwordx4 v240, s[78:79]
	v_mfma_f32_16x16x32_bf16 v[40:43], v[184:187], v[88:91], v[40:43]
	s_add_i32 m0, s81, 53248
	v_mfma_f32_16x16x32_bf16 v[44:47], v[184:187], v[92:95], v[44:47]
	global_load_lds_dwordx4 v241, s[78:79]
	s_waitcnt lgkmcnt(8)
	v_mfma_f32_16x16x32_bf16 v[48:51], v[188:191], v[80:83], v[48:51]
	s_add_i32 m0, s81, 57344
	v_mfma_f32_16x16x32_bf16 v[52:55], v[188:191], v[84:87], v[52:55]
	global_load_lds_dwordx4 v242, s[78:79]
	v_mfma_f32_16x16x32_bf16 v[56:59], v[188:191], v[88:91], v[56:59]
	s_add_i32 m0, s81, 61440
	v_mfma_f32_16x16x32_bf16 v[60:63], v[188:191], v[92:95], v[60:63]
	global_load_lds_dwordx4 v243, s[78:79]
	s_waitcnt lgkmcnt(6)
	v_mfma_f32_16x16x32_bf16 v[0:3], v[208:211], v[224:227], v[0:3]
	s_add_u32 s76, s76, 0x80
	s_addc_u32 s77, s77, 0
	s_waitcnt lgkmcnt(5)
	v_mfma_f32_16x16x32_bf16 v[4:7], v[208:211], v[228:231], v[4:7]
	s_waitcnt lgkmcnt(4)
	v_mfma_f32_16x16x32_bf16 v[8:11], v[208:211], v[232:235], v[8:11]
	s_add_u32 s78, s78, 0x80
	s_addc_u32 s79, s79, 0
	s_waitcnt lgkmcnt(3)
	v_mfma_f32_16x16x32_bf16 v[12:15], v[208:211], v[236:239], v[12:15]
	s_waitcnt lgkmcnt(2)
	v_mfma_f32_16x16x32_bf16 v[16:19], v[212:215], v[224:227], v[16:19]
	v_add_u32_e32 v96, 0x40000, v102
	v_mfma_f32_16x16x32_bf16 v[20:23], v[212:215], v[228:231], v[20:23]
	global_load_dwordx4 v[168:171], v96, s[86:87] offset:16 nt
	v_mfma_f32_16x16x32_bf16 v[24:27], v[212:215], v[232:235], v[24:27]
	v_mfma_f32_16x16x32_bf16 v[28:31], v[212:215], v[236:239], v[28:31]
	s_waitcnt lgkmcnt(1)
	v_mfma_f32_16x16x32_bf16 v[32:35], v[216:219], v[224:227], v[32:35]
	v_mfma_f32_16x16x32_bf16 v[36:39], v[216:219], v[228:231], v[36:39]
	v_mfma_f32_16x16x32_bf16 v[40:43], v[216:219], v[232:235], v[40:43]
	v_mfma_f32_16x16x32_bf16 v[44:47], v[216:219], v[236:239], v[44:47]
	s_waitcnt lgkmcnt(0)
	v_mfma_f32_16x16x32_bf16 v[48:51], v[220:223], v[224:227], v[48:51]
	v_mfma_f32_16x16x32_bf16 v[52:55], v[220:223], v[228:231], v[52:55]
	v_mfma_f32_16x16x32_bf16 v[56:59], v[220:223], v[232:235], v[56:59]
	v_mfma_f32_16x16x32_bf16 v[60:63], v[220:223], v[236:239], v[60:63]
	s_waitcnt vmcnt(1)
	s_barrier
	ds_read_b128 v[176:179], v244 offset:32768
	ds_read_b128 v[80:83], v246 offset:32768
	ds_read_b128 v[84:87], v246 offset:34816
	ds_read_b128 v[88:91], v246 offset:36864
	ds_read_b128 v[92:95], v246 offset:38912
	ds_read_b128 v[180:183], v244 offset:34816
	ds_read_b128 v[184:187], v244 offset:36864
	ds_read_b128 v[188:191], v244 offset:38912
	s_waitcnt lgkmcnt(6)
	v_mfma_f32_16x16x32_bf16 v[0:3], v[176:179], v[80:83], v[0:3]
	ds_read_b128 v[208:211], v245 offset:32768
	s_add_i32 m0, s81, 0
	s_waitcnt lgkmcnt(6)
	v_mfma_f32_16x16x32_bf16 v[4:7], v[176:179], v[84:87], v[4:7]
	ds_read_b128 v[224:227], v247 offset:32768
	global_load_lds_dwordx4 v240, s[76:77]
	s_waitcnt lgkmcnt(6)
	v_mfma_f32_16x16x32_bf16 v[8:11], v[176:179], v[88:91], v[8:11]
	ds_read_b128 v[228:231], v247 offset:34816
	s_add_i32 m0, s81, 4096
	s_waitcnt lgkmcnt(6)
	v_mfma_f32_16x16x32_bf16 v[12:15], v[176:179], v[92:95], v[12:15]
	ds_read_b128 v[232:235], v247 offset:36864
	global_load_lds_dwordx4 v241, s[76:77]
	s_waitcnt lgkmcnt(6)
	v_mfma_f32_16x16x32_bf16 v[16:19], v[180:183], v[80:83], v[16:19]
	ds_read_b128 v[236:239], v247 offset:38912
	s_add_i32 m0, s81, 8192
	v_mfma_f32_16x16x32_bf16 v[20:23], v[180:183], v[84:87], v[20:23]
	ds_read_b128 v[212:215], v245 offset:34816
	global_load_lds_dwordx4 v242, s[76:77]
	v_mfma_f32_16x16x32_bf16 v[24:27], v[180:183], v[88:91], v[24:27]
	ds_read_b128 v[216:219], v245 offset:36864
	s_add_i32 m0, s81, 12288
	v_mfma_f32_16x16x32_bf16 v[28:31], v[180:183], v[92:95], v[28:31]
	ds_read_b128 v[220:223], v245 offset:38912
	global_load_lds_dwordx4 v243, s[76:77]
	s_waitcnt lgkmcnt(9)
	v_mfma_f32_16x16x32_bf16 v[32:35], v[184:187], v[80:83], v[32:35]
	s_add_i32 m0, s81, 16384
	v_mfma_f32_16x16x32_bf16 v[36:39], v[184:187], v[84:87], v[36:39]
	global_load_lds_dwordx4 v240, s[78:79]
	v_mfma_f32_16x16x32_bf16 v[40:43], v[184:187], v[88:91], v[40:43]
	s_add_i32 m0, s81, 20480
	v_mfma_f32_16x16x32_bf16 v[44:47], v[184:187], v[92:95], v[44:47]
	global_load_lds_dwordx4 v241, s[78:79]
	s_waitcnt lgkmcnt(8)
	v_mfma_f32_16x16x32_bf16 v[48:51], v[188:191], v[80:83], v[48:51]
	s_add_i32 m0, s81, 24576
	v_mfma_f32_16x16x32_bf16 v[52:55], v[188:191], v[84:87], v[52:55]
	global_load_lds_dwordx4 v242, s[78:79]
	v_mfma_f32_16x16x32_bf16 v[56:59], v[188:191], v[88:91], v[56:59]
	s_add_i32 m0, s81, 28672
	v_mfma_f32_16x16x32_bf16 v[60:63], v[188:191], v[92:95], v[60:63]
	global_load_lds_dwordx4 v243, s[78:79]
	s_waitcnt lgkmcnt(6)
	v_mfma_f32_16x16x32_bf16 v[0:3], v[208:211], v[224:227], v[0:3]
	s_add_u32 s76, s76, 0x80
	s_addc_u32 s77, s77, 0
	s_waitcnt lgkmcnt(5)
	v_mfma_f32_16x16x32_bf16 v[4:7], v[208:211], v[228:231], v[4:7]
	s_waitcnt lgkmcnt(4)
	v_mfma_f32_16x16x32_bf16 v[8:11], v[208:211], v[232:235], v[8:11]
	s_add_u32 s78, s78, 0x80
	s_addc_u32 s79, s79, 0
	s_waitcnt lgkmcnt(3)
	v_mfma_f32_16x16x32_bf16 v[12:15], v[208:211], v[236:239], v[12:15]
	s_waitcnt lgkmcnt(2)
	v_mfma_f32_16x16x32_bf16 v[16:19], v[212:215], v[224:227], v[16:19]
	v_add_u32_e32 v96, 0x50000, v102
	v_mfma_f32_16x16x32_bf16 v[20:23], v[212:215], v[228:231], v[20:23]
	global_load_dwordx4 v[192:195], v96, s[86:87] nt
	v_mfma_f32_16x16x32_bf16 v[24:27], v[212:215], v[232:235], v[24:27]
	v_mfma_f32_16x16x32_bf16 v[28:31], v[212:215], v[236:239], v[28:31]
	s_waitcnt lgkmcnt(1)
	v_mfma_f32_16x16x32_bf16 v[32:35], v[216:219], v[224:227], v[32:35]
	v_mfma_f32_16x16x32_bf16 v[36:39], v[216:219], v[228:231], v[36:39]
	v_mfma_f32_16x16x32_bf16 v[40:43], v[216:219], v[232:235], v[40:43]
	v_mfma_f32_16x16x32_bf16 v[44:47], v[216:219], v[236:239], v[44:47]
	s_waitcnt lgkmcnt(0)
	v_mfma_f32_16x16x32_bf16 v[48:51], v[220:223], v[224:227], v[48:51]
	v_mfma_f32_16x16x32_bf16 v[52:55], v[220:223], v[228:231], v[52:55]
	v_mfma_f32_16x16x32_bf16 v[56:59], v[220:223], v[232:235], v[56:59]
	v_mfma_f32_16x16x32_bf16 v[60:63], v[220:223], v[236:239], v[60:63]
	s_waitcnt vmcnt(1)
	s_barrier
	ds_read_b128 v[176:179], v244 offset:0
	ds_read_b128 v[80:83], v246 offset:0
	ds_read_b128 v[84:87], v246 offset:2048
	ds_read_b128 v[88:91], v246 offset:4096
	ds_read_b128 v[92:95], v246 offset:6144
	ds_read_b128 v[180:183], v244 offset:2048
	ds_read_b128 v[184:187], v244 offset:4096
	ds_read_b128 v[188:191], v244 offset:6144
	s_waitcnt lgkmcnt(6)
	v_mfma_f32_16x16x32_bf16 v[0:3], v[176:179], v[80:83], v[0:3]
	ds_read_b128 v[208:211], v245 offset:0
	s_add_i32 m0, s81, 32768
	s_waitcnt lgkmcnt(6)
	v_mfma_f32_16x16x32_bf16 v[4:7], v[176:179], v[84:87], v[4:7]
	ds_read_b128 v[224:227], v247 offset:0
	global_load_lds_dwordx4 v240, s[76:77]
	s_waitcnt lgkmcnt(6)
	v_mfma_f32_16x16x32_bf16 v[8:11], v[176:179], v[88:91], v[8:11]
	ds_read_b128 v[228:231], v247 offset:2048
	s_add_i32 m0, s81, 36864
	s_waitcnt lgkmcnt(6)
	v_mfma_f32_16x16x32_bf16 v[12:15], v[176:179], v[92:95], v[12:15]
	ds_read_b128 v[232:235], v247 offset:4096
	global_load_lds_dwordx4 v241, s[76:77]
	s_waitcnt lgkmcnt(6)
	v_mfma_f32_16x16x32_bf16 v[16:19], v[180:183], v[80:83], v[16:19]
	ds_read_b128 v[236:239], v247 offset:6144
	s_add_i32 m0, s81, 40960
	v_mfma_f32_16x16x32_bf16 v[20:23], v[180:183], v[84:87], v[20:23]
	ds_read_b128 v[212:215], v245 offset:2048
	global_load_lds_dwordx4 v242, s[76:77]
	v_mfma_f32_16x16x32_bf16 v[24:27], v[180:183], v[88:91], v[24:27]
	ds_read_b128 v[216:219], v245 offset:4096
	s_add_i32 m0, s81, 45056
	v_mfma_f32_16x16x32_bf16 v[28:31], v[180:183], v[92:95], v[28:31]
	ds_read_b128 v[220:223], v245 offset:6144
	global_load_lds_dwordx4 v243, s[76:77]
	s_waitcnt lgkmcnt(9)
	v_mfma_f32_16x16x32_bf16 v[32:35], v[184:187], v[80:83], v[32:35]
	s_add_i32 m0, s81, 49152
	v_mfma_f32_16x16x32_bf16 v[36:39], v[184:187], v[84:87], v[36:39]
	global_load_lds_dwordx4 v240, s[78:79]
	v_mfma_f32_16x16x32_bf16 v[40:43], v[184:187], v[88:91], v[40:43]
	s_add_i32 m0, s81, 53248
	v_mfma_f32_16x16x32_bf16 v[44:47], v[184:187], v[92:95], v[44:47]
	global_load_lds_dwordx4 v241, s[78:79]
	s_waitcnt lgkmcnt(8)
	v_mfma_f32_16x16x32_bf16 v[48:51], v[188:191], v[80:83], v[48:51]
	s_add_i32 m0, s81, 57344
	v_mfma_f32_16x16x32_bf16 v[52:55], v[188:191], v[84:87], v[52:55]
	global_load_lds_dwordx4 v242, s[78:79]
	v_mfma_f32_16x16x32_bf16 v[56:59], v[188:191], v[88:91], v[56:59]
	s_add_i32 m0, s81, 61440
	v_mfma_f32_16x16x32_bf16 v[60:63], v[188:191], v[92:95], v[60:63]
	global_load_lds_dwordx4 v243, s[78:79]
	s_waitcnt lgkmcnt(6)
	v_mfma_f32_16x16x32_bf16 v[0:3], v[208:211], v[224:227], v[0:3]
	s_add_u32 s76, s76, 0x80
	s_addc_u32 s77, s77, 0
	s_waitcnt lgkmcnt(5)
	v_mfma_f32_16x16x32_bf16 v[4:7], v[208:211], v[228:231], v[4:7]
	s_waitcnt lgkmcnt(4)
	v_mfma_f32_16x16x32_bf16 v[8:11], v[208:211], v[232:235], v[8:11]
	s_add_u32 s78, s78, 0x80
	s_addc_u32 s79, s79, 0
	s_waitcnt lgkmcnt(3)
	v_mfma_f32_16x16x32_bf16 v[12:15], v[208:211], v[236:239], v[12:15]
	s_waitcnt lgkmcnt(2)
	v_mfma_f32_16x16x32_bf16 v[16:19], v[212:215], v[224:227], v[16:19]
	v_add_u32_e32 v96, 0x50000, v102
	v_mfma_f32_16x16x32_bf16 v[20:23], v[212:215], v[228:231], v[20:23]
	global_load_dwordx4 v[196:199], v96, s[86:87] offset:16 nt
	v_mfma_f32_16x16x32_bf16 v[24:27], v[212:215], v[232:235], v[24:27]
	v_mfma_f32_16x16x32_bf16 v[28:31], v[212:215], v[236:239], v[28:31]
	s_waitcnt lgkmcnt(1)
	v_mfma_f32_16x16x32_bf16 v[32:35], v[216:219], v[224:227], v[32:35]
	v_mfma_f32_16x16x32_bf16 v[36:39], v[216:219], v[228:231], v[36:39]
	v_mfma_f32_16x16x32_bf16 v[40:43], v[216:219], v[232:235], v[40:43]
	v_mfma_f32_16x16x32_bf16 v[44:47], v[216:219], v[236:239], v[44:47]
	s_waitcnt lgkmcnt(0)
	v_mfma_f32_16x16x32_bf16 v[48:51], v[220:223], v[224:227], v[48:51]
	v_mfma_f32_16x16x32_bf16 v[52:55], v[220:223], v[228:231], v[52:55]
	v_mfma_f32_16x16x32_bf16 v[56:59], v[220:223], v[232:235], v[56:59]
	v_mfma_f32_16x16x32_bf16 v[60:63], v[220:223], v[236:239], v[60:63]
	s_waitcnt vmcnt(1)
	s_barrier
	ds_read_b128 v[176:179], v244 offset:32768
	ds_read_b128 v[80:83], v246 offset:32768
	ds_read_b128 v[84:87], v246 offset:34816
	ds_read_b128 v[88:91], v246 offset:36864
	ds_read_b128 v[92:95], v246 offset:38912
	ds_read_b128 v[180:183], v244 offset:34816
	ds_read_b128 v[184:187], v244 offset:36864
	ds_read_b128 v[188:191], v244 offset:38912
	s_waitcnt lgkmcnt(6)
	v_mfma_f32_16x16x32_bf16 v[0:3], v[176:179], v[80:83], v[0:3]
	ds_read_b128 v[208:211], v245 offset:32768
	s_add_i32 m0, s81, 0
	s_waitcnt lgkmcnt(6)
	v_mfma_f32_16x16x32_bf16 v[4:7], v[176:179], v[84:87], v[4:7]
	ds_read_b128 v[224:227], v247 offset:32768
	global_load_lds_dwordx4 v240, s[76:77]
	s_waitcnt lgkmcnt(6)
	v_mfma_f32_16x16x32_bf16 v[8:11], v[176:179], v[88:91], v[8:11]
	ds_read_b128 v[228:231], v247 offset:34816
	s_add_i32 m0, s81, 4096
	s_waitcnt lgkmcnt(6)
	v_mfma_f32_16x16x32_bf16 v[12:15], v[176:179], v[92:95], v[12:15]
	ds_read_b128 v[232:235], v247 offset:36864
	global_load_lds_dwordx4 v241, s[76:77]
	s_waitcnt lgkmcnt(6)
	v_mfma_f32_16x16x32_bf16 v[16:19], v[180:183], v[80:83], v[16:19]
	ds_read_b128 v[236:239], v247 offset:38912
	s_add_i32 m0, s81, 8192
	v_mfma_f32_16x16x32_bf16 v[20:23], v[180:183], v[84:87], v[20:23]
	ds_read_b128 v[212:215], v245 offset:34816
	global_load_lds_dwordx4 v242, s[76:77]
	v_mfma_f32_16x16x32_bf16 v[24:27], v[180:183], v[88:91], v[24:27]
	ds_read_b128 v[216:219], v245 offset:36864
	s_add_i32 m0, s81, 12288
	v_mfma_f32_16x16x32_bf16 v[28:31], v[180:183], v[92:95], v[28:31]
	ds_read_b128 v[220:223], v245 offset:38912
	global_load_lds_dwordx4 v243, s[76:77]
	s_waitcnt lgkmcnt(9)
	v_mfma_f32_16x16x32_bf16 v[32:35], v[184:187], v[80:83], v[32:35]
	s_add_i32 m0, s81, 16384
	v_mfma_f32_16x16x32_bf16 v[36:39], v[184:187], v[84:87], v[36:39]
	global_load_lds_dwordx4 v240, s[78:79]
	v_mfma_f32_16x16x32_bf16 v[40:43], v[184:187], v[88:91], v[40:43]
	s_add_i32 m0, s81, 20480
	v_mfma_f32_16x16x32_bf16 v[44:47], v[184:187], v[92:95], v[44:47]
	global_load_lds_dwordx4 v241, s[78:79]
	s_waitcnt lgkmcnt(8)
	v_mfma_f32_16x16x32_bf16 v[48:51], v[188:191], v[80:83], v[48:51]
	s_add_i32 m0, s81, 24576
	v_mfma_f32_16x16x32_bf16 v[52:55], v[188:191], v[84:87], v[52:55]
	global_load_lds_dwordx4 v242, s[78:79]
	v_mfma_f32_16x16x32_bf16 v[56:59], v[188:191], v[88:91], v[56:59]
	s_add_i32 m0, s81, 28672
	v_mfma_f32_16x16x32_bf16 v[60:63], v[188:191], v[92:95], v[60:63]
	global_load_lds_dwordx4 v243, s[78:79]
	s_waitcnt lgkmcnt(6)
	v_mfma_f32_16x16x32_bf16 v[0:3], v[208:211], v[224:227], v[0:3]
	s_add_u32 s76, s76, 0x80
	s_addc_u32 s77, s77, 0
	s_waitcnt lgkmcnt(5)
	v_mfma_f32_16x16x32_bf16 v[4:7], v[208:211], v[228:231], v[4:7]
	s_waitcnt lgkmcnt(4)
	v_mfma_f32_16x16x32_bf16 v[8:11], v[208:211], v[232:235], v[8:11]
	s_add_u32 s78, s78, 0x80
	s_addc_u32 s79, s79, 0
	s_waitcnt lgkmcnt(3)
	v_mfma_f32_16x16x32_bf16 v[12:15], v[208:211], v[236:239], v[12:15]
	s_waitcnt lgkmcnt(2)
	v_mfma_f32_16x16x32_bf16 v[16:19], v[212:215], v[224:227], v[16:19]
	v_add_u32_e32 v96, 0x60000, v102
	v_mfma_f32_16x16x32_bf16 v[20:23], v[212:215], v[228:231], v[20:23]
	global_load_dwordx4 v[200:203], v96, s[86:87] nt
	v_mfma_f32_16x16x32_bf16 v[24:27], v[212:215], v[232:235], v[24:27]
	v_mfma_f32_16x16x32_bf16 v[28:31], v[212:215], v[236:239], v[28:31]
	s_waitcnt lgkmcnt(1)
	v_mfma_f32_16x16x32_bf16 v[32:35], v[216:219], v[224:227], v[32:35]
	v_mfma_f32_16x16x32_bf16 v[36:39], v[216:219], v[228:231], v[36:39]
	v_mfma_f32_16x16x32_bf16 v[40:43], v[216:219], v[232:235], v[40:43]
	v_mfma_f32_16x16x32_bf16 v[44:47], v[216:219], v[236:239], v[44:47]
	s_waitcnt lgkmcnt(0)
	v_mfma_f32_16x16x32_bf16 v[48:51], v[220:223], v[224:227], v[48:51]
	v_mfma_f32_16x16x32_bf16 v[52:55], v[220:223], v[228:231], v[52:55]
	v_mfma_f32_16x16x32_bf16 v[56:59], v[220:223], v[232:235], v[56:59]
	v_mfma_f32_16x16x32_bf16 v[60:63], v[220:223], v[236:239], v[60:63]
	s_waitcnt vmcnt(1)
	s_barrier
	ds_read_b128 v[176:179], v244 offset:0
	ds_read_b128 v[80:83], v246 offset:0
	ds_read_b128 v[84:87], v246 offset:2048
	ds_read_b128 v[88:91], v246 offset:4096
	ds_read_b128 v[92:95], v246 offset:6144
	ds_read_b128 v[180:183], v244 offset:2048
	ds_read_b128 v[184:187], v244 offset:4096
	ds_read_b128 v[188:191], v244 offset:6144
	s_waitcnt lgkmcnt(6)
	v_mfma_f32_16x16x32_bf16 v[0:3], v[176:179], v[80:83], v[0:3]
	ds_read_b128 v[208:211], v245 offset:0
	s_add_i32 m0, s81, 32768
	s_waitcnt lgkmcnt(6)
	v_mfma_f32_16x16x32_bf16 v[4:7], v[176:179], v[84:87], v[4:7]
	ds_read_b128 v[224:227], v247 offset:0
	global_load_lds_dwordx4 v240, s[76:77]
	s_waitcnt lgkmcnt(6)
	v_mfma_f32_16x16x32_bf16 v[8:11], v[176:179], v[88:91], v[8:11]
	ds_read_b128 v[228:231], v247 offset:2048
	s_add_i32 m0, s81, 36864
	s_waitcnt lgkmcnt(6)
	v_mfma_f32_16x16x32_bf16 v[12:15], v[176:179], v[92:95], v[12:15]
	ds_read_b128 v[232:235], v247 offset:4096
	global_load_lds_dwordx4 v241, s[76:77]
	s_waitcnt lgkmcnt(6)
	v_mfma_f32_16x16x32_bf16 v[16:19], v[180:183], v[80:83], v[16:19]
	ds_read_b128 v[236:239], v247 offset:6144
	s_add_i32 m0, s81, 40960
	v_mfma_f32_16x16x32_bf16 v[20:23], v[180:183], v[84:87], v[20:23]
	ds_read_b128 v[212:215], v245 offset:2048
	global_load_lds_dwordx4 v242, s[76:77]
	v_mfma_f32_16x16x32_bf16 v[24:27], v[180:183], v[88:91], v[24:27]
	ds_read_b128 v[216:219], v245 offset:4096
	s_add_i32 m0, s81, 45056
	v_mfma_f32_16x16x32_bf16 v[28:31], v[180:183], v[92:95], v[28:31]
	ds_read_b128 v[220:223], v245 offset:6144
	global_load_lds_dwordx4 v243, s[76:77]
	s_waitcnt lgkmcnt(9)
	v_mfma_f32_16x16x32_bf16 v[32:35], v[184:187], v[80:83], v[32:35]
	s_add_i32 m0, s81, 49152
	v_mfma_f32_16x16x32_bf16 v[36:39], v[184:187], v[84:87], v[36:39]
	global_load_lds_dwordx4 v240, s[78:79]
	v_mfma_f32_16x16x32_bf16 v[40:43], v[184:187], v[88:91], v[40:43]
	s_add_i32 m0, s81, 53248
	v_mfma_f32_16x16x32_bf16 v[44:47], v[184:187], v[92:95], v[44:47]
	global_load_lds_dwordx4 v241, s[78:79]
	s_waitcnt lgkmcnt(8)
	v_mfma_f32_16x16x32_bf16 v[48:51], v[188:191], v[80:83], v[48:51]
	s_add_i32 m0, s81, 57344
	v_mfma_f32_16x16x32_bf16 v[52:55], v[188:191], v[84:87], v[52:55]
	global_load_lds_dwordx4 v242, s[78:79]
	v_mfma_f32_16x16x32_bf16 v[56:59], v[188:191], v[88:91], v[56:59]
	s_add_i32 m0, s81, 61440
	v_mfma_f32_16x16x32_bf16 v[60:63], v[188:191], v[92:95], v[60:63]
	global_load_lds_dwordx4 v243, s[78:79]
	s_waitcnt lgkmcnt(6)
	v_mfma_f32_16x16x32_bf16 v[0:3], v[208:211], v[224:227], v[0:3]
	s_add_u32 s76, s76, 0x80
	s_addc_u32 s77, s77, 0
	s_waitcnt lgkmcnt(5)
	v_mfma_f32_16x16x32_bf16 v[4:7], v[208:211], v[228:231], v[4:7]
	s_waitcnt lgkmcnt(4)
	v_mfma_f32_16x16x32_bf16 v[8:11], v[208:211], v[232:235], v[8:11]
	s_add_u32 s78, s78, 0x80
	s_addc_u32 s79, s79, 0
	s_waitcnt lgkmcnt(3)
	v_mfma_f32_16x16x32_bf16 v[12:15], v[208:211], v[236:239], v[12:15]
	s_waitcnt lgkmcnt(2)
	v_mfma_f32_16x16x32_bf16 v[16:19], v[212:215], v[224:227], v[16:19]
	v_add_u32_e32 v96, 0x60000, v102
	v_mfma_f32_16x16x32_bf16 v[20:23], v[212:215], v[228:231], v[20:23]
	global_load_dwordx4 v[250:253], v96, s[86:87] offset:16 nt
	v_mfma_f32_16x16x32_bf16 v[24:27], v[212:215], v[232:235], v[24:27]
	v_mfma_f32_16x16x32_bf16 v[28:31], v[212:215], v[236:239], v[28:31]
	s_waitcnt lgkmcnt(1)
	v_mfma_f32_16x16x32_bf16 v[32:35], v[216:219], v[224:227], v[32:35]
	v_mfma_f32_16x16x32_bf16 v[36:39], v[216:219], v[228:231], v[36:39]
	v_mfma_f32_16x16x32_bf16 v[40:43], v[216:219], v[232:235], v[40:43]
	v_mfma_f32_16x16x32_bf16 v[44:47], v[216:219], v[236:239], v[44:47]
	s_waitcnt lgkmcnt(0)
	v_mfma_f32_16x16x32_bf16 v[48:51], v[220:223], v[224:227], v[48:51]
	v_mfma_f32_16x16x32_bf16 v[52:55], v[220:223], v[228:231], v[52:55]
	v_mfma_f32_16x16x32_bf16 v[56:59], v[220:223], v[232:235], v[56:59]
	v_mfma_f32_16x16x32_bf16 v[60:63], v[220:223], v[236:239], v[60:63]
	s_waitcnt vmcnt(1)
	s_barrier
	ds_read_b128 v[176:179], v244 offset:32768
	ds_read_b128 v[80:83], v246 offset:32768
	ds_read_b128 v[84:87], v246 offset:34816
	ds_read_b128 v[88:91], v246 offset:36864
	ds_read_b128 v[92:95], v246 offset:38912
	ds_read_b128 v[180:183], v244 offset:34816
	ds_read_b128 v[184:187], v244 offset:36864
	ds_read_b128 v[188:191], v244 offset:38912
	s_waitcnt lgkmcnt(6)
	v_mfma_f32_16x16x32_bf16 v[0:3], v[176:179], v[80:83], v[0:3]
	ds_read_b128 v[208:211], v245 offset:32768
	s_waitcnt lgkmcnt(6)
	v_mfma_f32_16x16x32_bf16 v[4:7], v[176:179], v[84:87], v[4:7]
	ds_read_b128 v[224:227], v247 offset:32768
	s_waitcnt lgkmcnt(6)
	v_mfma_f32_16x16x32_bf16 v[8:11], v[176:179], v[88:91], v[8:11]
	ds_read_b128 v[228:231], v247 offset:34816
	s_waitcnt lgkmcnt(6)
	v_mfma_f32_16x16x32_bf16 v[12:15], v[176:179], v[92:95], v[12:15]
	ds_read_b128 v[232:235], v247 offset:36864
	s_waitcnt lgkmcnt(6)
	v_mfma_f32_16x16x32_bf16 v[16:19], v[180:183], v[80:83], v[16:19]
	ds_read_b128 v[236:239], v247 offset:38912
	v_mfma_f32_16x16x32_bf16 v[20:23], v[180:183], v[84:87], v[20:23]
	ds_read_b128 v[212:215], v245 offset:34816
	v_mfma_f32_16x16x32_bf16 v[24:27], v[180:183], v[88:91], v[24:27]
	ds_read_b128 v[216:219], v245 offset:36864
	v_mfma_f32_16x16x32_bf16 v[28:31], v[180:183], v[92:95], v[28:31]
	ds_read_b128 v[220:223], v245 offset:38912
	s_waitcnt lgkmcnt(9)
	v_mfma_f32_16x16x32_bf16 v[32:35], v[184:187], v[80:83], v[32:35]
	v_mfma_f32_16x16x32_bf16 v[36:39], v[184:187], v[84:87], v[36:39]
	v_mfma_f32_16x16x32_bf16 v[40:43], v[184:187], v[88:91], v[40:43]
	v_mfma_f32_16x16x32_bf16 v[44:47], v[184:187], v[92:95], v[44:47]
	s_waitcnt lgkmcnt(8)
	v_mfma_f32_16x16x32_bf16 v[48:51], v[188:191], v[80:83], v[48:51]
	v_mfma_f32_16x16x32_bf16 v[52:55], v[188:191], v[84:87], v[52:55]
	v_mfma_f32_16x16x32_bf16 v[56:59], v[188:191], v[88:91], v[56:59]
	v_mfma_f32_16x16x32_bf16 v[60:63], v[188:191], v[92:95], v[60:63]
	s_waitcnt lgkmcnt(6)
	v_mfma_f32_16x16x32_bf16 v[0:3], v[208:211], v[224:227], v[0:3]
	s_waitcnt lgkmcnt(5)
	v_mfma_f32_16x16x32_bf16 v[4:7], v[208:211], v[228:231], v[4:7]
	s_waitcnt lgkmcnt(4)
	v_mfma_f32_16x16x32_bf16 v[8:11], v[208:211], v[232:235], v[8:11]
	s_waitcnt lgkmcnt(3)
	v_mfma_f32_16x16x32_bf16 v[12:15], v[208:211], v[236:239], v[12:15]
	s_waitcnt lgkmcnt(2)
	v_mfma_f32_16x16x32_bf16 v[16:19], v[212:215], v[224:227], v[16:19]
	v_mfma_f32_16x16x32_bf16 v[20:23], v[212:215], v[228:231], v[20:23]
	v_mfma_f32_16x16x32_bf16 v[24:27], v[212:215], v[232:235], v[24:27]
	v_mfma_f32_16x16x32_bf16 v[28:31], v[212:215], v[236:239], v[28:31]
	s_waitcnt lgkmcnt(1)
	v_mfma_f32_16x16x32_bf16 v[32:35], v[216:219], v[224:227], v[32:35]
	v_mfma_f32_16x16x32_bf16 v[36:39], v[216:219], v[228:231], v[36:39]
	v_mfma_f32_16x16x32_bf16 v[40:43], v[216:219], v[232:235], v[40:43]
	v_mfma_f32_16x16x32_bf16 v[44:47], v[216:219], v[236:239], v[44:47]
	s_waitcnt lgkmcnt(0)
	v_mfma_f32_16x16x32_bf16 v[48:51], v[220:223], v[224:227], v[48:51]
	v_mfma_f32_16x16x32_bf16 v[52:55], v[220:223], v[228:231], v[52:55]
	v_mfma_f32_16x16x32_bf16 v[56:59], v[220:223], v[232:235], v[56:59]
	v_mfma_f32_16x16x32_bf16 v[60:63], v[220:223], v[236:239], v[60:63]
	s_branch .Lot_stage
.Lot_main_l1:
	s_waitcnt vmcnt(0)
	s_barrier
	ds_read_b128 v[176:179], v244 offset:0
	ds_read_b128 v[80:83], v246 offset:0
	ds_read_b128 v[84:87], v246 offset:2048
	ds_read_b128 v[88:91], v246 offset:4096
	ds_read_b128 v[92:95], v246 offset:6144
	ds_read_b128 v[180:183], v244 offset:2048
	ds_read_b128 v[184:187], v244 offset:4096
	ds_read_b128 v[188:191], v244 offset:6144
	s_waitcnt lgkmcnt(6)
	v_mfma_f32_16x16x32_bf16 v[0:3], v[176:179], v[80:83], 0
	ds_read_b128 v[208:211], v245 offset:0
	s_add_i32 m0, s81, 32768
	s_waitcnt lgkmcnt(6)
	v_mfma_f32_16x16x32_bf16 v[4:7], v[176:179], v[84:87], 0
	ds_read_b128 v[224:227], v247 offset:0
	global_load_lds_dwordx4 v240, s[76:77]
	s_waitcnt lgkmcnt(6)
	v_mfma_f32_16x16x32_bf16 v[8:11], v[176:179], v[88:91], 0
	ds_read_b128 v[228:231], v247 offset:2048
	s_add_i32 m0, s81, 36864
	s_waitcnt lgkmcnt(6)
	v_mfma_f32_16x16x32_bf16 v[12:15], v[176:179], v[92:95], 0
	ds_read_b128 v[232:235], v247 offset:4096
	global_load_lds_dwordx4 v241, s[76:77]
	s_waitcnt lgkmcnt(6)
	v_mfma_f32_16x16x32_bf16 v[16:19], v[180:183], v[80:83], 0
	ds_read_b128 v[236:239], v247 offset:6144
	s_add_i32 m0, s81, 40960
	v_mfma_f32_16x16x32_bf16 v[20:23], v[180:183], v[84:87], 0
	ds_read_b128 v[212:215], v245 offset:2048
	global_load_lds_dwordx4 v242, s[76:77]
	v_mfma_f32_16x16x32_bf16 v[24:27], v[180:183], v[88:91], 0
	ds_read_b128 v[216:219], v245 offset:4096
	s_add_i32 m0, s81, 45056
	v_mfma_f32_16x16x32_bf16 v[28:31], v[180:183], v[92:95], 0
	ds_read_b128 v[220:223], v245 offset:6144
	global_load_lds_dwordx4 v243, s[76:77]
	s_waitcnt lgkmcnt(9)
	v_mfma_f32_16x16x32_bf16 v[32:35], v[184:187], v[80:83], 0
	s_add_i32 m0, s81, 49152
	v_mfma_f32_16x16x32_bf16 v[36:39], v[184:187], v[84:87], 0
	global_load_lds_dwordx4 v240, s[78:79]
	v_mfma_f32_16x16x32_bf16 v[40:43], v[184:187], v[88:91], 0
	s_add_i32 m0, s81, 53248
	v_mfma_f32_16x16x32_bf16 v[44:47], v[184:187], v[92:95], 0
	global_load_lds_dwordx4 v241, s[78:79]
	s_waitcnt lgkmcnt(8)
	v_mfma_f32_16x16x32_bf16 v[48:51], v[188:191], v[80:83], 0
	s_add_i32 m0, s81, 57344
	v_mfma_f32_16x16x32_bf16 v[52:55], v[188:191], v[84:87], 0
	global_load_lds_dwordx4 v242, s[78:79]
	v_mfma_f32_16x16x32_bf16 v[56:59], v[188:191], v[88:91], 0
	s_add_i32 m0, s81, 61440
	v_mfma_f32_16x16x32_bf16 v[60:63], v[188:191], v[92:95], 0
	global_load_lds_dwordx4 v243, s[78:79]
	s_waitcnt lgkmcnt(6)
	v_mfma_f32_16x16x32_bf16 v[0:3], v[208:211], v[224:227], v[0:3]
	s_add_u32 s76, s76, 0x80
	s_addc_u32 s77, s77, 0
	s_waitcnt lgkmcnt(5)
	v_mfma_f32_16x16x32_bf16 v[4:7], v[208:211], v[228:231], v[4:7]
	s_waitcnt lgkmcnt(4)
	v_mfma_f32_16x16x32_bf16 v[8:11], v[208:211], v[232:235], v[8:11]
	s_add_u32 s78, s78, 0x80
	s_addc_u32 s79, s79, 0
	s_waitcnt lgkmcnt(3)
	v_mfma_f32_16x16x32_bf16 v[12:15], v[208:211], v[236:239], v[12:15]
	s_waitcnt lgkmcnt(2)
	v_mfma_f32_16x16x32_bf16 v[16:19], v[212:215], v[224:227], v[16:19]
	v_mfma_f32_16x16x32_bf16 v[20:23], v[212:215], v[228:231], v[20:23]
	v_mfma_f32_16x16x32_bf16 v[24:27], v[212:215], v[232:235], v[24:27]
	v_mfma_f32_16x16x32_bf16 v[28:31], v[212:215], v[236:239], v[28:31]
	s_waitcnt lgkmcnt(1)
	v_mfma_f32_16x16x32_bf16 v[32:35], v[216:219], v[224:227], v[32:35]
	v_mfma_f32_16x16x32_bf16 v[36:39], v[216:219], v[228:231], v[36:39]
	v_mfma_f32_16x16x32_bf16 v[40:43], v[216:219], v[232:235], v[40:43]
	v_mfma_f32_16x16x32_bf16 v[44:47], v[216:219], v[236:239], v[44:47]
	s_waitcnt lgkmcnt(0)
	v_mfma_f32_16x16x32_bf16 v[48:51], v[220:223], v[224:227], v[48:51]
	v_mfma_f32_16x16x32_bf16 v[52:55], v[220:223], v[228:231], v[52:55]
	v_mfma_f32_16x16x32_bf16 v[56:59], v[220:223], v[232:235], v[56:59]
	v_mfma_f32_16x16x32_bf16 v[60:63], v[220:223], v[236:239], v[60:63]
	s_waitcnt vmcnt(0)
	s_barrier
	ds_read_b128 v[176:179], v244 offset:32768
	ds_read_b128 v[80:83], v246 offset:32768
	ds_read_b128 v[84:87], v246 offset:34816
	ds_read_b128 v[88:91], v246 offset:36864
	ds_read_b128 v[92:95], v246 offset:38912
	ds_read_b128 v[180:183], v244 offset:34816
	ds_read_b128 v[184:187], v244 offset:36864
	ds_read_b128 v[188:191], v244 offset:38912
	s_waitcnt lgkmcnt(6)
	v_mfma_f32_16x16x32_bf16 v[0:3], v[176:179], v[80:83], v[0:3]
	ds_read_b128 v[208:211], v245 offset:32768
	s_add_i32 m0, s81, 0
	s_waitcnt lgkmcnt(6)
	v_mfma_f32_16x16x32_bf16 v[4:7], v[176:179], v[84:87], v[4:7]
	ds_read_b128 v[224:227], v247 offset:32768
	global_load_lds_dwordx4 v240, s[76:77]
	s_waitcnt lgkmcnt(6)
	v_mfma_f32_16x16x32_bf16 v[8:11], v[176:179], v[88:91], v[8:11]
	ds_read_b128 v[228:231], v247 offset:34816
	s_add_i32 m0, s81, 4096
	s_waitcnt lgkmcnt(6)
	v_mfma_f32_16x16x32_bf16 v[12:15], v[176:179], v[92:95], v[12:15]
	ds_read_b128 v[232:235], v247 offset:36864
	global_load_lds_dwordx4 v241, s[76:77]
	s_waitcnt lgkmcnt(6)
	v_mfma_f32_16x16x32_bf16 v[16:19], v[180:183], v[80:83], v[16:19]
	ds_read_b128 v[236:239], v247 offset:38912
	s_add_i32 m0, s81, 8192
	v_mfma_f32_16x16x32_bf16 v[20:23], v[180:183], v[84:87], v[20:23]
	ds_read_b128 v[212:215], v245 offset:34816
	global_load_lds_dwordx4 v242, s[76:77]
	v_mfma_f32_16x16x32_bf16 v[24:27], v[180:183], v[88:91], v[24:27]
	ds_read_b128 v[216:219], v245 offset:36864
	s_add_i32 m0, s81, 12288
	v_mfma_f32_16x16x32_bf16 v[28:31], v[180:183], v[92:95], v[28:31]
	ds_read_b128 v[220:223], v245 offset:38912
	global_load_lds_dwordx4 v243, s[76:77]
	s_waitcnt lgkmcnt(9)
	v_mfma_f32_16x16x32_bf16 v[32:35], v[184:187], v[80:83], v[32:35]
	s_add_i32 m0, s81, 16384
	v_mfma_f32_16x16x32_bf16 v[36:39], v[184:187], v[84:87], v[36:39]
	global_load_lds_dwordx4 v240, s[78:79]
	v_mfma_f32_16x16x32_bf16 v[40:43], v[184:187], v[88:91], v[40:43]
	s_add_i32 m0, s81, 20480
	v_mfma_f32_16x16x32_bf16 v[44:47], v[184:187], v[92:95], v[44:47]
	global_load_lds_dwordx4 v241, s[78:79]
	s_waitcnt lgkmcnt(8)
	v_mfma_f32_16x16x32_bf16 v[48:51], v[188:191], v[80:83], v[48:51]
	s_add_i32 m0, s81, 24576
	v_mfma_f32_16x16x32_bf16 v[52:55], v[188:191], v[84:87], v[52:55]
	global_load_lds_dwordx4 v242, s[78:79]
	v_mfma_f32_16x16x32_bf16 v[56:59], v[188:191], v[88:91], v[56:59]
	s_add_i32 m0, s81, 28672
	v_mfma_f32_16x16x32_bf16 v[60:63], v[188:191], v[92:95], v[60:63]
	global_load_lds_dwordx4 v243, s[78:79]
	s_waitcnt lgkmcnt(6)
	v_mfma_f32_16x16x32_bf16 v[0:3], v[208:211], v[224:227], v[0:3]
	s_add_u32 s76, s76, 0x80
	s_addc_u32 s77, s77, 0
	s_waitcnt lgkmcnt(5)
	v_mfma_f32_16x16x32_bf16 v[4:7], v[208:211], v[228:231], v[4:7]
	s_waitcnt lgkmcnt(4)
	v_mfma_f32_16x16x32_bf16 v[8:11], v[208:211], v[232:235], v[8:11]
	s_add_u32 s78, s78, 0x80
	s_addc_u32 s79, s79, 0
	s_waitcnt lgkmcnt(3)
	v_mfma_f32_16x16x32_bf16 v[12:15], v[208:211], v[236:239], v[12:15]
	s_waitcnt lgkmcnt(2)
	v_mfma_f32_16x16x32_bf16 v[16:19], v[212:215], v[224:227], v[16:19]
	v_mfma_f32_16x16x32_bf16 v[20:23], v[212:215], v[228:231], v[20:23]
	v_mfma_f32_16x16x32_bf16 v[24:27], v[212:215], v[232:235], v[24:27]
	v_mfma_f32_16x16x32_bf16 v[28:31], v[212:215], v[236:239], v[28:31]
	s_waitcnt lgkmcnt(1)
	v_mfma_f32_16x16x32_bf16 v[32:35], v[216:219], v[224:227], v[32:35]
	v_mfma_f32_16x16x32_bf16 v[36:39], v[216:219], v[228:231], v[36:39]
	v_mfma_f32_16x16x32_bf16 v[40:43], v[216:219], v[232:235], v[40:43]
	v_mfma_f32_16x16x32_bf16 v[44:47], v[216:219], v[236:239], v[44:47]
	s_waitcnt lgkmcnt(0)
	v_mfma_f32_16x16x32_bf16 v[48:51], v[220:223], v[224:227], v[48:51]
	v_mfma_f32_16x16x32_bf16 v[52:55], v[220:223], v[228:231], v[52:55]
	v_mfma_f32_16x16x32_bf16 v[56:59], v[220:223], v[232:235], v[56:59]
	v_mfma_f32_16x16x32_bf16 v[60:63], v[220:223], v[236:239], v[60:63]
	s_waitcnt vmcnt(0)
	s_barrier
	ds_read_b128 v[176:179], v244 offset:0
	ds_read_b128 v[80:83], v246 offset:0
	ds_read_b128 v[84:87], v246 offset:2048
	ds_read_b128 v[88:91], v246 offset:4096
	ds_read_b128 v[92:95], v246 offset:6144
	ds_read_b128 v[180:183], v244 offset:2048
	ds_read_b128 v[184:187], v244 offset:4096
	ds_read_b128 v[188:191], v244 offset:6144
	s_waitcnt lgkmcnt(6)
	v_mfma_f32_16x16x32_bf16 v[0:3], v[176:179], v[80:83], v[0:3]
	ds_read_b128 v[208:211], v245 offset:0
	s_add_i32 m0, s81, 32768
	s_waitcnt lgkmcnt(6)
	v_mfma_f32_16x16x32_bf16 v[4:7], v[176:179], v[84:87], v[4:7]
	ds_read_b128 v[224:227], v247 offset:0
	global_load_lds_dwordx4 v240, s[76:77]
	s_waitcnt lgkmcnt(6)
	v_mfma_f32_16x16x32_bf16 v[8:11], v[176:179], v[88:91], v[8:11]
	ds_read_b128 v[228:231], v247 offset:2048
	s_add_i32 m0, s81, 36864
	s_waitcnt lgkmcnt(6)
	v_mfma_f32_16x16x32_bf16 v[12:15], v[176:179], v[92:95], v[12:15]
	ds_read_b128 v[232:235], v247 offset:4096
	global_load_lds_dwordx4 v241, s[76:77]
	s_waitcnt lgkmcnt(6)
	v_mfma_f32_16x16x32_bf16 v[16:19], v[180:183], v[80:83], v[16:19]
	ds_read_b128 v[236:239], v247 offset:6144
	s_add_i32 m0, s81, 40960
	v_mfma_f32_16x16x32_bf16 v[20:23], v[180:183], v[84:87], v[20:23]
	ds_read_b128 v[212:215], v245 offset:2048
	global_load_lds_dwordx4 v242, s[76:77]
	v_mfma_f32_16x16x32_bf16 v[24:27], v[180:183], v[88:91], v[24:27]
	ds_read_b128 v[216:219], v245 offset:4096
	s_add_i32 m0, s81, 45056
	v_mfma_f32_16x16x32_bf16 v[28:31], v[180:183], v[92:95], v[28:31]
	ds_read_b128 v[220:223], v245 offset:6144
	global_load_lds_dwordx4 v243, s[76:77]
	s_waitcnt lgkmcnt(9)
	v_mfma_f32_16x16x32_bf16 v[32:35], v[184:187], v[80:83], v[32:35]
	s_add_i32 m0, s81, 49152
	v_mfma_f32_16x16x32_bf16 v[36:39], v[184:187], v[84:87], v[36:39]
	global_load_lds_dwordx4 v240, s[78:79]
	v_mfma_f32_16x16x32_bf16 v[40:43], v[184:187], v[88:91], v[40:43]
	s_add_i32 m0, s81, 53248
	v_mfma_f32_16x16x32_bf16 v[44:47], v[184:187], v[92:95], v[44:47]
	global_load_lds_dwordx4 v241, s[78:79]
	s_waitcnt lgkmcnt(8)
	v_mfma_f32_16x16x32_bf16 v[48:51], v[188:191], v[80:83], v[48:51]
	s_add_i32 m0, s81, 57344
	v_mfma_f32_16x16x32_bf16 v[52:55], v[188:191], v[84:87], v[52:55]
	global_load_lds_dwordx4 v242, s[78:79]
	v_mfma_f32_16x16x32_bf16 v[56:59], v[188:191], v[88:91], v[56:59]
	s_add_i32 m0, s81, 61440
	v_mfma_f32_16x16x32_bf16 v[60:63], v[188:191], v[92:95], v[60:63]
	global_load_lds_dwordx4 v243, s[78:79]
	s_waitcnt lgkmcnt(6)
	v_mfma_f32_16x16x32_bf16 v[0:3], v[208:211], v[224:227], v[0:3]
	s_add_u32 s76, s76, 0x80
	s_addc_u32 s77, s77, 0
	s_waitcnt lgkmcnt(5)
	v_mfma_f32_16x16x32_bf16 v[4:7], v[208:211], v[228:231], v[4:7]
	s_waitcnt lgkmcnt(4)
	v_mfma_f32_16x16x32_bf16 v[8:11], v[208:211], v[232:235], v[8:11]
	s_add_u32 s78, s78, 0x80
	s_addc_u32 s79, s79, 0
	s_waitcnt lgkmcnt(3)
	v_mfma_f32_16x16x32_bf16 v[12:15], v[208:211], v[236:239], v[12:15]
	s_waitcnt lgkmcnt(2)
	v_mfma_f32_16x16x32_bf16 v[16:19], v[212:215], v[224:227], v[16:19]
	v_mfma_f32_16x16x32_bf16 v[20:23], v[212:215], v[228:231], v[20:23]
	v_mfma_f32_16x16x32_bf16 v[24:27], v[212:215], v[232:235], v[24:27]
	v_mfma_f32_16x16x32_bf16 v[28:31], v[212:215], v[236:239], v[28:31]
	s_waitcnt lgkmcnt(1)
	v_mfma_f32_16x16x32_bf16 v[32:35], v[216:219], v[224:227], v[32:35]
	v_mfma_f32_16x16x32_bf16 v[36:39], v[216:219], v[228:231], v[36:39]
	v_mfma_f32_16x16x32_bf16 v[40:43], v[216:219], v[232:235], v[40:43]
	v_mfma_f32_16x16x32_bf16 v[44:47], v[216:219], v[236:239], v[44:47]
	s_waitcnt lgkmcnt(0)
	v_mfma_f32_16x16x32_bf16 v[48:51], v[220:223], v[224:227], v[48:51]
	v_mfma_f32_16x16x32_bf16 v[52:55], v[220:223], v[228:231], v[52:55]
	v_mfma_f32_16x16x32_bf16 v[56:59], v[220:223], v[232:235], v[56:59]
	v_mfma_f32_16x16x32_bf16 v[60:63], v[220:223], v[236:239], v[60:63]
	s_waitcnt vmcnt(0)
	s_barrier
	ds_read_b128 v[176:179], v244 offset:32768
	ds_read_b128 v[80:83], v246 offset:32768
	ds_read_b128 v[84:87], v246 offset:34816
	ds_read_b128 v[88:91], v246 offset:36864
	ds_read_b128 v[92:95], v246 offset:38912
	ds_read_b128 v[180:183], v244 offset:34816
	ds_read_b128 v[184:187], v244 offset:36864
	ds_read_b128 v[188:191], v244 offset:38912
	s_waitcnt lgkmcnt(6)
	v_mfma_f32_16x16x32_bf16 v[0:3], v[176:179], v[80:83], v[0:3]
	ds_read_b128 v[208:211], v245 offset:32768
	s_add_i32 m0, s81, 0
	s_waitcnt lgkmcnt(6)
	v_mfma_f32_16x16x32_bf16 v[4:7], v[176:179], v[84:87], v[4:7]
	ds_read_b128 v[224:227], v247 offset:32768
	global_load_lds_dwordx4 v240, s[76:77]
	s_waitcnt lgkmcnt(6)
	v_mfma_f32_16x16x32_bf16 v[8:11], v[176:179], v[88:91], v[8:11]
	ds_read_b128 v[228:231], v247 offset:34816
	s_add_i32 m0, s81, 4096
	s_waitcnt lgkmcnt(6)
	v_mfma_f32_16x16x32_bf16 v[12:15], v[176:179], v[92:95], v[12:15]
	ds_read_b128 v[232:235], v247 offset:36864
	global_load_lds_dwordx4 v241, s[76:77]
	s_waitcnt lgkmcnt(6)
	v_mfma_f32_16x16x32_bf16 v[16:19], v[180:183], v[80:83], v[16:19]
	ds_read_b128 v[236:239], v247 offset:38912
	s_add_i32 m0, s81, 8192
	v_mfma_f32_16x16x32_bf16 v[20:23], v[180:183], v[84:87], v[20:23]
	ds_read_b128 v[212:215], v245 offset:34816
	global_load_lds_dwordx4 v242, s[76:77]
	v_mfma_f32_16x16x32_bf16 v[24:27], v[180:183], v[88:91], v[24:27]
	ds_read_b128 v[216:219], v245 offset:36864
	s_add_i32 m0, s81, 12288
	v_mfma_f32_16x16x32_bf16 v[28:31], v[180:183], v[92:95], v[28:31]
	ds_read_b128 v[220:223], v245 offset:38912
	global_load_lds_dwordx4 v243, s[76:77]
	s_waitcnt lgkmcnt(9)
	v_mfma_f32_16x16x32_bf16 v[32:35], v[184:187], v[80:83], v[32:35]
	s_add_i32 m0, s81, 16384
	v_mfma_f32_16x16x32_bf16 v[36:39], v[184:187], v[84:87], v[36:39]
	global_load_lds_dwordx4 v240, s[78:79]
	v_mfma_f32_16x16x32_bf16 v[40:43], v[184:187], v[88:91], v[40:43]
	s_add_i32 m0, s81, 20480
	v_mfma_f32_16x16x32_bf16 v[44:47], v[184:187], v[92:95], v[44:47]
	global_load_lds_dwordx4 v241, s[78:79]
	s_waitcnt lgkmcnt(8)
	v_mfma_f32_16x16x32_bf16 v[48:51], v[188:191], v[80:83], v[48:51]
	s_add_i32 m0, s81, 24576
	v_mfma_f32_16x16x32_bf16 v[52:55], v[188:191], v[84:87], v[52:55]
	global_load_lds_dwordx4 v242, s[78:79]
	v_mfma_f32_16x16x32_bf16 v[56:59], v[188:191], v[88:91], v[56:59]
	s_add_i32 m0, s81, 28672
	v_mfma_f32_16x16x32_bf16 v[60:63], v[188:191], v[92:95], v[60:63]
	global_load_lds_dwordx4 v243, s[78:79]
	s_waitcnt lgkmcnt(6)
	v_mfma_f32_16x16x32_bf16 v[0:3], v[208:211], v[224:227], v[0:3]
	s_add_u32 s76, s76, 0x80
	s_addc_u32 s77, s77, 0
	s_waitcnt lgkmcnt(5)
	v_mfma_f32_16x16x32_bf16 v[4:7], v[208:211], v[228:231], v[4:7]
	s_waitcnt lgkmcnt(4)
	v_mfma_f32_16x16x32_bf16 v[8:11], v[208:211], v[232:235], v[8:11]
	s_add_u32 s78, s78, 0x80
	s_addc_u32 s79, s79, 0
	s_waitcnt lgkmcnt(3)
	v_mfma_f32_16x16x32_bf16 v[12:15], v[208:211], v[236:239], v[12:15]
	s_waitcnt lgkmcnt(2)
	v_mfma_f32_16x16x32_bf16 v[16:19], v[212:215], v[224:227], v[16:19]
	v_mfma_f32_16x16x32_bf16 v[20:23], v[212:215], v[228:231], v[20:23]
	v_mfma_f32_16x16x32_bf16 v[24:27], v[212:215], v[232:235], v[24:27]
	v_mfma_f32_16x16x32_bf16 v[28:31], v[212:215], v[236:239], v[28:31]
	s_waitcnt lgkmcnt(1)
	v_mfma_f32_16x16x32_bf16 v[32:35], v[216:219], v[224:227], v[32:35]
	v_mfma_f32_16x16x32_bf16 v[36:39], v[216:219], v[228:231], v[36:39]
	v_mfma_f32_16x16x32_bf16 v[40:43], v[216:219], v[232:235], v[40:43]
	v_mfma_f32_16x16x32_bf16 v[44:47], v[216:219], v[236:239], v[44:47]
	s_waitcnt lgkmcnt(0)
	v_mfma_f32_16x16x32_bf16 v[48:51], v[220:223], v[224:227], v[48:51]
	v_mfma_f32_16x16x32_bf16 v[52:55], v[220:223], v[228:231], v[52:55]
	v_mfma_f32_16x16x32_bf16 v[56:59], v[220:223], v[232:235], v[56:59]
	v_mfma_f32_16x16x32_bf16 v[60:63], v[220:223], v[236:239], v[60:63]
	s_waitcnt vmcnt(0)
	s_barrier
	ds_read_b128 v[176:179], v244 offset:0
	ds_read_b128 v[80:83], v246 offset:0
	ds_read_b128 v[84:87], v246 offset:2048
	ds_read_b128 v[88:91], v246 offset:4096
	ds_read_b128 v[92:95], v246 offset:6144
	ds_read_b128 v[180:183], v244 offset:2048
	ds_read_b128 v[184:187], v244 offset:4096
	ds_read_b128 v[188:191], v244 offset:6144
	s_waitcnt lgkmcnt(6)
	v_mfma_f32_16x16x32_bf16 v[0:3], v[176:179], v[80:83], v[0:3]
	ds_read_b128 v[208:211], v245 offset:0
	s_add_i32 m0, s81, 32768
	s_waitcnt lgkmcnt(6)
	v_mfma_f32_16x16x32_bf16 v[4:7], v[176:179], v[84:87], v[4:7]
	ds_read_b128 v[224:227], v247 offset:0
	global_load_lds_dwordx4 v240, s[76:77]
	s_waitcnt lgkmcnt(6)
	v_mfma_f32_16x16x32_bf16 v[8:11], v[176:179], v[88:91], v[8:11]
	ds_read_b128 v[228:231], v247 offset:2048
	s_add_i32 m0, s81, 36864
	s_waitcnt lgkmcnt(6)
	v_mfma_f32_16x16x32_bf16 v[12:15], v[176:179], v[92:95], v[12:15]
	ds_read_b128 v[232:235], v247 offset:4096
	global_load_lds_dwordx4 v241, s[76:77]
	s_waitcnt lgkmcnt(6)
	v_mfma_f32_16x16x32_bf16 v[16:19], v[180:183], v[80:83], v[16:19]
	ds_read_b128 v[236:239], v247 offset:6144
	s_add_i32 m0, s81, 40960
	v_mfma_f32_16x16x32_bf16 v[20:23], v[180:183], v[84:87], v[20:23]
	ds_read_b128 v[212:215], v245 offset:2048
	global_load_lds_dwordx4 v242, s[76:77]
	v_mfma_f32_16x16x32_bf16 v[24:27], v[180:183], v[88:91], v[24:27]
	ds_read_b128 v[216:219], v245 offset:4096
	s_add_i32 m0, s81, 45056
	v_mfma_f32_16x16x32_bf16 v[28:31], v[180:183], v[92:95], v[28:31]
	ds_read_b128 v[220:223], v245 offset:6144
	global_load_lds_dwordx4 v243, s[76:77]
	s_waitcnt lgkmcnt(9)
	v_mfma_f32_16x16x32_bf16 v[32:35], v[184:187], v[80:83], v[32:35]
	s_add_i32 m0, s81, 49152
	v_mfma_f32_16x16x32_bf16 v[36:39], v[184:187], v[84:87], v[36:39]
	global_load_lds_dwordx4 v240, s[78:79]
	v_mfma_f32_16x16x32_bf16 v[40:43], v[184:187], v[88:91], v[40:43]
	s_add_i32 m0, s81, 53248
	v_mfma_f32_16x16x32_bf16 v[44:47], v[184:187], v[92:95], v[44:47]
	global_load_lds_dwordx4 v241, s[78:79]
	s_waitcnt lgkmcnt(8)
	v_mfma_f32_16x16x32_bf16 v[48:51], v[188:191], v[80:83], v[48:51]
	s_add_i32 m0, s81, 57344
	v_mfma_f32_16x16x32_bf16 v[52:55], v[188:191], v[84:87], v[52:55]
	global_load_lds_dwordx4 v242, s[78:79]
	v_mfma_f32_16x16x32_bf16 v[56:59], v[188:191], v[88:91], v[56:59]
	s_add_i32 m0, s81, 61440
	v_mfma_f32_16x16x32_bf16 v[60:63], v[188:191], v[92:95], v[60:63]
	global_load_lds_dwordx4 v243, s[78:79]
	s_waitcnt lgkmcnt(6)
	v_mfma_f32_16x16x32_bf16 v[0:3], v[208:211], v[224:227], v[0:3]
	s_add_u32 s76, s76, 0x80
	s_addc_u32 s77, s77, 0
	s_waitcnt lgkmcnt(5)
	v_mfma_f32_16x16x32_bf16 v[4:7], v[208:211], v[228:231], v[4:7]
	s_waitcnt lgkmcnt(4)
	v_mfma_f32_16x16x32_bf16 v[8:11], v[208:211], v[232:235], v[8:11]
	s_add_u32 s78, s78, 0x80
	s_addc_u32 s79, s79, 0
	s_waitcnt lgkmcnt(3)
	v_mfma_f32_16x16x32_bf16 v[12:15], v[208:211], v[236:239], v[12:15]
	s_waitcnt lgkmcnt(2)
	v_mfma_f32_16x16x32_bf16 v[16:19], v[212:215], v[224:227], v[16:19]
	v_mfma_f32_16x16x32_bf16 v[20:23], v[212:215], v[228:231], v[20:23]
	v_mfma_f32_16x16x32_bf16 v[24:27], v[212:215], v[232:235], v[24:27]
	v_mfma_f32_16x16x32_bf16 v[28:31], v[212:215], v[236:239], v[28:31]
	s_waitcnt lgkmcnt(1)
	v_mfma_f32_16x16x32_bf16 v[32:35], v[216:219], v[224:227], v[32:35]
	v_mfma_f32_16x16x32_bf16 v[36:39], v[216:219], v[228:231], v[36:39]
	v_mfma_f32_16x16x32_bf16 v[40:43], v[216:219], v[232:235], v[40:43]
	v_mfma_f32_16x16x32_bf16 v[44:47], v[216:219], v[236:239], v[44:47]
	s_waitcnt lgkmcnt(0)
	v_mfma_f32_16x16x32_bf16 v[48:51], v[220:223], v[224:227], v[48:51]
	v_mfma_f32_16x16x32_bf16 v[52:55], v[220:223], v[228:231], v[52:55]
	v_mfma_f32_16x16x32_bf16 v[56:59], v[220:223], v[232:235], v[56:59]
	v_mfma_f32_16x16x32_bf16 v[60:63], v[220:223], v[236:239], v[60:63]
	s_waitcnt vmcnt(0)
	s_barrier
	ds_read_b128 v[176:179], v244 offset:32768
	ds_read_b128 v[80:83], v246 offset:32768
	ds_read_b128 v[84:87], v246 offset:34816
	ds_read_b128 v[88:91], v246 offset:36864
	ds_read_b128 v[92:95], v246 offset:38912
	ds_read_b128 v[180:183], v244 offset:34816
	ds_read_b128 v[184:187], v244 offset:36864
	ds_read_b128 v[188:191], v244 offset:38912
	s_waitcnt lgkmcnt(6)
	v_mfma_f32_16x16x32_bf16 v[0:3], v[176:179], v[80:83], v[0:3]
	ds_read_b128 v[208:211], v245 offset:32768
	s_add_i32 m0, s81, 0
	s_waitcnt lgkmcnt(6)
	v_mfma_f32_16x16x32_bf16 v[4:7], v[176:179], v[84:87], v[4:7]
	ds_read_b128 v[224:227], v247 offset:32768
	global_load_lds_dwordx4 v240, s[76:77]
	s_waitcnt lgkmcnt(6)
	v_mfma_f32_16x16x32_bf16 v[8:11], v[176:179], v[88:91], v[8:11]
	ds_read_b128 v[228:231], v247 offset:34816
	s_add_i32 m0, s81, 4096
	s_waitcnt lgkmcnt(6)
	v_mfma_f32_16x16x32_bf16 v[12:15], v[176:179], v[92:95], v[12:15]
	ds_read_b128 v[232:235], v247 offset:36864
	global_load_lds_dwordx4 v241, s[76:77]
	s_waitcnt lgkmcnt(6)
	v_mfma_f32_16x16x32_bf16 v[16:19], v[180:183], v[80:83], v[16:19]
	ds_read_b128 v[236:239], v247 offset:38912
	s_add_i32 m0, s81, 8192
	v_mfma_f32_16x16x32_bf16 v[20:23], v[180:183], v[84:87], v[20:23]
	ds_read_b128 v[212:215], v245 offset:34816
	global_load_lds_dwordx4 v242, s[76:77]
	v_mfma_f32_16x16x32_bf16 v[24:27], v[180:183], v[88:91], v[24:27]
	ds_read_b128 v[216:219], v245 offset:36864
	s_add_i32 m0, s81, 12288
	v_mfma_f32_16x16x32_bf16 v[28:31], v[180:183], v[92:95], v[28:31]
	ds_read_b128 v[220:223], v245 offset:38912
	global_load_lds_dwordx4 v243, s[76:77]
	s_waitcnt lgkmcnt(9)
	v_mfma_f32_16x16x32_bf16 v[32:35], v[184:187], v[80:83], v[32:35]
	s_add_i32 m0, s81, 16384
	v_mfma_f32_16x16x32_bf16 v[36:39], v[184:187], v[84:87], v[36:39]
	global_load_lds_dwordx4 v240, s[78:79]
	v_mfma_f32_16x16x32_bf16 v[40:43], v[184:187], v[88:91], v[40:43]
	s_add_i32 m0, s81, 20480
	v_mfma_f32_16x16x32_bf16 v[44:47], v[184:187], v[92:95], v[44:47]
	global_load_lds_dwordx4 v241, s[78:79]
	s_waitcnt lgkmcnt(8)
	v_mfma_f32_16x16x32_bf16 v[48:51], v[188:191], v[80:83], v[48:51]
	s_add_i32 m0, s81, 24576
	v_mfma_f32_16x16x32_bf16 v[52:55], v[188:191], v[84:87], v[52:55]
	global_load_lds_dwordx4 v242, s[78:79]
	v_mfma_f32_16x16x32_bf16 v[56:59], v[188:191], v[88:91], v[56:59]
	s_add_i32 m0, s81, 28672
	v_mfma_f32_16x16x32_bf16 v[60:63], v[188:191], v[92:95], v[60:63]
	global_load_lds_dwordx4 v243, s[78:79]
	s_waitcnt lgkmcnt(6)
	v_mfma_f32_16x16x32_bf16 v[0:3], v[208:211], v[224:227], v[0:3]
	s_add_u32 s76, s76, 0x80
	s_addc_u32 s77, s77, 0
	s_waitcnt lgkmcnt(5)
	v_mfma_f32_16x16x32_bf16 v[4:7], v[208:211], v[228:231], v[4:7]
	s_waitcnt lgkmcnt(4)
	v_mfma_f32_16x16x32_bf16 v[8:11], v[208:211], v[232:235], v[8:11]
	s_add_u32 s78, s78, 0x80
	s_addc_u32 s79, s79, 0
	s_waitcnt lgkmcnt(3)
	v_mfma_f32_16x16x32_bf16 v[12:15], v[208:211], v[236:239], v[12:15]
	s_waitcnt lgkmcnt(2)
	v_mfma_f32_16x16x32_bf16 v[16:19], v[212:215], v[224:227], v[16:19]
	v_mfma_f32_16x16x32_bf16 v[20:23], v[212:215], v[228:231], v[20:23]
	v_mfma_f32_16x16x32_bf16 v[24:27], v[212:215], v[232:235], v[24:27]
	v_mfma_f32_16x16x32_bf16 v[28:31], v[212:215], v[236:239], v[28:31]
	s_waitcnt lgkmcnt(1)
	v_mfma_f32_16x16x32_bf16 v[32:35], v[216:219], v[224:227], v[32:35]
	v_mfma_f32_16x16x32_bf16 v[36:39], v[216:219], v[228:231], v[36:39]
	v_mfma_f32_16x16x32_bf16 v[40:43], v[216:219], v[232:235], v[40:43]
	v_mfma_f32_16x16x32_bf16 v[44:47], v[216:219], v[236:239], v[44:47]
	s_waitcnt lgkmcnt(0)
	v_mfma_f32_16x16x32_bf16 v[48:51], v[220:223], v[224:227], v[48:51]
	v_mfma_f32_16x16x32_bf16 v[52:55], v[220:223], v[228:231], v[52:55]
	v_mfma_f32_16x16x32_bf16 v[56:59], v[220:223], v[232:235], v[56:59]
	v_mfma_f32_16x16x32_bf16 v[60:63], v[220:223], v[236:239], v[60:63]
	s_waitcnt vmcnt(0)
	s_barrier
	ds_read_b128 v[176:179], v244 offset:0
	ds_read_b128 v[80:83], v246 offset:0
	ds_read_b128 v[84:87], v246 offset:2048
	ds_read_b128 v[88:91], v246 offset:4096
	ds_read_b128 v[92:95], v246 offset:6144
	ds_read_b128 v[180:183], v244 offset:2048
	ds_read_b128 v[184:187], v244 offset:4096
	ds_read_b128 v[188:191], v244 offset:6144
	s_waitcnt lgkmcnt(6)
	v_mfma_f32_16x16x32_bf16 v[0:3], v[176:179], v[80:83], v[0:3]
	ds_read_b128 v[208:211], v245 offset:0
	s_add_i32 m0, s81, 32768
	s_waitcnt lgkmcnt(6)
	v_mfma_f32_16x16x32_bf16 v[4:7], v[176:179], v[84:87], v[4:7]
	ds_read_b128 v[224:227], v247 offset:0
	global_load_lds_dwordx4 v240, s[76:77]
	s_waitcnt lgkmcnt(6)
	v_mfma_f32_16x16x32_bf16 v[8:11], v[176:179], v[88:91], v[8:11]
	ds_read_b128 v[228:231], v247 offset:2048
	s_add_i32 m0, s81, 36864
	s_waitcnt lgkmcnt(6)
	v_mfma_f32_16x16x32_bf16 v[12:15], v[176:179], v[92:95], v[12:15]
	ds_read_b128 v[232:235], v247 offset:4096
	global_load_lds_dwordx4 v241, s[76:77]
	s_waitcnt lgkmcnt(6)
	v_mfma_f32_16x16x32_bf16 v[16:19], v[180:183], v[80:83], v[16:19]
	ds_read_b128 v[236:239], v247 offset:6144
	s_add_i32 m0, s81, 40960
	v_mfma_f32_16x16x32_bf16 v[20:23], v[180:183], v[84:87], v[20:23]
	ds_read_b128 v[212:215], v245 offset:2048
	global_load_lds_dwordx4 v242, s[76:77]
	v_mfma_f32_16x16x32_bf16 v[24:27], v[180:183], v[88:91], v[24:27]
	ds_read_b128 v[216:219], v245 offset:4096
	s_add_i32 m0, s81, 45056
	v_mfma_f32_16x16x32_bf16 v[28:31], v[180:183], v[92:95], v[28:31]
	ds_read_b128 v[220:223], v245 offset:6144
	global_load_lds_dwordx4 v243, s[76:77]
	s_waitcnt lgkmcnt(9)
	v_mfma_f32_16x16x32_bf16 v[32:35], v[184:187], v[80:83], v[32:35]
	s_add_i32 m0, s81, 49152
	v_mfma_f32_16x16x32_bf16 v[36:39], v[184:187], v[84:87], v[36:39]
	global_load_lds_dwordx4 v240, s[78:79]
	v_mfma_f32_16x16x32_bf16 v[40:43], v[184:187], v[88:91], v[40:43]
	s_add_i32 m0, s81, 53248
	v_mfma_f32_16x16x32_bf16 v[44:47], v[184:187], v[92:95], v[44:47]
	global_load_lds_dwordx4 v241, s[78:79]
	s_waitcnt lgkmcnt(8)
	v_mfma_f32_16x16x32_bf16 v[48:51], v[188:191], v[80:83], v[48:51]
	s_add_i32 m0, s81, 57344
	v_mfma_f32_16x16x32_bf16 v[52:55], v[188:191], v[84:87], v[52:55]
	global_load_lds_dwordx4 v242, s[78:79]
	v_mfma_f32_16x16x32_bf16 v[56:59], v[188:191], v[88:91], v[56:59]
	s_add_i32 m0, s81, 61440
	v_mfma_f32_16x16x32_bf16 v[60:63], v[188:191], v[92:95], v[60:63]
	global_load_lds_dwordx4 v243, s[78:79]
	s_waitcnt lgkmcnt(6)
	v_mfma_f32_16x16x32_bf16 v[0:3], v[208:211], v[224:227], v[0:3]
	s_add_u32 s76, s76, 0x80
	s_addc_u32 s77, s77, 0
	s_waitcnt lgkmcnt(5)
	v_mfma_f32_16x16x32_bf16 v[4:7], v[208:211], v[228:231], v[4:7]
	s_waitcnt lgkmcnt(4)
	v_mfma_f32_16x16x32_bf16 v[8:11], v[208:211], v[232:235], v[8:11]
	s_add_u32 s78, s78, 0x80
	s_addc_u32 s79, s79, 0
	s_waitcnt lgkmcnt(3)
	v_mfma_f32_16x16x32_bf16 v[12:15], v[208:211], v[236:239], v[12:15]
	s_waitcnt lgkmcnt(2)
	v_mfma_f32_16x16x32_bf16 v[16:19], v[212:215], v[224:227], v[16:19]
	v_add_u32_e32 v96, 0x0, v108
	v_mfma_f32_16x16x32_bf16 v[20:23], v[212:215], v[228:231], v[20:23]
	global_load_dwordx4 v[64:67], v96, s[86:87] nt
	v_mfma_f32_16x16x32_bf16 v[24:27], v[212:215], v[232:235], v[24:27]
	v_mfma_f32_16x16x32_bf16 v[28:31], v[212:215], v[236:239], v[28:31]
	s_waitcnt lgkmcnt(1)
	v_mfma_f32_16x16x32_bf16 v[32:35], v[216:219], v[224:227], v[32:35]
	v_mfma_f32_16x16x32_bf16 v[36:39], v[216:219], v[228:231], v[36:39]
	v_mfma_f32_16x16x32_bf16 v[40:43], v[216:219], v[232:235], v[40:43]
	v_mfma_f32_16x16x32_bf16 v[44:47], v[216:219], v[236:239], v[44:47]
	s_waitcnt lgkmcnt(0)
	v_mfma_f32_16x16x32_bf16 v[48:51], v[220:223], v[224:227], v[48:51]
	v_mfma_f32_16x16x32_bf16 v[52:55], v[220:223], v[228:231], v[52:55]
	v_mfma_f32_16x16x32_bf16 v[56:59], v[220:223], v[232:235], v[56:59]
	v_mfma_f32_16x16x32_bf16 v[60:63], v[220:223], v[236:239], v[60:63]
	s_waitcnt vmcnt(1)
	s_barrier
	ds_read_b128 v[176:179], v244 offset:32768
	ds_read_b128 v[80:83], v246 offset:32768
	ds_read_b128 v[84:87], v246 offset:34816
	ds_read_b128 v[88:91], v246 offset:36864
	ds_read_b128 v[92:95], v246 offset:38912
	ds_read_b128 v[180:183], v244 offset:34816
	ds_read_b128 v[184:187], v244 offset:36864
	ds_read_b128 v[188:191], v244 offset:38912
	s_waitcnt lgkmcnt(6)
	v_mfma_f32_16x16x32_bf16 v[0:3], v[176:179], v[80:83], v[0:3]
	ds_read_b128 v[208:211], v245 offset:32768
	s_add_i32 m0, s81, 0
	s_waitcnt lgkmcnt(6)
	v_mfma_f32_16x16x32_bf16 v[4:7], v[176:179], v[84:87], v[4:7]
	ds_read_b128 v[224:227], v247 offset:32768
	global_load_lds_dwordx4 v240, s[76:77]
	s_waitcnt lgkmcnt(6)
	v_mfma_f32_16x16x32_bf16 v[8:11], v[176:179], v[88:91], v[8:11]
	ds_read_b128 v[228:231], v247 offset:34816
	s_add_i32 m0, s81, 4096
	s_waitcnt lgkmcnt(6)
	v_mfma_f32_16x16x32_bf16 v[12:15], v[176:179], v[92:95], v[12:15]
	ds_read_b128 v[232:235], v247 offset:36864
	global_load_lds_dwordx4 v241, s[76:77]
	s_waitcnt lgkmcnt(6)
	v_mfma_f32_16x16x32_bf16 v[16:19], v[180:183], v[80:83], v[16:19]
	ds_read_b128 v[236:239], v247 offset:38912
	s_add_i32 m0, s81, 8192
	v_mfma_f32_16x16x32_bf16 v[20:23], v[180:183], v[84:87], v[20:23]
	ds_read_b128 v[212:215], v245 offset:34816
	global_load_lds_dwordx4 v242, s[76:77]
	v_mfma_f32_16x16x32_bf16 v[24:27], v[180:183], v[88:91], v[24:27]
	ds_read_b128 v[216:219], v245 offset:36864
	s_add_i32 m0, s81, 12288
	v_mfma_f32_16x16x32_bf16 v[28:31], v[180:183], v[92:95], v[28:31]
	ds_read_b128 v[220:223], v245 offset:38912
	global_load_lds_dwordx4 v243, s[76:77]
	s_waitcnt lgkmcnt(9)
	v_mfma_f32_16x16x32_bf16 v[32:35], v[184:187], v[80:83], v[32:35]
	s_add_i32 m0, s81, 16384
	v_mfma_f32_16x16x32_bf16 v[36:39], v[184:187], v[84:87], v[36:39]
	global_load_lds_dwordx4 v240, s[78:79]
	v_mfma_f32_16x16x32_bf16 v[40:43], v[184:187], v[88:91], v[40:43]
	s_add_i32 m0, s81, 20480
	v_mfma_f32_16x16x32_bf16 v[44:47], v[184:187], v[92:95], v[44:47]
	global_load_lds_dwordx4 v241, s[78:79]
	s_waitcnt lgkmcnt(8)
	v_mfma_f32_16x16x32_bf16 v[48:51], v[188:191], v[80:83], v[48:51]
	s_add_i32 m0, s81, 24576
	v_mfma_f32_16x16x32_bf16 v[52:55], v[188:191], v[84:87], v[52:55]
	global_load_lds_dwordx4 v242, s[78:79]
	v_mfma_f32_16x16x32_bf16 v[56:59], v[188:191], v[88:91], v[56:59]
	s_add_i32 m0, s81, 28672
	v_mfma_f32_16x16x32_bf16 v[60:63], v[188:191], v[92:95], v[60:63]
	global_load_lds_dwordx4 v243, s[78:79]
	s_waitcnt lgkmcnt(6)
	v_mfma_f32_16x16x32_bf16 v[0:3], v[208:211], v[224:227], v[0:3]
	s_add_u32 s76, s76, 0x80
	s_addc_u32 s77, s77, 0
	s_waitcnt lgkmcnt(5)
	v_mfma_f32_16x16x32_bf16 v[4:7], v[208:211], v[228:231], v[4:7]
	s_waitcnt lgkmcnt(4)
	v_mfma_f32_16x16x32_bf16 v[8:11], v[208:211], v[232:235], v[8:11]
	s_add_u32 s78, s78, 0x80
	s_addc_u32 s79, s79, 0
	s_waitcnt lgkmcnt(3)
	v_mfma_f32_16x16x32_bf16 v[12:15], v[208:211], v[236:239], v[12:15]
	s_waitcnt lgkmcnt(2)
	v_mfma_f32_16x16x32_bf16 v[16:19], v[212:215], v[224:227], v[16:19]
	v_add_u32_e32 v96, 0x8000, v108
	v_mfma_f32_16x16x32_bf16 v[20:23], v[212:215], v[228:231], v[20:23]
	global_load_dwordx4 v[68:71], v96, s[86:87] nt
	v_mfma_f32_16x16x32_bf16 v[24:27], v[212:215], v[232:235], v[24:27]
	v_mfma_f32_16x16x32_bf16 v[28:31], v[212:215], v[236:239], v[28:31]
	s_waitcnt lgkmcnt(1)
	v_mfma_f32_16x16x32_bf16 v[32:35], v[216:219], v[224:227], v[32:35]
	v_mfma_f32_16x16x32_bf16 v[36:39], v[216:219], v[228:231], v[36:39]
	v_mfma_f32_16x16x32_bf16 v[40:43], v[216:219], v[232:235], v[40:43]
	v_mfma_f32_16x16x32_bf16 v[44:47], v[216:219], v[236:239], v[44:47]
	s_waitcnt lgkmcnt(0)
	v_mfma_f32_16x16x32_bf16 v[48:51], v[220:223], v[224:227], v[48:51]
	v_mfma_f32_16x16x32_bf16 v[52:55], v[220:223], v[228:231], v[52:55]
	v_mfma_f32_16x16x32_bf16 v[56:59], v[220:223], v[232:235], v[56:59]
	v_mfma_f32_16x16x32_bf16 v[60:63], v[220:223], v[236:239], v[60:63]
	s_waitcnt vmcnt(1)
	s_barrier
	ds_read_b128 v[176:179], v244 offset:0
	ds_read_b128 v[80:83], v246 offset:0
	ds_read_b128 v[84:87], v246 offset:2048
	ds_read_b128 v[88:91], v246 offset:4096
	ds_read_b128 v[92:95], v246 offset:6144
	ds_read_b128 v[180:183], v244 offset:2048
	ds_read_b128 v[184:187], v244 offset:4096
	ds_read_b128 v[188:191], v244 offset:6144
	s_waitcnt lgkmcnt(6)
	v_mfma_f32_16x16x32_bf16 v[0:3], v[176:179], v[80:83], v[0:3]
	ds_read_b128 v[208:211], v245 offset:0
	s_add_i32 m0, s81, 32768
	s_waitcnt lgkmcnt(6)
	v_mfma_f32_16x16x32_bf16 v[4:7], v[176:179], v[84:87], v[4:7]
	ds_read_b128 v[224:227], v247 offset:0
	global_load_lds_dwordx4 v240, s[76:77]
	s_waitcnt lgkmcnt(6)
	v_mfma_f32_16x16x32_bf16 v[8:11], v[176:179], v[88:91], v[8:11]
	ds_read_b128 v[228:231], v247 offset:2048
	s_add_i32 m0, s81, 36864
	s_waitcnt lgkmcnt(6)
	v_mfma_f32_16x16x32_bf16 v[12:15], v[176:179], v[92:95], v[12:15]
	ds_read_b128 v[232:235], v247 offset:4096
	global_load_lds_dwordx4 v241, s[76:77]
	s_waitcnt lgkmcnt(6)
	v_mfma_f32_16x16x32_bf16 v[16:19], v[180:183], v[80:83], v[16:19]
	ds_read_b128 v[236:239], v247 offset:6144
	s_add_i32 m0, s81, 40960
	v_mfma_f32_16x16x32_bf16 v[20:23], v[180:183], v[84:87], v[20:23]
	ds_read_b128 v[212:215], v245 offset:2048
	global_load_lds_dwordx4 v242, s[76:77]
	v_mfma_f32_16x16x32_bf16 v[24:27], v[180:183], v[88:91], v[24:27]
	ds_read_b128 v[216:219], v245 offset:4096
	s_add_i32 m0, s81, 45056
	v_mfma_f32_16x16x32_bf16 v[28:31], v[180:183], v[92:95], v[28:31]
	ds_read_b128 v[220:223], v245 offset:6144
	global_load_lds_dwordx4 v243, s[76:77]
	s_waitcnt lgkmcnt(9)
	v_mfma_f32_16x16x32_bf16 v[32:35], v[184:187], v[80:83], v[32:35]
	s_add_i32 m0, s81, 49152
	v_mfma_f32_16x16x32_bf16 v[36:39], v[184:187], v[84:87], v[36:39]
	global_load_lds_dwordx4 v240, s[78:79]
	v_mfma_f32_16x16x32_bf16 v[40:43], v[184:187], v[88:91], v[40:43]
	s_add_i32 m0, s81, 53248
	v_mfma_f32_16x16x32_bf16 v[44:47], v[184:187], v[92:95], v[44:47]
	global_load_lds_dwordx4 v241, s[78:79]
	s_waitcnt lgkmcnt(8)
	v_mfma_f32_16x16x32_bf16 v[48:51], v[188:191], v[80:83], v[48:51]
	s_add_i32 m0, s81, 57344
	v_mfma_f32_16x16x32_bf16 v[52:55], v[188:191], v[84:87], v[52:55]
	global_load_lds_dwordx4 v242, s[78:79]
	v_mfma_f32_16x16x32_bf16 v[56:59], v[188:191], v[88:91], v[56:59]
	s_add_i32 m0, s81, 61440
	v_mfma_f32_16x16x32_bf16 v[60:63], v[188:191], v[92:95], v[60:63]
	global_load_lds_dwordx4 v243, s[78:79]
	s_waitcnt lgkmcnt(6)
	v_mfma_f32_16x16x32_bf16 v[0:3], v[208:211], v[224:227], v[0:3]
	s_add_u32 s76, s76, 0x80
	s_addc_u32 s77, s77, 0
	s_waitcnt lgkmcnt(5)
	v_mfma_f32_16x16x32_bf16 v[4:7], v[208:211], v[228:231], v[4:7]
	s_waitcnt lgkmcnt(4)
	v_mfma_f32_16x16x32_bf16 v[8:11], v[208:211], v[232:235], v[8:11]
	s_add_u32 s78, s78, 0x80
	s_addc_u32 s79, s79, 0
	s_waitcnt lgkmcnt(3)
	v_mfma_f32_16x16x32_bf16 v[12:15], v[208:211], v[236:239], v[12:15]
	s_waitcnt lgkmcnt(2)
	v_mfma_f32_16x16x32_bf16 v[16:19], v[212:215], v[224:227], v[16:19]
	v_add_u32_e32 v96, 0x10000, v108
	v_mfma_f32_16x16x32_bf16 v[20:23], v[212:215], v[228:231], v[20:23]
	global_load_dwordx4 v[192:195], v96, s[86:87] nt
	v_mfma_f32_16x16x32_bf16 v[24:27], v[212:215], v[232:235], v[24:27]
	v_mfma_f32_16x16x32_bf16 v[28:31], v[212:215], v[236:239], v[28:31]
	s_waitcnt lgkmcnt(1)
	v_mfma_f32_16x16x32_bf16 v[32:35], v[216:219], v[224:227], v[32:35]
	v_mfma_f32_16x16x32_bf16 v[36:39], v[216:219], v[228:231], v[36:39]
	v_mfma_f32_16x16x32_bf16 v[40:43], v[216:219], v[232:235], v[40:43]
	v_mfma_f32_16x16x32_bf16 v[44:47], v[216:219], v[236:239], v[44:47]
	s_waitcnt lgkmcnt(0)
	v_mfma_f32_16x16x32_bf16 v[48:51], v[220:223], v[224:227], v[48:51]
	v_mfma_f32_16x16x32_bf16 v[52:55], v[220:223], v[228:231], v[52:55]
	v_mfma_f32_16x16x32_bf16 v[56:59], v[220:223], v[232:235], v[56:59]
	v_mfma_f32_16x16x32_bf16 v[60:63], v[220:223], v[236:239], v[60:63]
	s_waitcnt vmcnt(1)
	s_barrier
	ds_read_b128 v[176:179], v244 offset:32768
	ds_read_b128 v[80:83], v246 offset:32768
	ds_read_b128 v[84:87], v246 offset:34816
	ds_read_b128 v[88:91], v246 offset:36864
	ds_read_b128 v[92:95], v246 offset:38912
	ds_read_b128 v[180:183], v244 offset:34816
	ds_read_b128 v[184:187], v244 offset:36864
	ds_read_b128 v[188:191], v244 offset:38912
	s_waitcnt lgkmcnt(6)
	v_mfma_f32_16x16x32_bf16 v[0:3], v[176:179], v[80:83], v[0:3]
	ds_read_b128 v[208:211], v245 offset:32768
	s_add_i32 m0, s81, 0
	s_waitcnt lgkmcnt(6)
	v_mfma_f32_16x16x32_bf16 v[4:7], v[176:179], v[84:87], v[4:7]
	ds_read_b128 v[224:227], v247 offset:32768
	global_load_lds_dwordx4 v240, s[76:77]
	s_waitcnt lgkmcnt(6)
	v_mfma_f32_16x16x32_bf16 v[8:11], v[176:179], v[88:91], v[8:11]
	ds_read_b128 v[228:231], v247 offset:34816
	s_add_i32 m0, s81, 4096
	s_waitcnt lgkmcnt(6)
	v_mfma_f32_16x16x32_bf16 v[12:15], v[176:179], v[92:95], v[12:15]
	ds_read_b128 v[232:235], v247 offset:36864
	global_load_lds_dwordx4 v241, s[76:77]
	s_waitcnt lgkmcnt(6)
	v_mfma_f32_16x16x32_bf16 v[16:19], v[180:183], v[80:83], v[16:19]
	ds_read_b128 v[236:239], v247 offset:38912
	s_add_i32 m0, s81, 8192
	v_mfma_f32_16x16x32_bf16 v[20:23], v[180:183], v[84:87], v[20:23]
	ds_read_b128 v[212:215], v245 offset:34816
	global_load_lds_dwordx4 v242, s[76:77]
	v_mfma_f32_16x16x32_bf16 v[24:27], v[180:183], v[88:91], v[24:27]
	ds_read_b128 v[216:219], v245 offset:36864
	s_add_i32 m0, s81, 12288
	v_mfma_f32_16x16x32_bf16 v[28:31], v[180:183], v[92:95], v[28:31]
	ds_read_b128 v[220:223], v245 offset:38912
	global_load_lds_dwordx4 v243, s[76:77]
	s_waitcnt lgkmcnt(9)
	v_mfma_f32_16x16x32_bf16 v[32:35], v[184:187], v[80:83], v[32:35]
	s_add_i32 m0, s81, 16384
	v_mfma_f32_16x16x32_bf16 v[36:39], v[184:187], v[84:87], v[36:39]
	global_load_lds_dwordx4 v240, s[78:79]
	v_mfma_f32_16x16x32_bf16 v[40:43], v[184:187], v[88:91], v[40:43]
	s_add_i32 m0, s81, 20480
	v_mfma_f32_16x16x32_bf16 v[44:47], v[184:187], v[92:95], v[44:47]
	global_load_lds_dwordx4 v241, s[78:79]
	s_waitcnt lgkmcnt(8)
	v_mfma_f32_16x16x32_bf16 v[48:51], v[188:191], v[80:83], v[48:51]
	s_add_i32 m0, s81, 24576
	v_mfma_f32_16x16x32_bf16 v[52:55], v[188:191], v[84:87], v[52:55]
	global_load_lds_dwordx4 v242, s[78:79]
	v_mfma_f32_16x16x32_bf16 v[56:59], v[188:191], v[88:91], v[56:59]
	s_add_i32 m0, s81, 28672
	v_mfma_f32_16x16x32_bf16 v[60:63], v[188:191], v[92:95], v[60:63]
	global_load_lds_dwordx4 v243, s[78:79]
	s_waitcnt lgkmcnt(6)
	v_mfma_f32_16x16x32_bf16 v[0:3], v[208:211], v[224:227], v[0:3]
	s_add_u32 s76, s76, 0x80
	s_addc_u32 s77, s77, 0
	s_waitcnt lgkmcnt(5)
	v_mfma_f32_16x16x32_bf16 v[4:7], v[208:211], v[228:231], v[4:7]
	s_waitcnt lgkmcnt(4)
	v_mfma_f32_16x16x32_bf16 v[8:11], v[208:211], v[232:235], v[8:11]
	s_add_u32 s78, s78, 0x80
	s_addc_u32 s79, s79, 0
	s_waitcnt lgkmcnt(3)
	v_mfma_f32_16x16x32_bf16 v[12:15], v[208:211], v[236:239], v[12:15]
	s_waitcnt lgkmcnt(2)
	v_mfma_f32_16x16x32_bf16 v[16:19], v[212:215], v[224:227], v[16:19]
	v_add_u32_e32 v96, 0x18000, v108
	v_mfma_f32_16x16x32_bf16 v[20:23], v[212:215], v[228:231], v[20:23]
	global_load_dwordx4 v[196:199], v96, s[86:87] nt
	v_mfma_f32_16x16x32_bf16 v[24:27], v[212:215], v[232:235], v[24:27]
	v_mfma_f32_16x16x32_bf16 v[28:31], v[212:215], v[236:239], v[28:31]
	s_waitcnt lgkmcnt(1)
	v_mfma_f32_16x16x32_bf16 v[32:35], v[216:219], v[224:227], v[32:35]
	v_mfma_f32_16x16x32_bf16 v[36:39], v[216:219], v[228:231], v[36:39]
	v_mfma_f32_16x16x32_bf16 v[40:43], v[216:219], v[232:235], v[40:43]
	v_mfma_f32_16x16x32_bf16 v[44:47], v[216:219], v[236:239], v[44:47]
	s_waitcnt lgkmcnt(0)
	v_mfma_f32_16x16x32_bf16 v[48:51], v[220:223], v[224:227], v[48:51]
	v_mfma_f32_16x16x32_bf16 v[52:55], v[220:223], v[228:231], v[52:55]
	v_mfma_f32_16x16x32_bf16 v[56:59], v[220:223], v[232:235], v[56:59]
	v_mfma_f32_16x16x32_bf16 v[60:63], v[220:223], v[236:239], v[60:63]
	s_waitcnt vmcnt(1)
	s_barrier
	ds_read_b128 v[176:179], v244 offset:0
	ds_read_b128 v[80:83], v246 offset:0
	ds_read_b128 v[84:87], v246 offset:2048
	ds_read_b128 v[88:91], v246 offset:4096
	ds_read_b128 v[92:95], v246 offset:6144
	ds_read_b128 v[180:183], v244 offset:2048
	ds_read_b128 v[184:187], v244 offset:4096
	ds_read_b128 v[188:191], v244 offset:6144
	s_waitcnt lgkmcnt(6)
	v_mfma_f32_16x16x32_bf16 v[0:3], v[176:179], v[80:83], v[0:3]
	ds_read_b128 v[208:211], v245 offset:0
	s_add_i32 m0, s81, 32768
	s_waitcnt lgkmcnt(6)
	v_mfma_f32_16x16x32_bf16 v[4:7], v[176:179], v[84:87], v[4:7]
	ds_read_b128 v[224:227], v247 offset:0
	global_load_lds_dwordx4 v240, s[76:77]
	s_waitcnt lgkmcnt(6)
	v_mfma_f32_16x16x32_bf16 v[8:11], v[176:179], v[88:91], v[8:11]
	ds_read_b128 v[228:231], v247 offset:2048
	s_add_i32 m0, s81, 36864
	s_waitcnt lgkmcnt(6)
	v_mfma_f32_16x16x32_bf16 v[12:15], v[176:179], v[92:95], v[12:15]
	ds_read_b128 v[232:235], v247 offset:4096
	global_load_lds_dwordx4 v241, s[76:77]
	s_waitcnt lgkmcnt(6)
	v_mfma_f32_16x16x32_bf16 v[16:19], v[180:183], v[80:83], v[16:19]
	ds_read_b128 v[236:239], v247 offset:6144
	s_add_i32 m0, s81, 40960
	v_mfma_f32_16x16x32_bf16 v[20:23], v[180:183], v[84:87], v[20:23]
	ds_read_b128 v[212:215], v245 offset:2048
	global_load_lds_dwordx4 v242, s[76:77]
	v_mfma_f32_16x16x32_bf16 v[24:27], v[180:183], v[88:91], v[24:27]
	ds_read_b128 v[216:219], v245 offset:4096
	s_add_i32 m0, s81, 45056
	v_mfma_f32_16x16x32_bf16 v[28:31], v[180:183], v[92:95], v[28:31]
	ds_read_b128 v[220:223], v245 offset:6144
	global_load_lds_dwordx4 v243, s[76:77]
	s_waitcnt lgkmcnt(9)
	v_mfma_f32_16x16x32_bf16 v[32:35], v[184:187], v[80:83], v[32:35]
	s_add_i32 m0, s81, 49152
	v_mfma_f32_16x16x32_bf16 v[36:39], v[184:187], v[84:87], v[36:39]
	global_load_lds_dwordx4 v240, s[78:79]
	v_mfma_f32_16x16x32_bf16 v[40:43], v[184:187], v[88:91], v[40:43]
	s_add_i32 m0, s81, 53248
	v_mfma_f32_16x16x32_bf16 v[44:47], v[184:187], v[92:95], v[44:47]
	global_load_lds_dwordx4 v241, s[78:79]
	s_waitcnt lgkmcnt(8)
	v_mfma_f32_16x16x32_bf16 v[48:51], v[188:191], v[80:83], v[48:51]
	s_add_i32 m0, s81, 57344
	v_mfma_f32_16x16x32_bf16 v[52:55], v[188:191], v[84:87], v[52:55]
	global_load_lds_dwordx4 v242, s[78:79]
	v_mfma_f32_16x16x32_bf16 v[56:59], v[188:191], v[88:91], v[56:59]
	s_add_i32 m0, s81, 61440
	v_mfma_f32_16x16x32_bf16 v[60:63], v[188:191], v[92:95], v[60:63]
	global_load_lds_dwordx4 v243, s[78:79]
	s_waitcnt lgkmcnt(6)
	v_mfma_f32_16x16x32_bf16 v[0:3], v[208:211], v[224:227], v[0:3]
	s_add_u32 s76, s76, 0x80
	s_addc_u32 s77, s77, 0
	s_waitcnt lgkmcnt(5)
	v_mfma_f32_16x16x32_bf16 v[4:7], v[208:211], v[228:231], v[4:7]
	s_waitcnt lgkmcnt(4)
	v_mfma_f32_16x16x32_bf16 v[8:11], v[208:211], v[232:235], v[8:11]
	s_add_u32 s78, s78, 0x80
	s_addc_u32 s79, s79, 0
	s_waitcnt lgkmcnt(3)
	v_mfma_f32_16x16x32_bf16 v[12:15], v[208:211], v[236:239], v[12:15]
	s_waitcnt lgkmcnt(2)
	v_mfma_f32_16x16x32_bf16 v[16:19], v[212:215], v[224:227], v[16:19]
	v_add_u32_e32 v96, 0x20000, v108
	v_mfma_f32_16x16x32_bf16 v[20:23], v[212:215], v[228:231], v[20:23]
	global_load_dwordx4 v[200:203], v96, s[86:87] nt
	v_mfma_f32_16x16x32_bf16 v[24:27], v[212:215], v[232:235], v[24:27]
	v_mfma_f32_16x16x32_bf16 v[28:31], v[212:215], v[236:239], v[28:31]
	s_waitcnt lgkmcnt(1)
	v_mfma_f32_16x16x32_bf16 v[32:35], v[216:219], v[224:227], v[32:35]
	v_mfma_f32_16x16x32_bf16 v[36:39], v[216:219], v[228:231], v[36:39]
	v_mfma_f32_16x16x32_bf16 v[40:43], v[216:219], v[232:235], v[40:43]
	v_mfma_f32_16x16x32_bf16 v[44:47], v[216:219], v[236:239], v[44:47]
	s_waitcnt lgkmcnt(0)
	v_mfma_f32_16x16x32_bf16 v[48:51], v[220:223], v[224:227], v[48:51]
	v_mfma_f32_16x16x32_bf16 v[52:55], v[220:223], v[228:231], v[52:55]
	v_mfma_f32_16x16x32_bf16 v[56:59], v[220:223], v[232:235], v[56:59]
	v_mfma_f32_16x16x32_bf16 v[60:63], v[220:223], v[236:239], v[60:63]
	s_waitcnt vmcnt(1)
	s_barrier
	ds_read_b128 v[176:179], v244 offset:32768
	ds_read_b128 v[80:83], v246 offset:32768
	ds_read_b128 v[84:87], v246 offset:34816
	ds_read_b128 v[88:91], v246 offset:36864
	ds_read_b128 v[92:95], v246 offset:38912
	ds_read_b128 v[180:183], v244 offset:34816
	ds_read_b128 v[184:187], v244 offset:36864
	ds_read_b128 v[188:191], v244 offset:38912
	s_waitcnt lgkmcnt(6)
	v_mfma_f32_16x16x32_bf16 v[0:3], v[176:179], v[80:83], v[0:3]
	ds_read_b128 v[208:211], v245 offset:32768
	s_add_i32 m0, s81, 0
	s_waitcnt lgkmcnt(6)
	v_mfma_f32_16x16x32_bf16 v[4:7], v[176:179], v[84:87], v[4:7]
	ds_read_b128 v[224:227], v247 offset:32768
	global_load_lds_dwordx4 v240, s[76:77]
	s_waitcnt lgkmcnt(6)
	v_mfma_f32_16x16x32_bf16 v[8:11], v[176:179], v[88:91], v[8:11]
	ds_read_b128 v[228:231], v247 offset:34816
	s_add_i32 m0, s81, 4096
	s_waitcnt lgkmcnt(6)
	v_mfma_f32_16x16x32_bf16 v[12:15], v[176:179], v[92:95], v[12:15]
	ds_read_b128 v[232:235], v247 offset:36864
	global_load_lds_dwordx4 v241, s[76:77]
	s_waitcnt lgkmcnt(6)
	v_mfma_f32_16x16x32_bf16 v[16:19], v[180:183], v[80:83], v[16:19]
	ds_read_b128 v[236:239], v247 offset:38912
	s_add_i32 m0, s81, 8192
	v_mfma_f32_16x16x32_bf16 v[20:23], v[180:183], v[84:87], v[20:23]
	ds_read_b128 v[212:215], v245 offset:34816
	global_load_lds_dwordx4 v242, s[76:77]
	v_mfma_f32_16x16x32_bf16 v[24:27], v[180:183], v[88:91], v[24:27]
	ds_read_b128 v[216:219], v245 offset:36864
	s_add_i32 m0, s81, 12288
	v_mfma_f32_16x16x32_bf16 v[28:31], v[180:183], v[92:95], v[28:31]
	ds_read_b128 v[220:223], v245 offset:38912
	global_load_lds_dwordx4 v243, s[76:77]
	s_waitcnt lgkmcnt(9)
	v_mfma_f32_16x16x32_bf16 v[32:35], v[184:187], v[80:83], v[32:35]
	s_add_i32 m0, s81, 16384
	v_mfma_f32_16x16x32_bf16 v[36:39], v[184:187], v[84:87], v[36:39]
	global_load_lds_dwordx4 v240, s[78:79]
	v_mfma_f32_16x16x32_bf16 v[40:43], v[184:187], v[88:91], v[40:43]
	s_add_i32 m0, s81, 20480
	v_mfma_f32_16x16x32_bf16 v[44:47], v[184:187], v[92:95], v[44:47]
	global_load_lds_dwordx4 v241, s[78:79]
	s_waitcnt lgkmcnt(8)
	v_mfma_f32_16x16x32_bf16 v[48:51], v[188:191], v[80:83], v[48:51]
	s_add_i32 m0, s81, 24576
	v_mfma_f32_16x16x32_bf16 v[52:55], v[188:191], v[84:87], v[52:55]
	global_load_lds_dwordx4 v242, s[78:79]
	v_mfma_f32_16x16x32_bf16 v[56:59], v[188:191], v[88:91], v[56:59]
	s_add_i32 m0, s81, 28672
	v_mfma_f32_16x16x32_bf16 v[60:63], v[188:191], v[92:95], v[60:63]
	global_load_lds_dwordx4 v243, s[78:79]
	s_waitcnt lgkmcnt(6)
	v_mfma_f32_16x16x32_bf16 v[0:3], v[208:211], v[224:227], v[0:3]
	s_add_u32 s76, s76, 0x80
	s_addc_u32 s77, s77, 0
	s_waitcnt lgkmcnt(5)
	v_mfma_f32_16x16x32_bf16 v[4:7], v[208:211], v[228:231], v[4:7]
	s_waitcnt lgkmcnt(4)
	v_mfma_f32_16x16x32_bf16 v[8:11], v[208:211], v[232:235], v[8:11]
	s_add_u32 s78, s78, 0x80
	s_addc_u32 s79, s79, 0
	s_waitcnt lgkmcnt(3)
	v_mfma_f32_16x16x32_bf16 v[12:15], v[208:211], v[236:239], v[12:15]
	s_waitcnt lgkmcnt(2)
	v_mfma_f32_16x16x32_bf16 v[16:19], v[212:215], v[224:227], v[16:19]
	v_add_u32_e32 v96, 0x28000, v108
	v_mfma_f32_16x16x32_bf16 v[20:23], v[212:215], v[228:231], v[20:23]
	global_load_dwordx4 v[110:113], v96, s[86:87] nt
	v_mfma_f32_16x16x32_bf16 v[24:27], v[212:215], v[232:235], v[24:27]
	v_mfma_f32_16x16x32_bf16 v[28:31], v[212:215], v[236:239], v[28:31]
	s_waitcnt lgkmcnt(1)
	v_mfma_f32_16x16x32_bf16 v[32:35], v[216:219], v[224:227], v[32:35]
	v_mfma_f32_16x16x32_bf16 v[36:39], v[216:219], v[228:231], v[36:39]
	v_mfma_f32_16x16x32_bf16 v[40:43], v[216:219], v[232:235], v[40:43]
	v_mfma_f32_16x16x32_bf16 v[44:47], v[216:219], v[236:239], v[44:47]
	s_waitcnt lgkmcnt(0)
	v_mfma_f32_16x16x32_bf16 v[48:51], v[220:223], v[224:227], v[48:51]
	v_mfma_f32_16x16x32_bf16 v[52:55], v[220:223], v[228:231], v[52:55]
	v_mfma_f32_16x16x32_bf16 v[56:59], v[220:223], v[232:235], v[56:59]
	v_mfma_f32_16x16x32_bf16 v[60:63], v[220:223], v[236:239], v[60:63]
	s_waitcnt vmcnt(1)
	s_barrier
	ds_read_b128 v[176:179], v244 offset:0
	ds_read_b128 v[80:83], v246 offset:0
	ds_read_b128 v[84:87], v246 offset:2048
	ds_read_b128 v[88:91], v246 offset:4096
	ds_read_b128 v[92:95], v246 offset:6144
	ds_read_b128 v[180:183], v244 offset:2048
	ds_read_b128 v[184:187], v244 offset:4096
	ds_read_b128 v[188:191], v244 offset:6144
	s_waitcnt lgkmcnt(6)
	v_mfma_f32_16x16x32_bf16 v[0:3], v[176:179], v[80:83], v[0:3]
	ds_read_b128 v[208:211], v245 offset:0
	s_add_i32 m0, s81, 32768
	s_waitcnt lgkmcnt(6)
	v_mfma_f32_16x16x32_bf16 v[4:7], v[176:179], v[84:87], v[4:7]
	ds_read_b128 v[224:227], v247 offset:0
	global_load_lds_dwordx4 v240, s[76:77]
	s_waitcnt lgkmcnt(6)
	v_mfma_f32_16x16x32_bf16 v[8:11], v[176:179], v[88:91], v[8:11]
	ds_read_b128 v[228:231], v247 offset:2048
	s_add_i32 m0, s81, 36864
	s_waitcnt lgkmcnt(6)
	v_mfma_f32_16x16x32_bf16 v[12:15], v[176:179], v[92:95], v[12:15]
	ds_read_b128 v[232:235], v247 offset:4096
	global_load_lds_dwordx4 v241, s[76:77]
	s_waitcnt lgkmcnt(6)
	v_mfma_f32_16x16x32_bf16 v[16:19], v[180:183], v[80:83], v[16:19]
	ds_read_b128 v[236:239], v247 offset:6144
	s_add_i32 m0, s81, 40960
	v_mfma_f32_16x16x32_bf16 v[20:23], v[180:183], v[84:87], v[20:23]
	ds_read_b128 v[212:215], v245 offset:2048
	global_load_lds_dwordx4 v242, s[76:77]
	v_mfma_f32_16x16x32_bf16 v[24:27], v[180:183], v[88:91], v[24:27]
	ds_read_b128 v[216:219], v245 offset:4096
	s_add_i32 m0, s81, 45056
	v_mfma_f32_16x16x32_bf16 v[28:31], v[180:183], v[92:95], v[28:31]
	ds_read_b128 v[220:223], v245 offset:6144
	global_load_lds_dwordx4 v243, s[76:77]
	s_waitcnt lgkmcnt(9)
	v_mfma_f32_16x16x32_bf16 v[32:35], v[184:187], v[80:83], v[32:35]
	s_add_i32 m0, s81, 49152
	v_mfma_f32_16x16x32_bf16 v[36:39], v[184:187], v[84:87], v[36:39]
	global_load_lds_dwordx4 v240, s[78:79]
	v_mfma_f32_16x16x32_bf16 v[40:43], v[184:187], v[88:91], v[40:43]
	s_add_i32 m0, s81, 53248
	v_mfma_f32_16x16x32_bf16 v[44:47], v[184:187], v[92:95], v[44:47]
	global_load_lds_dwordx4 v241, s[78:79]
	s_waitcnt lgkmcnt(8)
	v_mfma_f32_16x16x32_bf16 v[48:51], v[188:191], v[80:83], v[48:51]
	s_add_i32 m0, s81, 57344
	v_mfma_f32_16x16x32_bf16 v[52:55], v[188:191], v[84:87], v[52:55]
	global_load_lds_dwordx4 v242, s[78:79]
	v_mfma_f32_16x16x32_bf16 v[56:59], v[188:191], v[88:91], v[56:59]
	s_add_i32 m0, s81, 61440
	v_mfma_f32_16x16x32_bf16 v[60:63], v[188:191], v[92:95], v[60:63]
	global_load_lds_dwordx4 v243, s[78:79]
	s_waitcnt lgkmcnt(6)
	v_mfma_f32_16x16x32_bf16 v[0:3], v[208:211], v[224:227], v[0:3]
	s_add_u32 s76, s76, 0x80
	s_addc_u32 s77, s77, 0
	s_waitcnt lgkmcnt(5)
	v_mfma_f32_16x16x32_bf16 v[4:7], v[208:211], v[228:231], v[4:7]
	s_waitcnt lgkmcnt(4)
	v_mfma_f32_16x16x32_bf16 v[8:11], v[208:211], v[232:235], v[8:11]
	s_add_u32 s78, s78, 0x80
	s_addc_u32 s79, s79, 0
	s_waitcnt lgkmcnt(3)
	v_mfma_f32_16x16x32_bf16 v[12:15], v[208:211], v[236:239], v[12:15]
	s_waitcnt lgkmcnt(2)
	v_mfma_f32_16x16x32_bf16 v[16:19], v[212:215], v[224:227], v[16:19]
	v_add_u32_e32 v96, 0x30000, v108
	v_mfma_f32_16x16x32_bf16 v[20:23], v[212:215], v[228:231], v[20:23]
	global_load_dwordx4 v[116:119], v96, s[86:87] nt
	v_mfma_f32_16x16x32_bf16 v[24:27], v[212:215], v[232:235], v[24:27]
	v_mfma_f32_16x16x32_bf16 v[28:31], v[212:215], v[236:239], v[28:31]
	s_waitcnt lgkmcnt(1)
	v_mfma_f32_16x16x32_bf16 v[32:35], v[216:219], v[224:227], v[32:35]
	v_mfma_f32_16x16x32_bf16 v[36:39], v[216:219], v[228:231], v[36:39]
	v_mfma_f32_16x16x32_bf16 v[40:43], v[216:219], v[232:235], v[40:43]
	v_mfma_f32_16x16x32_bf16 v[44:47], v[216:219], v[236:239], v[44:47]
	s_waitcnt lgkmcnt(0)
	v_mfma_f32_16x16x32_bf16 v[48:51], v[220:223], v[224:227], v[48:51]
	v_mfma_f32_16x16x32_bf16 v[52:55], v[220:223], v[228:231], v[52:55]
	v_mfma_f32_16x16x32_bf16 v[56:59], v[220:223], v[232:235], v[56:59]
	v_mfma_f32_16x16x32_bf16 v[60:63], v[220:223], v[236:239], v[60:63]
	s_waitcnt vmcnt(1)
	s_barrier
	ds_read_b128 v[176:179], v244 offset:32768
	ds_read_b128 v[80:83], v246 offset:32768
	ds_read_b128 v[84:87], v246 offset:34816
	ds_read_b128 v[88:91], v246 offset:36864
	ds_read_b128 v[92:95], v246 offset:38912
	ds_read_b128 v[180:183], v244 offset:34816
	ds_read_b128 v[184:187], v244 offset:36864
	ds_read_b128 v[188:191], v244 offset:38912
	s_waitcnt lgkmcnt(6)
	v_mfma_f32_16x16x32_bf16 v[0:3], v[176:179], v[80:83], v[0:3]
	ds_read_b128 v[208:211], v245 offset:32768
	s_add_i32 m0, s81, 0
	s_waitcnt lgkmcnt(6)
	v_mfma_f32_16x16x32_bf16 v[4:7], v[176:179], v[84:87], v[4:7]
	ds_read_b128 v[224:227], v247 offset:32768
	global_load_lds_dwordx4 v240, s[76:77]
	s_waitcnt lgkmcnt(6)
	v_mfma_f32_16x16x32_bf16 v[8:11], v[176:179], v[88:91], v[8:11]
	ds_read_b128 v[228:231], v247 offset:34816
	s_add_i32 m0, s81, 4096
	s_waitcnt lgkmcnt(6)
	v_mfma_f32_16x16x32_bf16 v[12:15], v[176:179], v[92:95], v[12:15]
	ds_read_b128 v[232:235], v247 offset:36864
	global_load_lds_dwordx4 v241, s[76:77]
	s_waitcnt lgkmcnt(6)
	v_mfma_f32_16x16x32_bf16 v[16:19], v[180:183], v[80:83], v[16:19]
	ds_read_b128 v[236:239], v247 offset:38912
	s_add_i32 m0, s81, 8192
	v_mfma_f32_16x16x32_bf16 v[20:23], v[180:183], v[84:87], v[20:23]
	ds_read_b128 v[212:215], v245 offset:34816
	global_load_lds_dwordx4 v242, s[76:77]
	v_mfma_f32_16x16x32_bf16 v[24:27], v[180:183], v[88:91], v[24:27]
	ds_read_b128 v[216:219], v245 offset:36864
	s_add_i32 m0, s81, 12288
	v_mfma_f32_16x16x32_bf16 v[28:31], v[180:183], v[92:95], v[28:31]
	ds_read_b128 v[220:223], v245 offset:38912
	global_load_lds_dwordx4 v243, s[76:77]
	s_waitcnt lgkmcnt(9)
	v_mfma_f32_16x16x32_bf16 v[32:35], v[184:187], v[80:83], v[32:35]
	s_add_i32 m0, s81, 16384
	v_mfma_f32_16x16x32_bf16 v[36:39], v[184:187], v[84:87], v[36:39]
	global_load_lds_dwordx4 v240, s[78:79]
	v_mfma_f32_16x16x32_bf16 v[40:43], v[184:187], v[88:91], v[40:43]
	s_add_i32 m0, s81, 20480
	v_mfma_f32_16x16x32_bf16 v[44:47], v[184:187], v[92:95], v[44:47]
	global_load_lds_dwordx4 v241, s[78:79]
	s_waitcnt lgkmcnt(8)
	v_mfma_f32_16x16x32_bf16 v[48:51], v[188:191], v[80:83], v[48:51]
	s_add_i32 m0, s81, 24576
	v_mfma_f32_16x16x32_bf16 v[52:55], v[188:191], v[84:87], v[52:55]
	global_load_lds_dwordx4 v242, s[78:79]
	v_mfma_f32_16x16x32_bf16 v[56:59], v[188:191], v[88:91], v[56:59]
	s_add_i32 m0, s81, 28672
	v_mfma_f32_16x16x32_bf16 v[60:63], v[188:191], v[92:95], v[60:63]
	global_load_lds_dwordx4 v243, s[78:79]
	s_waitcnt lgkmcnt(6)
	v_mfma_f32_16x16x32_bf16 v[0:3], v[208:211], v[224:227], v[0:3]
	s_add_u32 s76, s76, 0x80
	s_addc_u32 s77, s77, 0
	s_waitcnt lgkmcnt(5)
	v_mfma_f32_16x16x32_bf16 v[4:7], v[208:211], v[228:231], v[4:7]
	s_waitcnt lgkmcnt(4)
	v_mfma_f32_16x16x32_bf16 v[8:11], v[208:211], v[232:235], v[8:11]
	s_add_u32 s78, s78, 0x80
	s_addc_u32 s79, s79, 0
	s_waitcnt lgkmcnt(3)
	v_mfma_f32_16x16x32_bf16 v[12:15], v[208:211], v[236:239], v[12:15]
	s_waitcnt lgkmcnt(2)
	v_mfma_f32_16x16x32_bf16 v[16:19], v[212:215], v[224:227], v[16:19]
	v_add_u32_e32 v96, 0x38000, v108
	v_mfma_f32_16x16x32_bf16 v[20:23], v[212:215], v[228:231], v[20:23]
	global_load_dwordx4 v[120:123], v96, s[86:87] nt
	v_mfma_f32_16x16x32_bf16 v[24:27], v[212:215], v[232:235], v[24:27]
	v_mfma_f32_16x16x32_bf16 v[28:31], v[212:215], v[236:239], v[28:31]
	s_waitcnt lgkmcnt(1)
	v_mfma_f32_16x16x32_bf16 v[32:35], v[216:219], v[224:227], v[32:35]
	v_mfma_f32_16x16x32_bf16 v[36:39], v[216:219], v[228:231], v[36:39]
	v_mfma_f32_16x16x32_bf16 v[40:43], v[216:219], v[232:235], v[40:43]
	v_mfma_f32_16x16x32_bf16 v[44:47], v[216:219], v[236:239], v[44:47]
	s_waitcnt lgkmcnt(0)
	v_mfma_f32_16x16x32_bf16 v[48:51], v[220:223], v[224:227], v[48:51]
	v_mfma_f32_16x16x32_bf16 v[52:55], v[220:223], v[228:231], v[52:55]
	v_mfma_f32_16x16x32_bf16 v[56:59], v[220:223], v[232:235], v[56:59]
	v_mfma_f32_16x16x32_bf16 v[60:63], v[220:223], v[236:239], v[60:63]
	s_waitcnt vmcnt(1)
	s_barrier
	ds_read_b128 v[176:179], v244 offset:0
	ds_read_b128 v[80:83], v246 offset:0
	ds_read_b128 v[84:87], v246 offset:2048
	ds_read_b128 v[88:91], v246 offset:4096
	ds_read_b128 v[92:95], v246 offset:6144
	ds_read_b128 v[180:183], v244 offset:2048
	ds_read_b128 v[184:187], v244 offset:4096
	ds_read_b128 v[188:191], v244 offset:6144
	s_waitcnt lgkmcnt(6)
	v_mfma_f32_16x16x32_bf16 v[0:3], v[176:179], v[80:83], v[0:3]
	ds_read_b128 v[208:211], v245 offset:0
	s_add_i32 m0, s81, 32768
	s_waitcnt lgkmcnt(6)
	v_mfma_f32_16x16x32_bf16 v[4:7], v[176:179], v[84:87], v[4:7]
	ds_read_b128 v[224:227], v247 offset:0
	global_load_lds_dwordx4 v240, s[76:77]
	s_waitcnt lgkmcnt(6)
	v_mfma_f32_16x16x32_bf16 v[8:11], v[176:179], v[88:91], v[8:11]
	ds_read_b128 v[228:231], v247 offset:2048
	s_add_i32 m0, s81, 36864
	s_waitcnt lgkmcnt(6)
	v_mfma_f32_16x16x32_bf16 v[12:15], v[176:179], v[92:95], v[12:15]
	ds_read_b128 v[232:235], v247 offset:4096
	global_load_lds_dwordx4 v241, s[76:77]
	s_waitcnt lgkmcnt(6)
	v_mfma_f32_16x16x32_bf16 v[16:19], v[180:183], v[80:83], v[16:19]
	ds_read_b128 v[236:239], v247 offset:6144
	s_add_i32 m0, s81, 40960
	v_mfma_f32_16x16x32_bf16 v[20:23], v[180:183], v[84:87], v[20:23]
	ds_read_b128 v[212:215], v245 offset:2048
	global_load_lds_dwordx4 v242, s[76:77]
	v_mfma_f32_16x16x32_bf16 v[24:27], v[180:183], v[88:91], v[24:27]
	ds_read_b128 v[216:219], v245 offset:4096
	s_add_i32 m0, s81, 45056
	v_mfma_f32_16x16x32_bf16 v[28:31], v[180:183], v[92:95], v[28:31]
	ds_read_b128 v[220:223], v245 offset:6144
	global_load_lds_dwordx4 v243, s[76:77]
	s_waitcnt lgkmcnt(9)
	v_mfma_f32_16x16x32_bf16 v[32:35], v[184:187], v[80:83], v[32:35]
	s_add_i32 m0, s81, 49152
	v_mfma_f32_16x16x32_bf16 v[36:39], v[184:187], v[84:87], v[36:39]
	global_load_lds_dwordx4 v240, s[78:79]
	v_mfma_f32_16x16x32_bf16 v[40:43], v[184:187], v[88:91], v[40:43]
	s_add_i32 m0, s81, 53248
	v_mfma_f32_16x16x32_bf16 v[44:47], v[184:187], v[92:95], v[44:47]
	global_load_lds_dwordx4 v241, s[78:79]
	s_waitcnt lgkmcnt(8)
	v_mfma_f32_16x16x32_bf16 v[48:51], v[188:191], v[80:83], v[48:51]
	s_add_i32 m0, s81, 57344
	v_mfma_f32_16x16x32_bf16 v[52:55], v[188:191], v[84:87], v[52:55]
	global_load_lds_dwordx4 v242, s[78:79]
	v_mfma_f32_16x16x32_bf16 v[56:59], v[188:191], v[88:91], v[56:59]
	s_add_i32 m0, s81, 61440
	v_mfma_f32_16x16x32_bf16 v[60:63], v[188:191], v[92:95], v[60:63]
	global_load_lds_dwordx4 v243, s[78:79]
	s_waitcnt lgkmcnt(6)
	v_mfma_f32_16x16x32_bf16 v[0:3], v[208:211], v[224:227], v[0:3]
	s_add_u32 s76, s76, 0x80
	s_addc_u32 s77, s77, 0
	s_waitcnt lgkmcnt(5)
	v_mfma_f32_16x16x32_bf16 v[4:7], v[208:211], v[228:231], v[4:7]
	s_waitcnt lgkmcnt(4)
	v_mfma_f32_16x16x32_bf16 v[8:11], v[208:211], v[232:235], v[8:11]
	s_add_u32 s78, s78, 0x80
	s_addc_u32 s79, s79, 0
	s_waitcnt lgkmcnt(3)
	v_mfma_f32_16x16x32_bf16 v[12:15], v[208:211], v[236:239], v[12:15]
	s_waitcnt lgkmcnt(2)
	v_mfma_f32_16x16x32_bf16 v[16:19], v[212:215], v[224:227], v[16:19]
	v_mfma_f32_16x16x32_bf16 v[20:23], v[212:215], v[228:231], v[20:23]
	v_mfma_f32_16x16x32_bf16 v[24:27], v[212:215], v[232:235], v[24:27]
	v_mfma_f32_16x16x32_bf16 v[28:31], v[212:215], v[236:239], v[28:31]
	s_waitcnt lgkmcnt(1)
	v_mfma_f32_16x16x32_bf16 v[32:35], v[216:219], v[224:227], v[32:35]
	v_mfma_f32_16x16x32_bf16 v[36:39], v[216:219], v[228:231], v[36:39]
	v_mfma_f32_16x16x32_bf16 v[40:43], v[216:219], v[232:235], v[40:43]
	v_mfma_f32_16x16x32_bf16 v[44:47], v[216:219], v[236:239], v[44:47]
	s_waitcnt lgkmcnt(0)
	v_mfma_f32_16x16x32_bf16 v[48:51], v[220:223], v[224:227], v[48:51]
	v_mfma_f32_16x16x32_bf16 v[52:55], v[220:223], v[228:231], v[52:55]
	v_mfma_f32_16x16x32_bf16 v[56:59], v[220:223], v[232:235], v[56:59]
	v_mfma_f32_16x16x32_bf16 v[60:63], v[220:223], v[236:239], v[60:63]
	s_waitcnt vmcnt(0)
	s_barrier
	ds_read_b128 v[176:179], v244 offset:32768
	ds_read_b128 v[80:83], v246 offset:32768
	ds_read_b128 v[84:87], v246 offset:34816
	ds_read_b128 v[88:91], v246 offset:36864
	ds_read_b128 v[92:95], v246 offset:38912
	ds_read_b128 v[180:183], v244 offset:34816
	ds_read_b128 v[184:187], v244 offset:36864
	ds_read_b128 v[188:191], v244 offset:38912
	s_waitcnt lgkmcnt(6)
	v_mfma_f32_16x16x32_bf16 v[0:3], v[176:179], v[80:83], v[0:3]
	ds_read_b128 v[208:211], v245 offset:32768
	s_waitcnt lgkmcnt(6)
	v_mfma_f32_16x16x32_bf16 v[4:7], v[176:179], v[84:87], v[4:7]
	ds_read_b128 v[224:227], v247 offset:32768
	s_waitcnt lgkmcnt(6)
	v_mfma_f32_16x16x32_bf16 v[8:11], v[176:179], v[88:91], v[8:11]
	ds_read_b128 v[228:231], v247 offset:34816
	s_waitcnt lgkmcnt(6)
	v_mfma_f32_16x16x32_bf16 v[12:15], v[176:179], v[92:95], v[12:15]
	ds_read_b128 v[232:235], v247 offset:36864
	s_waitcnt lgkmcnt(6)
	v_mfma_f32_16x16x32_bf16 v[16:19], v[180:183], v[80:83], v[16:19]
	ds_read_b128 v[236:239], v247 offset:38912
	v_mfma_f32_16x16x32_bf16 v[20:23], v[180:183], v[84:87], v[20:23]
	ds_read_b128 v[212:215], v245 offset:34816
	v_mfma_f32_16x16x32_bf16 v[24:27], v[180:183], v[88:91], v[24:27]
	ds_read_b128 v[216:219], v245 offset:36864
	v_mfma_f32_16x16x32_bf16 v[28:31], v[180:183], v[92:95], v[28:31]
	ds_read_b128 v[220:223], v245 offset:38912
	s_waitcnt lgkmcnt(9)
	v_mfma_f32_16x16x32_bf16 v[32:35], v[184:187], v[80:83], v[32:35]
	v_mfma_f32_16x16x32_bf16 v[36:39], v[184:187], v[84:87], v[36:39]
	v_mfma_f32_16x16x32_bf16 v[40:43], v[184:187], v[88:91], v[40:43]
	v_mfma_f32_16x16x32_bf16 v[44:47], v[184:187], v[92:95], v[44:47]
	s_waitcnt lgkmcnt(8)
	v_mfma_f32_16x16x32_bf16 v[48:51], v[188:191], v[80:83], v[48:51]
	v_mfma_f32_16x16x32_bf16 v[52:55], v[188:191], v[84:87], v[52:55]
	v_mfma_f32_16x16x32_bf16 v[56:59], v[188:191], v[88:91], v[56:59]
	v_mfma_f32_16x16x32_bf16 v[60:63], v[188:191], v[92:95], v[60:63]
	s_waitcnt lgkmcnt(6)
	v_mfma_f32_16x16x32_bf16 v[0:3], v[208:211], v[224:227], v[0:3]
	s_waitcnt lgkmcnt(5)
	v_mfma_f32_16x16x32_bf16 v[4:7], v[208:211], v[228:231], v[4:7]
	s_waitcnt lgkmcnt(4)
	v_mfma_f32_16x16x32_bf16 v[8:11], v[208:211], v[232:235], v[8:11]
	s_waitcnt lgkmcnt(3)
	v_mfma_f32_16x16x32_bf16 v[12:15], v[208:211], v[236:239], v[12:15]
	s_waitcnt lgkmcnt(2)
	v_mfma_f32_16x16x32_bf16 v[16:19], v[212:215], v[224:227], v[16:19]
	v_mfma_f32_16x16x32_bf16 v[20:23], v[212:215], v[228:231], v[20:23]
	v_mfma_f32_16x16x32_bf16 v[24:27], v[212:215], v[232:235], v[24:27]
	v_mfma_f32_16x16x32_bf16 v[28:31], v[212:215], v[236:239], v[28:31]
	s_waitcnt lgkmcnt(1)
	v_mfma_f32_16x16x32_bf16 v[32:35], v[216:219], v[224:227], v[32:35]
	v_mfma_f32_16x16x32_bf16 v[36:39], v[216:219], v[228:231], v[36:39]
	v_mfma_f32_16x16x32_bf16 v[40:43], v[216:219], v[232:235], v[40:43]
	v_mfma_f32_16x16x32_bf16 v[44:47], v[216:219], v[236:239], v[44:47]
	s_waitcnt lgkmcnt(0)
	v_mfma_f32_16x16x32_bf16 v[48:51], v[220:223], v[224:227], v[48:51]
	v_mfma_f32_16x16x32_bf16 v[52:55], v[220:223], v[228:231], v[52:55]
	v_mfma_f32_16x16x32_bf16 v[56:59], v[220:223], v[232:235], v[56:59]
	v_mfma_f32_16x16x32_bf16 v[60:63], v[220:223], v[236:239], v[60:63]
